# GEMM K-loops: first iteration peeled with zero C operand on each accumulator's first MFMA; per-unit accumulator zeroing (128 v_mov) removed from the hot path
# speedup vs baseline: 1.0107x; 1.0033x over previous
; #define PG8_STAGE(bufoff, gbase, voff) do { _Pragma("unroll") for (int _i = 0; _i < 2; ++_i) \
;         __builtin_amdgcn_global_load_lds((const unsigned*)((const char*)(gbase) + (voff)[_i]), (PG8_LAS unsigned*)(lds + (bufoff) + ldsw + _i * 8192), 16, 0, 0); } while (0)
; #define PG8_LDA(dst, b, h) do { _Pragma("unroll") for (int m = 0; m < 4; ++m) _Pragma("unroll") for (int k = 0; k < 2; ++k) dst[m][k] = *(const PG8_LAS bf16x8*)(lds + PG8_SA(b, h) + aoff + m * 2048 + k * 1024); } while (0)
; #define PG8_LDB(dst, b, h) do { _Pragma("unroll") for (int n = 0; n < 2; ++n) _Pragma("unroll") for (int k = 0; k < 2; ++k) dst[n][k] = *(const PG8_LAS bf16x8*)(lds + PG8_SB(b, h) + boff + n * 2048 + k * 1024); } while (0)
; #define PG8_MMA(ai, bj, At, Bt) do { __builtin_amdgcn_s_setprio(1); _Pragma("unroll") for (int m = 0; m < 4; ++m) _Pragma("unroll") for (int n = 0; n < 2; ++n) _Pragma("unroll") for (int k = 0; k < 2; ++k) \
;         acc[ai][bj][m][n] = __builtin_amdgcn_mfma_f32_16x16x32_bf16(Bt[n][k], At[m][k], acc[ai][bj][m][n], 0, 0, 0); __builtin_amdgcn_s_setprio(0); } while (0)
; template <class Epi, class Sched, bool ALIGN_EPI = false, bool SP2 = false>
; __device__ __forceinline__ void gemm_phase(PG8_LAS unsigned char* lds, const Gemm g, const Sched& S, const Epi& E, const int wid) {
;     ...
;         const bool has_next = S.next(ui + 1, nxt);
;         const char* nA = has_next ? (const char*)g.A + (size_t)nxt.pm * tstep : cA; const char* nB = has_next ? (const char*)g.Bt + (size_t)nxt.pn * tstep : cB;
;         for (int t = 0; t < nt; t += 2) {
;             const bool last = (t == nt - 2);
;             const char* a1 = cA + (size_t)(t + 1) * kstep;
;             const char* a2 = last ? nA : cA + (size_t)(t + 2) * kstep; const char* b2 = last ? nB : cB + (size_t)(t + 2) * kstep;
;             const char* a3 = a2 + kstep; const char* b3 = b2 + kstep;
;             if (last && has_next) S.a_ready(nxt);
;             if constexpr (SP2) {
;             PG8_LDB(B0, 0, 0); PG8_LDB(B1, 0, 1); PG8_SCHED; PG8_LDA(At, 0, 0); PG8_STAGE(PG8_SA(1, 1), a1 + hstep, voffA);
;             PG8_WAIT_V(8); PG8_WAIT_L(0); PG8_BAR; PG8_MMA(0, 0, At, B0); PG8_MMA(0, 1, At, B1); PG8_BAR; PG8_SCHED;
;             PG8_LDA(At, 0, 1); PG8_STAGE(PG8_SB(0, 0), b2, voffB); PG8_STAGE(PG8_SB(0, 1), b2 + hstep, voffB); PG8_STAGE(PG8_SA(0, 0), a2, voffA);
.LBB0_18:
	s_andn2_b64 vcc, exec, s[24:25]
	s_cbranch_vccnz .Lz_G1A
	s_add_u32 s4, s38, 0x80
	s_addc_u32 s5, s39, 0
	s_add_u32 s0, s36, 0x100
	s_addc_u32 s1, s37, 0
	s_mov_b32 s36, 0
	ds_read_b128 v[128:131], v165
	ds_read_b128 v[146:149], v165 offset:1024
	ds_read_b128 v[150:153], v165 offset:2048
	ds_read_b128 v[154:157], v165 offset:3072
	ds_read_b128 v[158:161], v166
	ds_read_b128 v[172:175], v166 offset:1024
	ds_read_b128 v[176:179], v166 offset:2048
	ds_read_b128 v[180:183], v166 offset:3072
	s_add_i32 s38, s36, 2
	s_add_u32 s33, s4, 0x80
	s_addc_u32 s37, s5, 0
	s_cmp_eq_u32 s57, s36
	s_cselect_b32 s36, s30, s33
	s_cselect_b32 s37, s31, s37
	s_cselect_b32 s71, s35, s1
	s_cselect_b32 s70, s34, s0
	v_lshl_add_u64 v[216:217], s[4:5], 0, v[140:141]
	s_add_i32 m0, s47, 0xc000
	ds_read_b128 v[184:187], v167
	ds_read_b128 v[188:191], v167 offset:1024
	ds_read_b128 v[192:195], v167 offset:2048
	ds_read_b128 v[196:199], v167 offset:3072
	ds_read_b128 v[200:203], v167 offset:4096
	ds_read_b128 v[204:207], v167 offset:5120
	ds_read_b128 v[208:211], v167 offset:6144
	ds_read_b128 v[212:215], v167 offset:7168
	global_load_lds_dwordx4 v[216:217], off
	v_lshl_add_u64 v[216:217], s[4:5], 0, v[142:143]
	s_add_i32 m0, s47, 0xe000
	s_nop 0
	global_load_lds_dwordx4 v[216:217], off
	s_waitcnt vmcnt(8)
	s_waitcnt lgkmcnt(0)
	s_barrier
	s_setprio 1
	s_waitcnt lgkmcnt(0)
	v_mfma_f32_16x16x32_bf16 v[124:127], v[128:131], v[184:187], 0
	v_mfma_f32_16x16x32_bf16 v[120:123], v[150:153], v[184:187], 0
	v_mfma_f32_16x16x32_bf16 v[108:111], v[128:131], v[192:195], 0
	v_mfma_f32_16x16x32_bf16 v[104:107], v[150:153], v[192:195], 0
	v_mfma_f32_16x16x32_bf16 v[92:95], v[128:131], v[200:203], 0
	v_mfma_f32_16x16x32_bf16 v[88:91], v[150:153], v[200:203], 0
	v_mfma_f32_16x16x32_bf16 v[76:79], v[128:131], v[208:211], 0
	v_mfma_f32_16x16x32_bf16 v[72:75], v[150:153], v[208:211], 0
	v_mfma_f32_16x16x32_bf16 v[124:127], v[146:149], v[188:191], v[124:127]
	v_mfma_f32_16x16x32_bf16 v[120:123], v[154:157], v[188:191], v[120:123]
	v_mfma_f32_16x16x32_bf16 v[108:111], v[146:149], v[196:199], v[108:111]
	v_mfma_f32_16x16x32_bf16 v[104:107], v[154:157], v[196:199], v[104:107]
	v_mfma_f32_16x16x32_bf16 v[92:95], v[146:149], v[204:207], v[92:95]
	v_mfma_f32_16x16x32_bf16 v[88:91], v[154:157], v[204:207], v[88:91]
	v_mfma_f32_16x16x32_bf16 v[76:79], v[146:149], v[212:215], v[76:79]
	v_mfma_f32_16x16x32_bf16 v[72:75], v[154:157], v[212:215], v[72:75]
	s_setprio 0
	s_setprio 1
	v_mfma_f32_16x16x32_bf16 v[116:119], v[158:161], v[184:187], 0
	v_mfma_f32_16x16x32_bf16 v[112:115], v[176:179], v[184:187], 0
	v_mfma_f32_16x16x32_bf16 v[100:103], v[158:161], v[192:195], 0
	v_mfma_f32_16x16x32_bf16 v[96:99], v[176:179], v[192:195], 0
	v_mfma_f32_16x16x32_bf16 v[84:87], v[158:161], v[200:203], 0
	v_mfma_f32_16x16x32_bf16 v[80:83], v[176:179], v[200:203], 0
	v_mfma_f32_16x16x32_bf16 v[68:71], v[158:161], v[208:211], 0
	v_mfma_f32_16x16x32_bf16 v[64:67], v[176:179], v[208:211], 0
	v_mfma_f32_16x16x32_bf16 v[116:119], v[172:175], v[188:191], v[116:119]
	v_mfma_f32_16x16x32_bf16 v[112:115], v[180:183], v[188:191], v[112:115]
	v_mfma_f32_16x16x32_bf16 v[100:103], v[172:175], v[196:199], v[100:103]
	v_mfma_f32_16x16x32_bf16 v[96:99], v[180:183], v[196:199], v[96:99]
	v_mfma_f32_16x16x32_bf16 v[84:87], v[172:175], v[204:207], v[84:87]
	v_mfma_f32_16x16x32_bf16 v[80:83], v[180:183], v[204:207], v[80:83]
	v_mfma_f32_16x16x32_bf16 v[68:71], v[172:175], v[212:215], v[68:71]
	v_mfma_f32_16x16x32_bf16 v[64:67], v[180:183], v[212:215], v[64:67]
	s_setprio 0
	s_barrier
	s_add_i32 s33, s60, s40
	v_lshl_add_u64 v[216:217], s[70:71], 0, v[136:137]
	s_mov_b32 m0, s33
	ds_read_b128 v[184:187], v167 offset:16384
	ds_read_b128 v[188:191], v167 offset:17408
	ds_read_b128 v[192:195], v167 offset:18432
	ds_read_b128 v[196:199], v167 offset:19456
	ds_read_b128 v[200:203], v167 offset:20480
	ds_read_b128 v[204:207], v167 offset:21504
	ds_read_b128 v[208:211], v167 offset:22528
	ds_read_b128 v[212:215], v167 offset:23552
	global_load_lds_dwordx4 v[216:217], off
	s_add_i32 m0, s33, 0x2000
	v_lshl_add_u64 v[218:219], s[70:71], 0, v[132:133]
	s_add_u32 s70, s70, s6
	s_addc_u32 s71, s71, s7
	s_add_i32 s33, s61, s40
	global_load_lds_dwordx4 v[218:219], off
	v_lshl_add_u64 v[220:221], s[70:71], 0, v[136:137]
	s_mov_b32 m0, s33
	v_lshl_add_u64 v[222:223], s[70:71], 0, v[132:133]
	global_load_lds_dwordx4 v[220:221], off
	s_add_i32 m0, s33, 0x2000
	v_lshl_add_u64 v[224:225], s[36:37], 0, v[138:139]
	global_load_lds_dwordx4 v[222:223], off
	s_mov_b32 m0, s47
	v_lshl_add_u64 v[226:227], s[36:37], 0, v[134:135]
	global_load_lds_dwordx4 v[224:225], off
	s_mov_b32 m0, s49
	s_nop 0
	global_load_lds_dwordx4 v[226:227], off
	s_waitcnt vmcnt(8)
	s_waitcnt lgkmcnt(0)
	s_barrier
; #define PG8_STAGE(bufoff, gbase, voff) do { _Pragma("unroll") for (int _i = 0; _i < 2; ++_i) \
;         __builtin_amdgcn_global_load_lds((const unsigned*)((const char*)(gbase) + (voff)[_i]), (PG8_LAS unsigned*)(lds + (bufoff) + ldsw + _i * 8192), 16, 0, 0); } while (0)
; #define PG8_LDA(dst, b, h) do { _Pragma("unroll") for (int m = 0; m < 4; ++m) _Pragma("unroll") for (int k = 0; k < 2; ++k) dst[m][k] = *(const PG8_LAS bf16x8*)(lds + PG8_SA(b, h) + aoff + m * 2048 + k * 1024); } while (0)
; #define PG8_LDB(dst, b, h) do { _Pragma("unroll") for (int n = 0; n < 2; ++n) _Pragma("unroll") for (int k = 0; k < 2; ++k) dst[n][k] = *(const PG8_LAS bf16x8*)(lds + PG8_SB(b, h) + boff + n * 2048 + k * 1024); } while (0)
; #define PG8_MMA(ai, bj, At, Bt) do { __builtin_amdgcn_s_setprio(1); _Pragma("unroll") for (int m = 0; m < 4; ++m) _Pragma("unroll") for (int n = 0; n < 2; ++n) _Pragma("unroll") for (int k = 0; k < 2; ++k) \
;         acc[ai][bj][m][n] = __builtin_amdgcn_mfma_f32_16x16x32_bf16(Bt[n][k], At[m][k], acc[ai][bj][m][n], 0, 0, 0); __builtin_amdgcn_s_setprio(0); } while (0)
; #define PG8_WAIT_V(n) asm volatile("s_waitcnt vmcnt(" #n ")" ::: "memory")
; #define PG8_WAIT_L(n) asm volatile("s_waitcnt lgkmcnt(" #n ")" ::: "memory")
; #define PG8_BAR __builtin_amdgcn_s_barrier()
; #define PG8_SCHED __builtin_amdgcn_sched_barrier(0)
; template <class Epi, class Sched, bool ALIGN_EPI = false, bool SP2 = false>
; __device__ __forceinline__ void gemm_phase(PG8_LAS unsigned char* lds, const Gemm g, const Sched& S, const Epi& E, const int wid) {
;     ...
;             PG8_WAIT_V(8); PG8_WAIT_L(0); PG8_BAR; PG8_MMA(1, 0, At, B0); PG8_MMA(1, 1, At, B1); PG8_BAR; PG8_SCHED;
;             PG8_LDB(B0, 1, 0); PG8_LDB(B1, 1, 1); PG8_SCHED; PG8_LDA(At, 1, 0); PG8_STAGE(PG8_SA(0, 1), a2 + hstep, voffA);
;             PG8_WAIT_V(8); PG8_WAIT_L(0); PG8_BAR; PG8_MMA(0, 0, At, B0); PG8_MMA(0, 1, At, B1); PG8_BAR; PG8_SCHED;
	s_setprio 1
	s_waitcnt lgkmcnt(0)
	v_mfma_f32_16x16x32_bf16 v[60:63], v[128:131], v[184:187], 0
	v_mfma_f32_16x16x32_bf16 v[56:59], v[150:153], v[184:187], 0
	v_mfma_f32_16x16x32_bf16 v[44:47], v[128:131], v[192:195], 0
	v_mfma_f32_16x16x32_bf16 v[40:43], v[150:153], v[192:195], 0
	v_mfma_f32_16x16x32_bf16 v[28:31], v[128:131], v[200:203], 0
	v_mfma_f32_16x16x32_bf16 v[24:27], v[150:153], v[200:203], 0
	v_mfma_f32_16x16x32_bf16 v[12:15], v[128:131], v[208:211], 0
	v_mfma_f32_16x16x32_bf16 v[8:11], v[150:153], v[208:211], 0
	v_mfma_f32_16x16x32_bf16 v[60:63], v[146:149], v[188:191], v[60:63]
	v_mfma_f32_16x16x32_bf16 v[56:59], v[154:157], v[188:191], v[56:59]
	v_mfma_f32_16x16x32_bf16 v[44:47], v[146:149], v[196:199], v[44:47]
	v_mfma_f32_16x16x32_bf16 v[40:43], v[154:157], v[196:199], v[40:43]
	v_mfma_f32_16x16x32_bf16 v[28:31], v[146:149], v[204:207], v[28:31]
	v_mfma_f32_16x16x32_bf16 v[24:27], v[154:157], v[204:207], v[24:27]
	v_mfma_f32_16x16x32_bf16 v[12:15], v[146:149], v[212:215], v[12:15]
	v_mfma_f32_16x16x32_bf16 v[8:11], v[154:157], v[212:215], v[8:11]
	s_setprio 0
	s_setprio 1
	v_mfma_f32_16x16x32_bf16 v[52:55], v[158:161], v[184:187], 0
	v_mfma_f32_16x16x32_bf16 v[48:51], v[176:179], v[184:187], 0
	v_mfma_f32_16x16x32_bf16 v[36:39], v[158:161], v[192:195], 0
	v_mfma_f32_16x16x32_bf16 v[32:35], v[176:179], v[192:195], 0
	v_mfma_f32_16x16x32_bf16 v[20:23], v[158:161], v[200:203], 0
	v_mfma_f32_16x16x32_bf16 v[16:19], v[176:179], v[200:203], 0
	v_mfma_f32_16x16x32_bf16 v[4:7], v[158:161], v[208:211], 0
	v_mfma_f32_16x16x32_bf16 v[0:3], v[176:179], v[208:211], 0
	v_mfma_f32_16x16x32_bf16 v[52:55], v[172:175], v[188:191], v[52:55]
	v_mfma_f32_16x16x32_bf16 v[48:51], v[180:183], v[188:191], v[48:51]
	v_mfma_f32_16x16x32_bf16 v[36:39], v[172:175], v[196:199], v[36:39]
	v_mfma_f32_16x16x32_bf16 v[32:35], v[180:183], v[196:199], v[32:35]
	v_mfma_f32_16x16x32_bf16 v[20:23], v[172:175], v[204:207], v[20:23]
	v_mfma_f32_16x16x32_bf16 v[16:19], v[180:183], v[204:207], v[16:19]
	v_mfma_f32_16x16x32_bf16 v[4:7], v[172:175], v[212:215], v[4:7]
	v_mfma_f32_16x16x32_bf16 v[0:3], v[180:183], v[212:215], v[0:3]
	s_setprio 0
	s_barrier
	s_add_i32 s33, 0, 0x18000
	s_add_i32 s39, 0, 0x1c000
	v_add_u32_e32 v154, s33, v164
	v_add_u32_e32 v180, s39, v164
	ds_read_b128 v[128:131], v154
	ds_read_b128 v[146:149], v154 offset:1024
	ds_read_b128 v[150:153], v154 offset:2048
	ds_read_b128 v[154:157], v154 offset:3072
	ds_read_b128 v[158:161], v180
	ds_read_b128 v[172:175], v180 offset:1024
	ds_read_b128 v[176:179], v180 offset:2048
	ds_read_b128 v[180:183], v180 offset:3072
	s_add_u32 s36, s36, s6
	s_addc_u32 s37, s37, s7
	s_mov_b32 m0, s50
	v_lshl_add_u64 v[228:229], s[36:37], 0, v[138:139]
	ds_read_b128 v[184:187], v167 offset:32768
	ds_read_b128 v[188:191], v167 offset:33792
	ds_read_b128 v[192:195], v167 offset:34816
	ds_read_b128 v[196:199], v167 offset:35840
	ds_read_b128 v[200:203], v167 offset:36864
	ds_read_b128 v[204:207], v167 offset:37888
	ds_read_b128 v[208:211], v167 offset:38912
	ds_read_b128 v[212:215], v167 offset:39936
	global_load_lds_dwordx4 v[228:229], off
	v_lshl_add_u64 v[228:229], s[36:37], 0, v[134:135]
	s_mov_b32 m0, s51
	s_nop 0
	global_load_lds_dwordx4 v[228:229], off
	s_waitcnt vmcnt(8)
	s_waitcnt lgkmcnt(0)
	s_barrier
	s_setprio 1
	s_waitcnt lgkmcnt(0)
	v_mfma_f32_16x16x32_bf16 v[124:127], v[128:131], v[184:187], v[124:127]
	v_mfma_f32_16x16x32_bf16 v[120:123], v[150:153], v[184:187], v[120:123]
	v_mfma_f32_16x16x32_bf16 v[108:111], v[128:131], v[192:195], v[108:111]
	v_mfma_f32_16x16x32_bf16 v[104:107], v[150:153], v[192:195], v[104:107]
	v_mfma_f32_16x16x32_bf16 v[92:95], v[128:131], v[200:203], v[92:95]
	v_mfma_f32_16x16x32_bf16 v[88:91], v[150:153], v[200:203], v[88:91]
	v_mfma_f32_16x16x32_bf16 v[76:79], v[128:131], v[208:211], v[76:79]
	v_mfma_f32_16x16x32_bf16 v[72:75], v[150:153], v[208:211], v[72:75]
	v_mfma_f32_16x16x32_bf16 v[124:127], v[146:149], v[188:191], v[124:127]
	v_mfma_f32_16x16x32_bf16 v[120:123], v[154:157], v[188:191], v[120:123]
	v_mfma_f32_16x16x32_bf16 v[108:111], v[146:149], v[196:199], v[108:111]
	v_mfma_f32_16x16x32_bf16 v[104:107], v[154:157], v[196:199], v[104:107]
	v_mfma_f32_16x16x32_bf16 v[92:95], v[146:149], v[204:207], v[92:95]
	v_mfma_f32_16x16x32_bf16 v[88:91], v[154:157], v[204:207], v[88:91]
	v_mfma_f32_16x16x32_bf16 v[76:79], v[146:149], v[212:215], v[76:79]
	v_mfma_f32_16x16x32_bf16 v[72:75], v[154:157], v[212:215], v[72:75]
	s_setprio 0
	s_setprio 1
	v_mfma_f32_16x16x32_bf16 v[116:119], v[158:161], v[184:187], v[116:119]
	v_mfma_f32_16x16x32_bf16 v[112:115], v[176:179], v[184:187], v[112:115]
	v_mfma_f32_16x16x32_bf16 v[100:103], v[158:161], v[192:195], v[100:103]
	v_mfma_f32_16x16x32_bf16 v[96:99], v[176:179], v[192:195], v[96:99]
	v_mfma_f32_16x16x32_bf16 v[84:87], v[158:161], v[200:203], v[84:87]
	v_mfma_f32_16x16x32_bf16 v[80:83], v[176:179], v[200:203], v[80:83]
	v_mfma_f32_16x16x32_bf16 v[68:71], v[158:161], v[208:211], v[68:71]
	v_mfma_f32_16x16x32_bf16 v[64:67], v[176:179], v[208:211], v[64:67]
	v_mfma_f32_16x16x32_bf16 v[116:119], v[172:175], v[188:191], v[116:119]
	v_mfma_f32_16x16x32_bf16 v[112:115], v[180:183], v[188:191], v[112:115]
	v_mfma_f32_16x16x32_bf16 v[100:103], v[172:175], v[196:199], v[100:103]
	v_mfma_f32_16x16x32_bf16 v[96:99], v[180:183], v[196:199], v[96:99]
	v_mfma_f32_16x16x32_bf16 v[84:87], v[172:175], v[204:207], v[84:87]
	v_mfma_f32_16x16x32_bf16 v[80:83], v[180:183], v[204:207], v[80:83]
	v_mfma_f32_16x16x32_bf16 v[68:71], v[172:175], v[212:215], v[68:71]
	v_mfma_f32_16x16x32_bf16 v[64:67], v[180:183], v[212:215], v[64:67]
	s_setprio 0
	s_barrier
; #define PG8_STAGE(bufoff, gbase, voff) do { _Pragma("unroll") for (int _i = 0; _i < 2; ++_i) \
;         __builtin_amdgcn_global_load_lds((const unsigned*)((const char*)(gbase) + (voff)[_i]), (PG8_LAS unsigned*)(lds + (bufoff) + ldsw + _i * 8192), 16, 0, 0); } while (0)
; #define PG8_LDA(dst, b, h) do { _Pragma("unroll") for (int m = 0; m < 4; ++m) _Pragma("unroll") for (int k = 0; k < 2; ++k) dst[m][k] = *(const PG8_LAS bf16x8*)(lds + PG8_SA(b, h) + aoff + m * 2048 + k * 1024); } while (0)
; #define PG8_MMA(ai, bj, At, Bt) do { __builtin_amdgcn_s_setprio(1); _Pragma("unroll") for (int m = 0; m < 4; ++m) _Pragma("unroll") for (int n = 0; n < 2; ++n) _Pragma("unroll") for (int k = 0; k < 2; ++k) \
;         acc[ai][bj][m][n] = __builtin_amdgcn_mfma_f32_16x16x32_bf16(Bt[n][k], At[m][k], acc[ai][bj][m][n], 0, 0, 0); __builtin_amdgcn_s_setprio(0); } while (0)
; #define PG8_WAIT_V(n) asm volatile("s_waitcnt vmcnt(" #n ")" ::: "memory")
; #define PG8_WAIT_L(n) asm volatile("s_waitcnt lgkmcnt(" #n ")" ::: "memory")
; #define PG8_BAR __builtin_amdgcn_s_barrier()
; #define PG8_SCHED __builtin_amdgcn_sched_barrier(0)
; template <class Epi, class Sched, bool ALIGN_EPI = false, bool SP2 = false>
; __device__ __forceinline__ void gemm_phase(PG8_LAS unsigned char* lds, const Gemm g, const Sched& S, const Epi& E, const int wid) {
;     ...
;         for (int t = 0; t < nt; t += 2) {
;             const bool last = (t == nt - 2);
;             const char* a1 = cA + (size_t)(t + 1) * kstep;
;             const char* a2 = last ? nA : cA + (size_t)(t + 2) * kstep; const char* b2 = last ? nB : cB + (size_t)(t + 2) * kstep;
;             const char* a3 = a2 + kstep; const char* b3 = b2 + kstep;
;     ...
;             PG8_LDA(At, 1, 1); PG8_STAGE(PG8_SB(1, 0), b3, voffB); PG8_STAGE(PG8_SB(1, 1), b3 + hstep, voffB); PG8_STAGE(PG8_SA(1, 0), a3, voffA);
;             PG8_WAIT_V(8); PG8_WAIT_L(0); PG8_BAR; PG8_MMA(1, 0, At, B0); PG8_MMA(1, 1, At, B1); PG8_BAR; PG8_SCHED;
	s_add_i32 s33, s33, s40
	v_lshl_add_u64 v[216:217], v[216:217], 0, s[22:23]
	s_mov_b32 m0, s33
	ds_read_b128 v[184:187], v167 offset:49152
	ds_read_b128 v[188:191], v167 offset:50176
	ds_read_b128 v[192:195], v167 offset:51200
	ds_read_b128 v[196:199], v167 offset:52224
	ds_read_b128 v[200:203], v167 offset:53248
	ds_read_b128 v[204:207], v167 offset:54272
	ds_read_b128 v[208:211], v167 offset:55296
	ds_read_b128 v[212:215], v167 offset:56320
	global_load_lds_dwordx4 v[216:217], off
	v_lshl_add_u64 v[216:217], v[218:219], 0, s[22:23]
	s_add_i32 m0, s33, 0x2000
	s_add_i32 s33, s39, s40
	global_load_lds_dwordx4 v[216:217], off
	v_lshl_add_u64 v[216:217], v[220:221], 0, s[22:23]
	s_mov_b32 m0, s33
	s_nop 0
	global_load_lds_dwordx4 v[216:217], off
	v_lshl_add_u64 v[216:217], v[222:223], 0, s[22:23]
	s_add_i32 m0, s33, 0x2000
	s_nop 0
	global_load_lds_dwordx4 v[216:217], off
	v_lshl_add_u64 v[216:217], v[224:225], 0, s[22:23]
	s_mov_b32 m0, s53
	s_nop 0
	global_load_lds_dwordx4 v[216:217], off
	v_lshl_add_u64 v[216:217], v[226:227], 0, s[22:23]
	s_mov_b32 m0, s54
	s_nop 0
	global_load_lds_dwordx4 v[216:217], off
	s_waitcnt vmcnt(8)
	s_waitcnt lgkmcnt(0)
	s_barrier
	s_setprio 1
	s_waitcnt lgkmcnt(0)
	v_mfma_f32_16x16x32_bf16 v[60:63], v[128:131], v[184:187], v[60:63]
	v_mfma_f32_16x16x32_bf16 v[56:59], v[150:153], v[184:187], v[56:59]
	v_mfma_f32_16x16x32_bf16 v[44:47], v[128:131], v[192:195], v[44:47]
	v_mfma_f32_16x16x32_bf16 v[40:43], v[150:153], v[192:195], v[40:43]
	v_mfma_f32_16x16x32_bf16 v[28:31], v[128:131], v[200:203], v[28:31]
	v_mfma_f32_16x16x32_bf16 v[24:27], v[150:153], v[200:203], v[24:27]
	v_mfma_f32_16x16x32_bf16 v[12:15], v[128:131], v[208:211], v[12:15]
	v_mfma_f32_16x16x32_bf16 v[8:11], v[150:153], v[208:211], v[8:11]
	v_mfma_f32_16x16x32_bf16 v[60:63], v[146:149], v[188:191], v[60:63]
	v_mfma_f32_16x16x32_bf16 v[56:59], v[154:157], v[188:191], v[56:59]
	v_mfma_f32_16x16x32_bf16 v[44:47], v[146:149], v[196:199], v[44:47]
	v_mfma_f32_16x16x32_bf16 v[40:43], v[154:157], v[196:199], v[40:43]
	v_mfma_f32_16x16x32_bf16 v[28:31], v[146:149], v[204:207], v[28:31]
	v_mfma_f32_16x16x32_bf16 v[24:27], v[154:157], v[204:207], v[24:27]
	v_mfma_f32_16x16x32_bf16 v[12:15], v[146:149], v[212:215], v[12:15]
	v_mfma_f32_16x16x32_bf16 v[8:11], v[154:157], v[212:215], v[8:11]
	s_setprio 0
	s_setprio 1
	v_mfma_f32_16x16x32_bf16 v[52:55], v[158:161], v[184:187], v[52:55]
	v_mfma_f32_16x16x32_bf16 v[48:51], v[176:179], v[184:187], v[48:51]
	v_mfma_f32_16x16x32_bf16 v[36:39], v[158:161], v[192:195], v[36:39]
	v_mfma_f32_16x16x32_bf16 v[32:35], v[176:179], v[192:195], v[32:35]
	v_mfma_f32_16x16x32_bf16 v[20:23], v[158:161], v[200:203], v[20:23]
	v_mfma_f32_16x16x32_bf16 v[16:19], v[176:179], v[200:203], v[16:19]
	v_mfma_f32_16x16x32_bf16 v[4:7], v[158:161], v[208:211], v[4:7]
	v_mfma_f32_16x16x32_bf16 v[0:3], v[176:179], v[208:211], v[0:3]
	v_mfma_f32_16x16x32_bf16 v[52:55], v[172:175], v[188:191], v[52:55]
	v_mfma_f32_16x16x32_bf16 v[48:51], v[180:183], v[188:191], v[48:51]
	v_mfma_f32_16x16x32_bf16 v[36:39], v[172:175], v[196:199], v[36:39]
	v_mfma_f32_16x16x32_bf16 v[32:35], v[180:183], v[196:199], v[32:35]
	v_mfma_f32_16x16x32_bf16 v[20:23], v[172:175], v[204:207], v[20:23]
	v_mfma_f32_16x16x32_bf16 v[16:19], v[180:183], v[204:207], v[16:19]
	v_mfma_f32_16x16x32_bf16 v[4:7], v[172:175], v[212:215], v[4:7]
	v_mfma_f32_16x16x32_bf16 v[0:3], v[180:183], v[212:215], v[0:3]
	s_setprio 0
	s_barrier
	s_add_u32 s4, s4, 0x100
	s_addc_u32 s5, s5, 0
	s_add_u32 s0, s0, 0x100
	s_addc_u32 s1, s1, 0
	s_cmp_ge_i32 s38, s55
	s_mov_b32 s36, s38
	s_cbranch_scc1 .LBB0_21

; template <class Epi, class Sched, bool ALIGN_EPI = false, bool SP2 = false>
; __device__ __forceinline__ void gemm_phase(PG8_LAS unsigned char* lds, const Gemm g, const Sched& S, const Epi& E, const int wid) {
;     ...
;     f32x4 acc[2][2][4][2];
; #pragma unroll
;     for (int a = 0; a < 2; ++a)
; #pragma unroll
;         for (int b = 0; b < 2; ++b)
; #pragma unroll
;             for (int m = 0; m < 4; ++m)
; #pragma unroll
;                 for (int n = 0; n < 2; ++n) acc[a][b][m][n] = (f32x4){0.f, 0.f, 0.f, 0.f};
.Lz_G1A:
	v_mov_b32_e32 v127, 0
	v_mov_b32_e32 v126, v127
	v_mov_b32_e32 v125, v127
	v_mov_b32_e32 v124, v127
	v_mov_b32_e32 v123, v127
	v_mov_b32_e32 v122, v127
	v_mov_b32_e32 v121, v127
	v_mov_b32_e32 v120, v127
	v_mov_b32_e32 v111, v127
	v_mov_b32_e32 v110, v127
	v_mov_b32_e32 v109, v127
	v_mov_b32_e32 v108, v127
	v_mov_b32_e32 v107, v127
	v_mov_b32_e32 v106, v127
	v_mov_b32_e32 v105, v127
	v_mov_b32_e32 v104, v127
	v_mov_b32_e32 v95, v127
	v_mov_b32_e32 v94, v127
	v_mov_b32_e32 v93, v127
	v_mov_b32_e32 v92, v127
	v_mov_b32_e32 v91, v127
	v_mov_b32_e32 v90, v127
	v_mov_b32_e32 v89, v127
	v_mov_b32_e32 v88, v127
	v_mov_b32_e32 v79, v127
	v_mov_b32_e32 v78, v127
	v_mov_b32_e32 v77, v127
	v_mov_b32_e32 v76, v127
	v_mov_b32_e32 v75, v127
	v_mov_b32_e32 v74, v127
	v_mov_b32_e32 v73, v127
	v_mov_b32_e32 v72, v127
	v_mov_b32_e32 v119, v127
	v_mov_b32_e32 v118, v127
	v_mov_b32_e32 v117, v127
	v_mov_b32_e32 v116, v127
	v_mov_b32_e32 v115, v127
	v_mov_b32_e32 v114, v127
	v_mov_b32_e32 v113, v127
	v_mov_b32_e32 v112, v127
	v_mov_b32_e32 v103, v127
	v_mov_b32_e32 v102, v127
	v_mov_b32_e32 v101, v127
	v_mov_b32_e32 v100, v127
	v_mov_b32_e32 v99, v127
	v_mov_b32_e32 v98, v127
	v_mov_b32_e32 v97, v127
	v_mov_b32_e32 v96, v127
	v_mov_b32_e32 v87, v127
	v_mov_b32_e32 v86, v127
	v_mov_b32_e32 v85, v127
	v_mov_b32_e32 v84, v127
	v_mov_b32_e32 v83, v127
	v_mov_b32_e32 v82, v127
	v_mov_b32_e32 v81, v127
	v_mov_b32_e32 v80, v127
	v_mov_b32_e32 v71, v127
	v_mov_b32_e32 v70, v127
	v_mov_b32_e32 v69, v127
	v_mov_b32_e32 v68, v127
	v_mov_b32_e32 v67, v127
	v_mov_b32_e32 v66, v127
	v_mov_b32_e32 v65, v127
	v_mov_b32_e32 v64, v127
	v_mov_b32_e32 v63, v127
	v_mov_b32_e32 v62, v127
	v_mov_b32_e32 v61, v127
	v_mov_b32_e32 v60, v127
	v_mov_b32_e32 v59, v127
	v_mov_b32_e32 v58, v127
	v_mov_b32_e32 v57, v127
	v_mov_b32_e32 v56, v127
	v_mov_b32_e32 v47, v127
	v_mov_b32_e32 v46, v127
	v_mov_b32_e32 v45, v127
	v_mov_b32_e32 v44, v127
	v_mov_b32_e32 v43, v127
	v_mov_b32_e32 v42, v127
	v_mov_b32_e32 v41, v127
	v_mov_b32_e32 v40, v127
	v_mov_b32_e32 v31, v127
	v_mov_b32_e32 v30, v127
	v_mov_b32_e32 v29, v127
	v_mov_b32_e32 v28, v127
	v_mov_b32_e32 v27, v127
	v_mov_b32_e32 v26, v127
	v_mov_b32_e32 v25, v127
	v_mov_b32_e32 v24, v127
	v_mov_b32_e32 v15, v127
	v_mov_b32_e32 v14, v127
	v_mov_b32_e32 v13, v127
	v_mov_b32_e32 v12, v127
	v_mov_b32_e32 v11, v127
	v_mov_b32_e32 v10, v127
	v_mov_b32_e32 v9, v127
	v_mov_b32_e32 v8, v127
	v_mov_b32_e32 v55, v127
	v_mov_b32_e32 v54, v127
	v_mov_b32_e32 v53, v127
	v_mov_b32_e32 v52, v127
	v_mov_b32_e32 v51, v127
	v_mov_b32_e32 v50, v127
	v_mov_b32_e32 v49, v127
	v_mov_b32_e32 v48, v127
	v_mov_b32_e32 v39, v127
	v_mov_b32_e32 v38, v127
	v_mov_b32_e32 v37, v127
	v_mov_b32_e32 v36, v127
	v_mov_b32_e32 v35, v127
	v_mov_b32_e32 v34, v127
	v_mov_b32_e32 v33, v127
	v_mov_b32_e32 v32, v127
	v_mov_b32_e32 v23, v127
	v_mov_b32_e32 v22, v127
	v_mov_b32_e32 v21, v127
	v_mov_b32_e32 v20, v127
	v_mov_b32_e32 v19, v127
	v_mov_b32_e32 v18, v127
	v_mov_b32_e32 v17, v127
	v_mov_b32_e32 v16, v127
	v_mov_b32_e32 v7, v127
	v_mov_b32_e32 v6, v127
	v_mov_b32_e32 v5, v127
	v_mov_b32_e32 v4, v127
	v_mov_b32_e32 v3, v127
	v_mov_b32_e32 v2, v127
	v_mov_b32_e32 v1, v127
	v_mov_b32_e32 v0, v127
	s_branch .LBB0_21

; #define PG8_STAGE(bufoff, gbase, voff) do { _Pragma("unroll") for (int _i = 0; _i < 2; ++_i) \
;         __builtin_amdgcn_global_load_lds((const unsigned*)((const char*)(gbase) + (voff)[_i]), (PG8_LAS unsigned*)(lds + (bufoff) + ldsw + _i * 8192), 16, 0, 0); } while (0)
; #define PG8_LDA(dst, b, h) do { _Pragma("unroll") for (int m = 0; m < 4; ++m) _Pragma("unroll") for (int k = 0; k < 2; ++k) dst[m][k] = *(const PG8_LAS bf16x8*)(lds + PG8_SA(b, h) + aoff + m * 2048 + k * 1024); } while (0)
; #define PG8_LDB(dst, b, h) do { _Pragma("unroll") for (int n = 0; n < 2; ++n) _Pragma("unroll") for (int k = 0; k < 2; ++k) dst[n][k] = *(const PG8_LAS bf16x8*)(lds + PG8_SB(b, h) + boff + n * 2048 + k * 1024); } while (0)
; #define PG8_MMA(ai, bj, At, Bt) do { __builtin_amdgcn_s_setprio(1); _Pragma("unroll") for (int m = 0; m < 4; ++m) _Pragma("unroll") for (int n = 0; n < 2; ++n) _Pragma("unroll") for (int k = 0; k < 2; ++k) \
;         acc[ai][bj][m][n] = __builtin_amdgcn_mfma_f32_16x16x32_bf16(Bt[n][k], At[m][k], acc[ai][bj][m][n], 0, 0, 0); __builtin_amdgcn_s_setprio(0); } while (0)
; template <class Epi, class Sched, bool ALIGN_EPI = false, bool SP2 = false>
; __device__ __forceinline__ void gemm_phase(PG8_LAS unsigned char* lds, const Gemm g, const Sched& S, const Epi& E, const int wid) {
;     ...
;         const bool has_next = S.next(ui + 1, nxt);
;         const char* nA = has_next ? (const char*)g.A + (size_t)nxt.pm * tstep : cA; const char* nB = has_next ? (const char*)g.Bt + (size_t)nxt.pn * tstep : cB;
;         for (int t = 0; t < nt; t += 2) {
;             const bool last = (t == nt - 2);
;             const char* a1 = cA + (size_t)(t + 1) * kstep;
;             const char* a2 = last ? nA : cA + (size_t)(t + 2) * kstep; const char* b2 = last ? nB : cB + (size_t)(t + 2) * kstep;
;             const char* a3 = a2 + kstep; const char* b3 = b2 + kstep;
;             if (last && has_next) S.a_ready(nxt);
;             if constexpr (SP2) {
;             PG8_LDB(B0, 0, 0); PG8_LDB(B1, 0, 1); PG8_SCHED; PG8_LDA(At, 0, 0); PG8_STAGE(PG8_SA(1, 1), a1 + hstep, voffA);
;             PG8_WAIT_V(8); PG8_WAIT_L(0); PG8_BAR; PG8_MMA(0, 0, At, B0); PG8_MMA(0, 1, At, B1); PG8_BAR; PG8_SCHED;
;             PG8_LDA(At, 0, 1); PG8_STAGE(PG8_SB(0, 0), b2, voffB); PG8_STAGE(PG8_SB(0, 1), b2 + hstep, voffB); PG8_STAGE(PG8_SA(0, 0), a2, voffA);
.LBB0_1177:
	s_andn2_b64 vcc, exec, s[20:21]
	s_cbranch_vccnz .Lz_GMA
	s_add_u32 s26, s26, 0x80
	s_addc_u32 s27, s27, 0
	s_add_u32 s0, s28, 0x100
	s_addc_u32 s1, s29, 0
	s_mov_b32 s28, 0
	ds_read_b128 v[142:145], v149
	ds_read_b128 v[152:155], v149 offset:1024
	ds_read_b128 v[156:159], v149 offset:2048
	ds_read_b128 v[160:163], v149 offset:3072
	ds_read_b128 v[164:167], v150
	ds_read_b128 v[168:171], v150 offset:1024
	ds_read_b128 v[172:175], v150 offset:2048
	ds_read_b128 v[176:179], v150 offset:3072
	s_add_i32 s61, s28, 2
	s_add_u32 s33, s26, 0x80
	s_addc_u32 s29, s27, 0
	s_cmp_eq_u32 s53, s28
	s_cselect_b32 s28, s4, s33
	s_cselect_b32 s29, s5, s29
	s_cselect_b32 s63, s25, s1
	s_cselect_b32 s62, s24, s0
	v_lshl_add_u64 v[212:213], s[26:27], 0, v[136:137]
	s_add_i32 m0, s42, 0xc000
	ds_read_b128 v[180:183], v151
	ds_read_b128 v[184:187], v151 offset:1024
	ds_read_b128 v[188:191], v151 offset:2048
	ds_read_b128 v[192:195], v151 offset:3072
	ds_read_b128 v[196:199], v151 offset:4096
	ds_read_b128 v[200:203], v151 offset:5120
	ds_read_b128 v[204:207], v151 offset:6144
	ds_read_b128 v[208:211], v151 offset:7168
	global_load_lds_dwordx4 v[212:213], off
	v_lshl_add_u64 v[212:213], s[26:27], 0, v[138:139]
	s_add_i32 m0, s42, 0xe000
	s_nop 0
	global_load_lds_dwordx4 v[212:213], off
	s_waitcnt vmcnt(8)
	s_waitcnt lgkmcnt(0)
	s_barrier
	s_setprio 1
	s_waitcnt lgkmcnt(0)
	v_mfma_f32_16x16x32_bf16 v[124:127], v[142:145], v[180:183], 0
	v_mfma_f32_16x16x32_bf16 v[120:123], v[156:159], v[180:183], 0
	v_mfma_f32_16x16x32_bf16 v[108:111], v[142:145], v[188:191], 0
	v_mfma_f32_16x16x32_bf16 v[104:107], v[156:159], v[188:191], 0
	v_mfma_f32_16x16x32_bf16 v[92:95], v[142:145], v[196:199], 0
	v_mfma_f32_16x16x32_bf16 v[88:91], v[156:159], v[196:199], 0
	v_mfma_f32_16x16x32_bf16 v[76:79], v[142:145], v[204:207], 0
	v_mfma_f32_16x16x32_bf16 v[72:75], v[156:159], v[204:207], 0
	v_mfma_f32_16x16x32_bf16 v[124:127], v[152:155], v[184:187], v[124:127]
	v_mfma_f32_16x16x32_bf16 v[120:123], v[160:163], v[184:187], v[120:123]
	v_mfma_f32_16x16x32_bf16 v[108:111], v[152:155], v[192:195], v[108:111]
	v_mfma_f32_16x16x32_bf16 v[104:107], v[160:163], v[192:195], v[104:107]
	v_mfma_f32_16x16x32_bf16 v[92:95], v[152:155], v[200:203], v[92:95]
	v_mfma_f32_16x16x32_bf16 v[88:91], v[160:163], v[200:203], v[88:91]
	v_mfma_f32_16x16x32_bf16 v[76:79], v[152:155], v[208:211], v[76:79]
	v_mfma_f32_16x16x32_bf16 v[72:75], v[160:163], v[208:211], v[72:75]
	s_setprio 0
	s_setprio 1
	v_mfma_f32_16x16x32_bf16 v[116:119], v[164:167], v[180:183], 0
	v_mfma_f32_16x16x32_bf16 v[112:115], v[172:175], v[180:183], 0
	v_mfma_f32_16x16x32_bf16 v[100:103], v[164:167], v[188:191], 0
	v_mfma_f32_16x16x32_bf16 v[96:99], v[172:175], v[188:191], 0
	v_mfma_f32_16x16x32_bf16 v[84:87], v[164:167], v[196:199], 0
	v_mfma_f32_16x16x32_bf16 v[80:83], v[172:175], v[196:199], 0
	v_mfma_f32_16x16x32_bf16 v[68:71], v[164:167], v[204:207], 0
	v_mfma_f32_16x16x32_bf16 v[64:67], v[172:175], v[204:207], 0
	v_mfma_f32_16x16x32_bf16 v[116:119], v[168:171], v[184:187], v[116:119]
	v_mfma_f32_16x16x32_bf16 v[112:115], v[176:179], v[184:187], v[112:115]
	v_mfma_f32_16x16x32_bf16 v[100:103], v[168:171], v[192:195], v[100:103]
	v_mfma_f32_16x16x32_bf16 v[96:99], v[176:179], v[192:195], v[96:99]
	v_mfma_f32_16x16x32_bf16 v[84:87], v[168:171], v[200:203], v[84:87]
	v_mfma_f32_16x16x32_bf16 v[80:83], v[176:179], v[200:203], v[80:83]
	v_mfma_f32_16x16x32_bf16 v[68:71], v[168:171], v[208:211], v[68:71]
	v_mfma_f32_16x16x32_bf16 v[64:67], v[176:179], v[208:211], v[64:67]
	s_setprio 0
	s_barrier
	s_add_i32 s33, s55, s34
	v_lshl_add_u64 v[212:213], s[62:63], 0, v[132:133]
	s_mov_b32 m0, s33
	ds_read_b128 v[180:183], v151 offset:16384
	ds_read_b128 v[184:187], v151 offset:17408
	ds_read_b128 v[188:191], v151 offset:18432
	ds_read_b128 v[192:195], v151 offset:19456
	ds_read_b128 v[196:199], v151 offset:20480
	ds_read_b128 v[200:203], v151 offset:21504
	ds_read_b128 v[204:207], v151 offset:22528
	ds_read_b128 v[208:211], v151 offset:23552
	global_load_lds_dwordx4 v[212:213], off
	s_add_i32 m0, s33, 0x2000
	v_lshl_add_u64 v[214:215], s[62:63], 0, v[128:129]
	s_add_u32 s62, s62, s8
	s_addc_u32 s63, s63, s9
	s_add_i32 s33, s56, s34
	global_load_lds_dwordx4 v[214:215], off
	v_lshl_add_u64 v[216:217], s[62:63], 0, v[132:133]
	s_mov_b32 m0, s33
	v_lshl_add_u64 v[218:219], s[62:63], 0, v[128:129]
	global_load_lds_dwordx4 v[216:217], off
	s_add_i32 m0, s33, 0x2000
	v_lshl_add_u64 v[220:221], s[28:29], 0, v[134:135]
	global_load_lds_dwordx4 v[218:219], off
	s_mov_b32 m0, s42
	v_lshl_add_u64 v[222:223], s[28:29], 0, v[130:131]
	global_load_lds_dwordx4 v[220:221], off
	s_mov_b32 m0, s43
	s_nop 0
	global_load_lds_dwordx4 v[222:223], off
	s_waitcnt vmcnt(8)
	s_waitcnt lgkmcnt(0)
	s_barrier
; #define PG8_STAGE(bufoff, gbase, voff) do { _Pragma("unroll") for (int _i = 0; _i < 2; ++_i) \
;         __builtin_amdgcn_global_load_lds((const unsigned*)((const char*)(gbase) + (voff)[_i]), (PG8_LAS unsigned*)(lds + (bufoff) + ldsw + _i * 8192), 16, 0, 0); } while (0)
; #define PG8_LDA(dst, b, h) do { _Pragma("unroll") for (int m = 0; m < 4; ++m) _Pragma("unroll") for (int k = 0; k < 2; ++k) dst[m][k] = *(const PG8_LAS bf16x8*)(lds + PG8_SA(b, h) + aoff + m * 2048 + k * 1024); } while (0)
; #define PG8_LDB(dst, b, h) do { _Pragma("unroll") for (int n = 0; n < 2; ++n) _Pragma("unroll") for (int k = 0; k < 2; ++k) dst[n][k] = *(const PG8_LAS bf16x8*)(lds + PG8_SB(b, h) + boff + n * 2048 + k * 1024); } while (0)
; #define PG8_MMA(ai, bj, At, Bt) do { __builtin_amdgcn_s_setprio(1); _Pragma("unroll") for (int m = 0; m < 4; ++m) _Pragma("unroll") for (int n = 0; n < 2; ++n) _Pragma("unroll") for (int k = 0; k < 2; ++k) \
;         acc[ai][bj][m][n] = __builtin_amdgcn_mfma_f32_16x16x32_bf16(Bt[n][k], At[m][k], acc[ai][bj][m][n], 0, 0, 0); __builtin_amdgcn_s_setprio(0); } while (0)
; #define PG8_WAIT_V(n) asm volatile("s_waitcnt vmcnt(" #n ")" ::: "memory")
; #define PG8_WAIT_L(n) asm volatile("s_waitcnt lgkmcnt(" #n ")" ::: "memory")
; #define PG8_BAR __builtin_amdgcn_s_barrier()
; #define PG8_SCHED __builtin_amdgcn_sched_barrier(0)
; template <class Epi, class Sched, bool ALIGN_EPI = false, bool SP2 = false>
; __device__ __forceinline__ void gemm_phase(PG8_LAS unsigned char* lds, const Gemm g, const Sched& S, const Epi& E, const int wid) {
;     ...
;             PG8_WAIT_V(8); PG8_WAIT_L(0); PG8_BAR; PG8_MMA(1, 0, At, B0); PG8_MMA(1, 1, At, B1); PG8_BAR; PG8_SCHED;
;             PG8_LDB(B0, 1, 0); PG8_LDB(B1, 1, 1); PG8_SCHED; PG8_LDA(At, 1, 0); PG8_STAGE(PG8_SA(0, 1), a2 + hstep, voffA);
;             PG8_WAIT_V(8); PG8_WAIT_L(0); PG8_BAR; PG8_MMA(0, 0, At, B0); PG8_MMA(0, 1, At, B1); PG8_BAR; PG8_SCHED;
	s_setprio 1
	s_waitcnt lgkmcnt(0)
	v_mfma_f32_16x16x32_bf16 v[60:63], v[142:145], v[180:183], 0
	v_mfma_f32_16x16x32_bf16 v[56:59], v[156:159], v[180:183], 0
	v_mfma_f32_16x16x32_bf16 v[44:47], v[142:145], v[188:191], 0
	v_mfma_f32_16x16x32_bf16 v[40:43], v[156:159], v[188:191], 0
	v_mfma_f32_16x16x32_bf16 v[28:31], v[142:145], v[196:199], 0
	v_mfma_f32_16x16x32_bf16 v[24:27], v[156:159], v[196:199], 0
	v_mfma_f32_16x16x32_bf16 v[12:15], v[142:145], v[204:207], 0
	v_mfma_f32_16x16x32_bf16 v[8:11], v[156:159], v[204:207], 0
	v_mfma_f32_16x16x32_bf16 v[60:63], v[152:155], v[184:187], v[60:63]
	v_mfma_f32_16x16x32_bf16 v[56:59], v[160:163], v[184:187], v[56:59]
	v_mfma_f32_16x16x32_bf16 v[44:47], v[152:155], v[192:195], v[44:47]
	v_mfma_f32_16x16x32_bf16 v[40:43], v[160:163], v[192:195], v[40:43]
	v_mfma_f32_16x16x32_bf16 v[28:31], v[152:155], v[200:203], v[28:31]
	v_mfma_f32_16x16x32_bf16 v[24:27], v[160:163], v[200:203], v[24:27]
	v_mfma_f32_16x16x32_bf16 v[12:15], v[152:155], v[208:211], v[12:15]
	v_mfma_f32_16x16x32_bf16 v[8:11], v[160:163], v[208:211], v[8:11]
	s_setprio 0
	s_setprio 1
	v_mfma_f32_16x16x32_bf16 v[52:55], v[164:167], v[180:183], 0
	v_mfma_f32_16x16x32_bf16 v[48:51], v[172:175], v[180:183], 0
	v_mfma_f32_16x16x32_bf16 v[36:39], v[164:167], v[188:191], 0
	v_mfma_f32_16x16x32_bf16 v[32:35], v[172:175], v[188:191], 0
	v_mfma_f32_16x16x32_bf16 v[20:23], v[164:167], v[196:199], 0
	v_mfma_f32_16x16x32_bf16 v[16:19], v[172:175], v[196:199], 0
	v_mfma_f32_16x16x32_bf16 v[4:7], v[164:167], v[204:207], 0
	v_mfma_f32_16x16x32_bf16 v[0:3], v[172:175], v[204:207], 0
	v_mfma_f32_16x16x32_bf16 v[52:55], v[168:171], v[184:187], v[52:55]
	v_mfma_f32_16x16x32_bf16 v[48:51], v[176:179], v[184:187], v[48:51]
	v_mfma_f32_16x16x32_bf16 v[36:39], v[168:171], v[192:195], v[36:39]
	v_mfma_f32_16x16x32_bf16 v[32:35], v[176:179], v[192:195], v[32:35]
	v_mfma_f32_16x16x32_bf16 v[20:23], v[168:171], v[200:203], v[20:23]
	v_mfma_f32_16x16x32_bf16 v[16:19], v[176:179], v[200:203], v[16:19]
	v_mfma_f32_16x16x32_bf16 v[4:7], v[168:171], v[208:211], v[4:7]
	v_mfma_f32_16x16x32_bf16 v[0:3], v[176:179], v[208:211], v[0:3]
	s_setprio 0
	s_barrier
	s_add_i32 s33, 0, 0x18000
	s_add_i32 s62, 0, 0x1c000
	v_add_u32_e32 v160, s33, v148
	v_add_u32_e32 v176, s62, v148
	ds_read_b128 v[142:145], v160
	ds_read_b128 v[152:155], v160 offset:1024
	ds_read_b128 v[156:159], v160 offset:2048
	ds_read_b128 v[160:163], v160 offset:3072
	ds_read_b128 v[164:167], v176
	ds_read_b128 v[168:171], v176 offset:1024
	ds_read_b128 v[172:175], v176 offset:2048
	ds_read_b128 v[176:179], v176 offset:3072
	s_add_u32 s28, s28, s8
	s_addc_u32 s29, s29, s9
	s_mov_b32 m0, s44
	v_lshl_add_u64 v[224:225], s[28:29], 0, v[134:135]
	ds_read_b128 v[180:183], v151 offset:32768
	ds_read_b128 v[184:187], v151 offset:33792
	ds_read_b128 v[188:191], v151 offset:34816
	ds_read_b128 v[192:195], v151 offset:35840
	ds_read_b128 v[196:199], v151 offset:36864
	ds_read_b128 v[200:203], v151 offset:37888
	ds_read_b128 v[204:207], v151 offset:38912
	ds_read_b128 v[208:211], v151 offset:39936
	global_load_lds_dwordx4 v[224:225], off
	v_lshl_add_u64 v[224:225], s[28:29], 0, v[130:131]
	s_mov_b32 m0, s45
	s_nop 0
	global_load_lds_dwordx4 v[224:225], off
	s_waitcnt vmcnt(8)
	s_waitcnt lgkmcnt(0)
	s_barrier
	s_setprio 1
	s_waitcnt lgkmcnt(0)
	v_mfma_f32_16x16x32_bf16 v[124:127], v[142:145], v[180:183], v[124:127]
	v_mfma_f32_16x16x32_bf16 v[120:123], v[156:159], v[180:183], v[120:123]
	v_mfma_f32_16x16x32_bf16 v[108:111], v[142:145], v[188:191], v[108:111]
	v_mfma_f32_16x16x32_bf16 v[104:107], v[156:159], v[188:191], v[104:107]
	v_mfma_f32_16x16x32_bf16 v[92:95], v[142:145], v[196:199], v[92:95]
	v_mfma_f32_16x16x32_bf16 v[88:91], v[156:159], v[196:199], v[88:91]
	v_mfma_f32_16x16x32_bf16 v[76:79], v[142:145], v[204:207], v[76:79]
	v_mfma_f32_16x16x32_bf16 v[72:75], v[156:159], v[204:207], v[72:75]
	v_mfma_f32_16x16x32_bf16 v[124:127], v[152:155], v[184:187], v[124:127]
	v_mfma_f32_16x16x32_bf16 v[120:123], v[160:163], v[184:187], v[120:123]
	v_mfma_f32_16x16x32_bf16 v[108:111], v[152:155], v[192:195], v[108:111]
	v_mfma_f32_16x16x32_bf16 v[104:107], v[160:163], v[192:195], v[104:107]
	v_mfma_f32_16x16x32_bf16 v[92:95], v[152:155], v[200:203], v[92:95]
	v_mfma_f32_16x16x32_bf16 v[88:91], v[160:163], v[200:203], v[88:91]
	v_mfma_f32_16x16x32_bf16 v[76:79], v[152:155], v[208:211], v[76:79]
	v_mfma_f32_16x16x32_bf16 v[72:75], v[160:163], v[208:211], v[72:75]
	s_setprio 0
	s_setprio 1
	v_mfma_f32_16x16x32_bf16 v[116:119], v[164:167], v[180:183], v[116:119]
	v_mfma_f32_16x16x32_bf16 v[112:115], v[172:175], v[180:183], v[112:115]
	v_mfma_f32_16x16x32_bf16 v[100:103], v[164:167], v[188:191], v[100:103]
	v_mfma_f32_16x16x32_bf16 v[96:99], v[172:175], v[188:191], v[96:99]
	v_mfma_f32_16x16x32_bf16 v[84:87], v[164:167], v[196:199], v[84:87]
	v_mfma_f32_16x16x32_bf16 v[80:83], v[172:175], v[196:199], v[80:83]
	v_mfma_f32_16x16x32_bf16 v[68:71], v[164:167], v[204:207], v[68:71]
	v_mfma_f32_16x16x32_bf16 v[64:67], v[172:175], v[204:207], v[64:67]
	v_mfma_f32_16x16x32_bf16 v[116:119], v[168:171], v[184:187], v[116:119]
	v_mfma_f32_16x16x32_bf16 v[112:115], v[176:179], v[184:187], v[112:115]
	v_mfma_f32_16x16x32_bf16 v[100:103], v[168:171], v[192:195], v[100:103]
	v_mfma_f32_16x16x32_bf16 v[96:99], v[176:179], v[192:195], v[96:99]
	v_mfma_f32_16x16x32_bf16 v[84:87], v[168:171], v[200:203], v[84:87]
	v_mfma_f32_16x16x32_bf16 v[80:83], v[176:179], v[200:203], v[80:83]
	v_mfma_f32_16x16x32_bf16 v[68:71], v[168:171], v[208:211], v[68:71]
	v_mfma_f32_16x16x32_bf16 v[64:67], v[176:179], v[208:211], v[64:67]
	s_setprio 0
	s_barrier
; #define PG8_STAGE(bufoff, gbase, voff) do { _Pragma("unroll") for (int _i = 0; _i < 2; ++_i) \
;         __builtin_amdgcn_global_load_lds((const unsigned*)((const char*)(gbase) + (voff)[_i]), (PG8_LAS unsigned*)(lds + (bufoff) + ldsw + _i * 8192), 16, 0, 0); } while (0)
; #define PG8_LDA(dst, b, h) do { _Pragma("unroll") for (int m = 0; m < 4; ++m) _Pragma("unroll") for (int k = 0; k < 2; ++k) dst[m][k] = *(const PG8_LAS bf16x8*)(lds + PG8_SA(b, h) + aoff + m * 2048 + k * 1024); } while (0)
; #define PG8_MMA(ai, bj, At, Bt) do { __builtin_amdgcn_s_setprio(1); _Pragma("unroll") for (int m = 0; m < 4; ++m) _Pragma("unroll") for (int n = 0; n < 2; ++n) _Pragma("unroll") for (int k = 0; k < 2; ++k) \
;         acc[ai][bj][m][n] = __builtin_amdgcn_mfma_f32_16x16x32_bf16(Bt[n][k], At[m][k], acc[ai][bj][m][n], 0, 0, 0); __builtin_amdgcn_s_setprio(0); } while (0)
; #define PG8_WAIT_V(n) asm volatile("s_waitcnt vmcnt(" #n ")" ::: "memory")
; #define PG8_WAIT_L(n) asm volatile("s_waitcnt lgkmcnt(" #n ")" ::: "memory")
; #define PG8_BAR __builtin_amdgcn_s_barrier()
; #define PG8_SCHED __builtin_amdgcn_sched_barrier(0)
; template <class Epi, class Sched, bool ALIGN_EPI = false, bool SP2 = false>
; __device__ __forceinline__ void gemm_phase(PG8_LAS unsigned char* lds, const Gemm g, const Sched& S, const Epi& E, const int wid) {
;     ...
;         for (int t = 0; t < nt; t += 2) {
;             const bool last = (t == nt - 2);
;             const char* a1 = cA + (size_t)(t + 1) * kstep;
;             const char* a2 = last ? nA : cA + (size_t)(t + 2) * kstep; const char* b2 = last ? nB : cB + (size_t)(t + 2) * kstep;
;             const char* a3 = a2 + kstep; const char* b3 = b2 + kstep;
;     ...
;             PG8_LDA(At, 1, 1); PG8_STAGE(PG8_SB(1, 0), b3, voffB); PG8_STAGE(PG8_SB(1, 1), b3 + hstep, voffB); PG8_STAGE(PG8_SA(1, 0), a3, voffA);
;             PG8_WAIT_V(8); PG8_WAIT_L(0); PG8_BAR; PG8_MMA(1, 0, At, B0); PG8_MMA(1, 1, At, B1); PG8_BAR; PG8_SCHED;
	s_add_i32 s28, s33, s34
	v_lshl_add_u64 v[212:213], v[212:213], 0, s[18:19]
	s_mov_b32 m0, s28
	ds_read_b128 v[180:183], v151 offset:49152
	ds_read_b128 v[184:187], v151 offset:50176
	ds_read_b128 v[188:191], v151 offset:51200
	ds_read_b128 v[192:195], v151 offset:52224
	ds_read_b128 v[196:199], v151 offset:53248
	ds_read_b128 v[200:203], v151 offset:54272
	ds_read_b128 v[204:207], v151 offset:55296
	ds_read_b128 v[208:211], v151 offset:56320
	global_load_lds_dwordx4 v[212:213], off
	v_lshl_add_u64 v[212:213], v[214:215], 0, s[18:19]
	s_add_i32 m0, s28, 0x2000
	s_add_i32 s28, s62, s34
	global_load_lds_dwordx4 v[212:213], off
	v_lshl_add_u64 v[212:213], v[216:217], 0, s[18:19]
	s_mov_b32 m0, s28
	s_nop 0
	global_load_lds_dwordx4 v[212:213], off
	v_lshl_add_u64 v[212:213], v[218:219], 0, s[18:19]
	s_add_i32 m0, s28, 0x2000
	s_nop 0
	global_load_lds_dwordx4 v[212:213], off
	v_lshl_add_u64 v[212:213], v[220:221], 0, s[18:19]
	s_mov_b32 m0, s47
	s_nop 0
	global_load_lds_dwordx4 v[212:213], off
	v_lshl_add_u64 v[212:213], v[222:223], 0, s[18:19]
	s_mov_b32 m0, s49
	s_nop 0
	global_load_lds_dwordx4 v[212:213], off
	s_waitcnt vmcnt(8)
	s_waitcnt lgkmcnt(0)
	s_barrier
	s_setprio 1
	s_waitcnt lgkmcnt(0)
	v_mfma_f32_16x16x32_bf16 v[60:63], v[142:145], v[180:183], v[60:63]
	v_mfma_f32_16x16x32_bf16 v[56:59], v[156:159], v[180:183], v[56:59]
	v_mfma_f32_16x16x32_bf16 v[44:47], v[142:145], v[188:191], v[44:47]
	v_mfma_f32_16x16x32_bf16 v[40:43], v[156:159], v[188:191], v[40:43]
	v_mfma_f32_16x16x32_bf16 v[28:31], v[142:145], v[196:199], v[28:31]
	v_mfma_f32_16x16x32_bf16 v[24:27], v[156:159], v[196:199], v[24:27]
	v_mfma_f32_16x16x32_bf16 v[12:15], v[142:145], v[204:207], v[12:15]
	v_mfma_f32_16x16x32_bf16 v[8:11], v[156:159], v[204:207], v[8:11]
	v_mfma_f32_16x16x32_bf16 v[60:63], v[152:155], v[184:187], v[60:63]
	v_mfma_f32_16x16x32_bf16 v[56:59], v[160:163], v[184:187], v[56:59]
	v_mfma_f32_16x16x32_bf16 v[44:47], v[152:155], v[192:195], v[44:47]
	v_mfma_f32_16x16x32_bf16 v[40:43], v[160:163], v[192:195], v[40:43]
	v_mfma_f32_16x16x32_bf16 v[28:31], v[152:155], v[200:203], v[28:31]
	v_mfma_f32_16x16x32_bf16 v[24:27], v[160:163], v[200:203], v[24:27]
	v_mfma_f32_16x16x32_bf16 v[12:15], v[152:155], v[208:211], v[12:15]
	v_mfma_f32_16x16x32_bf16 v[8:11], v[160:163], v[208:211], v[8:11]
	s_setprio 0
	s_setprio 1
	v_mfma_f32_16x16x32_bf16 v[52:55], v[164:167], v[180:183], v[52:55]
	v_mfma_f32_16x16x32_bf16 v[48:51], v[172:175], v[180:183], v[48:51]
	v_mfma_f32_16x16x32_bf16 v[36:39], v[164:167], v[188:191], v[36:39]
	v_mfma_f32_16x16x32_bf16 v[32:35], v[172:175], v[188:191], v[32:35]
	v_mfma_f32_16x16x32_bf16 v[20:23], v[164:167], v[196:199], v[20:23]
	v_mfma_f32_16x16x32_bf16 v[16:19], v[172:175], v[196:199], v[16:19]
	v_mfma_f32_16x16x32_bf16 v[4:7], v[164:167], v[204:207], v[4:7]
	v_mfma_f32_16x16x32_bf16 v[0:3], v[172:175], v[204:207], v[0:3]
	v_mfma_f32_16x16x32_bf16 v[52:55], v[168:171], v[184:187], v[52:55]
	v_mfma_f32_16x16x32_bf16 v[48:51], v[176:179], v[184:187], v[48:51]
	v_mfma_f32_16x16x32_bf16 v[36:39], v[168:171], v[192:195], v[36:39]
	v_mfma_f32_16x16x32_bf16 v[32:35], v[176:179], v[192:195], v[32:35]
	v_mfma_f32_16x16x32_bf16 v[20:23], v[168:171], v[200:203], v[20:23]
	v_mfma_f32_16x16x32_bf16 v[16:19], v[176:179], v[200:203], v[16:19]
	v_mfma_f32_16x16x32_bf16 v[4:7], v[168:171], v[208:211], v[4:7]
	v_mfma_f32_16x16x32_bf16 v[0:3], v[176:179], v[208:211], v[0:3]
	s_setprio 0
	s_barrier
	s_add_u32 s26, s26, 0x100
	s_addc_u32 s27, s27, 0
	s_add_u32 s0, s0, 0x100
	s_addc_u32 s1, s1, 0
	s_cmp_ge_i32 s61, s50
	s_mov_b32 s28, s61
	s_cbranch_scc1 .LBB0_1180

; #define PG8_STAGE(bufoff, gbase, voff) do { _Pragma("unroll") for (int _i = 0; _i < 2; ++_i) \
;         __builtin_amdgcn_global_load_lds((const unsigned*)((const char*)(gbase) + (voff)[_i]), (PG8_LAS unsigned*)(lds + (bufoff) + ldsw + _i * 8192), 16, 0, 0); } while (0)
; #define PG8_LDA(dst, b, h) do { _Pragma("unroll") for (int m = 0; m < 4; ++m) _Pragma("unroll") for (int k = 0; k < 2; ++k) dst[m][k] = *(const PG8_LAS bf16x8*)(lds + PG8_SA(b, h) + aoff + m * 2048 + k * 1024); } while (0)
; #define PG8_LDB(dst, b, h) do { _Pragma("unroll") for (int n = 0; n < 2; ++n) _Pragma("unroll") for (int k = 0; k < 2; ++k) dst[n][k] = *(const PG8_LAS bf16x8*)(lds + PG8_SB(b, h) + boff + n * 2048 + k * 1024); } while (0)
; #define PG8_MMA(ai, bj, At, Bt) do { __builtin_amdgcn_s_setprio(1); _Pragma("unroll") for (int m = 0; m < 4; ++m) _Pragma("unroll") for (int n = 0; n < 2; ++n) _Pragma("unroll") for (int k = 0; k < 2; ++k) \
;         acc[ai][bj][m][n] = __builtin_amdgcn_mfma_f32_16x16x32_bf16(Bt[n][k], At[m][k], acc[ai][bj][m][n], 0, 0, 0); __builtin_amdgcn_s_setprio(0); } while (0)
; template <class Epi, class Sched, bool ALIGN_EPI = false, bool SP2 = false>
; __device__ __forceinline__ void gemm_phase(PG8_LAS unsigned char* lds, const Gemm g, const Sched& S, const Epi& E, const int wid) {
;     ...
;         const bool has_next = S.next(ui + 1, nxt);
;         const char* nA = has_next ? (const char*)g.A + (size_t)nxt.pm * tstep : cA; const char* nB = has_next ? (const char*)g.Bt + (size_t)nxt.pn * tstep : cB;
;         for (int t = 0; t < nt; t += 2) {
;             const bool last = (t == nt - 2);
;             const char* a1 = cA + (size_t)(t + 1) * kstep;
;             const char* a2 = last ? nA : cA + (size_t)(t + 2) * kstep; const char* b2 = last ? nB : cB + (size_t)(t + 2) * kstep;
;             const char* a3 = a2 + kstep; const char* b3 = b2 + kstep;
;             if (last && has_next) S.a_ready(nxt);
;             if constexpr (SP2) {
;             PG8_LDB(B0, 0, 0); PG8_LDB(B1, 0, 1); PG8_SCHED; PG8_LDA(At, 0, 0); PG8_STAGE(PG8_SA(1, 1), a1 + hstep, voffA);
;             PG8_WAIT_V(8); PG8_WAIT_L(0); PG8_BAR; PG8_MMA(0, 0, At, B0); PG8_MMA(0, 1, At, B1); PG8_BAR; PG8_SCHED;
;             PG8_LDA(At, 0, 1); PG8_STAGE(PG8_SB(0, 0), b2, voffB); PG8_STAGE(PG8_SB(0, 1), b2 + hstep, voffB); PG8_STAGE(PG8_SA(0, 0), a2, voffA);
.LBB0_1256:
	s_andn2_b64 vcc, exec, s[20:21]
	s_cbranch_vccnz .Lz_GMB
	s_add_u32 s28, s28, 0x80
	s_addc_u32 s29, s29, 0
	s_add_u32 s0, s30, 0x100
	s_addc_u32 s1, s31, 0
	s_mov_b32 s30, 0
	ds_read_b128 v[142:145], v149
	ds_read_b128 v[152:155], v149 offset:1024
	ds_read_b128 v[156:159], v149 offset:2048
	ds_read_b128 v[160:163], v149 offset:3072
	ds_read_b128 v[164:167], v150
	ds_read_b128 v[168:171], v150 offset:1024
	ds_read_b128 v[172:175], v150 offset:2048
	ds_read_b128 v[176:179], v150 offset:3072
	s_add_i32 s66, s30, 2
	s_add_u32 s33, s28, 0x80
	s_addc_u32 s31, s29, 0
	s_cmp_eq_u32 s57, s30
	s_cselect_b32 s30, s4, s33
	s_cselect_b32 s31, s5, s31
	s_cselect_b32 s69, s27, s1
	s_cselect_b32 s68, s26, s0
	v_lshl_add_u64 v[212:213], s[28:29], 0, v[136:137]
	s_add_i32 m0, s46, 0xc000
	ds_read_b128 v[180:183], v151
	ds_read_b128 v[184:187], v151 offset:1024
	ds_read_b128 v[188:191], v151 offset:2048
	ds_read_b128 v[192:195], v151 offset:3072
	ds_read_b128 v[196:199], v151 offset:4096
	ds_read_b128 v[200:203], v151 offset:5120
	ds_read_b128 v[204:207], v151 offset:6144
	ds_read_b128 v[208:211], v151 offset:7168
	global_load_lds_dwordx4 v[212:213], off
	v_lshl_add_u64 v[212:213], s[28:29], 0, v[138:139]
	s_add_i32 m0, s46, 0xe000
	s_nop 0
	global_load_lds_dwordx4 v[212:213], off
	s_waitcnt vmcnt(8)
	s_waitcnt lgkmcnt(0)
	s_barrier
	s_setprio 1
	s_waitcnt lgkmcnt(0)
	v_mfma_f32_16x16x32_bf16 v[124:127], v[142:145], v[180:183], 0
	v_mfma_f32_16x16x32_bf16 v[120:123], v[156:159], v[180:183], 0
	v_mfma_f32_16x16x32_bf16 v[108:111], v[142:145], v[188:191], 0
	v_mfma_f32_16x16x32_bf16 v[104:107], v[156:159], v[188:191], 0
	v_mfma_f32_16x16x32_bf16 v[92:95], v[142:145], v[196:199], 0
	v_mfma_f32_16x16x32_bf16 v[88:91], v[156:159], v[196:199], 0
	v_mfma_f32_16x16x32_bf16 v[76:79], v[142:145], v[204:207], 0
	v_mfma_f32_16x16x32_bf16 v[72:75], v[156:159], v[204:207], 0
	v_mfma_f32_16x16x32_bf16 v[124:127], v[152:155], v[184:187], v[124:127]
	v_mfma_f32_16x16x32_bf16 v[120:123], v[160:163], v[184:187], v[120:123]
	v_mfma_f32_16x16x32_bf16 v[108:111], v[152:155], v[192:195], v[108:111]
	v_mfma_f32_16x16x32_bf16 v[104:107], v[160:163], v[192:195], v[104:107]
	v_mfma_f32_16x16x32_bf16 v[92:95], v[152:155], v[200:203], v[92:95]
	v_mfma_f32_16x16x32_bf16 v[88:91], v[160:163], v[200:203], v[88:91]
	v_mfma_f32_16x16x32_bf16 v[76:79], v[152:155], v[208:211], v[76:79]
	v_mfma_f32_16x16x32_bf16 v[72:75], v[160:163], v[208:211], v[72:75]
	s_setprio 0
	s_setprio 1
	v_mfma_f32_16x16x32_bf16 v[116:119], v[164:167], v[180:183], 0
	v_mfma_f32_16x16x32_bf16 v[112:115], v[172:175], v[180:183], 0
	v_mfma_f32_16x16x32_bf16 v[100:103], v[164:167], v[188:191], 0
	v_mfma_f32_16x16x32_bf16 v[96:99], v[172:175], v[188:191], 0
	v_mfma_f32_16x16x32_bf16 v[84:87], v[164:167], v[196:199], 0
	v_mfma_f32_16x16x32_bf16 v[80:83], v[172:175], v[196:199], 0
	v_mfma_f32_16x16x32_bf16 v[68:71], v[164:167], v[204:207], 0
	v_mfma_f32_16x16x32_bf16 v[64:67], v[172:175], v[204:207], 0
	v_mfma_f32_16x16x32_bf16 v[116:119], v[168:171], v[184:187], v[116:119]
	v_mfma_f32_16x16x32_bf16 v[112:115], v[176:179], v[184:187], v[112:115]
	v_mfma_f32_16x16x32_bf16 v[100:103], v[168:171], v[192:195], v[100:103]
	v_mfma_f32_16x16x32_bf16 v[96:99], v[176:179], v[192:195], v[96:99]
	v_mfma_f32_16x16x32_bf16 v[84:87], v[168:171], v[200:203], v[84:87]
	v_mfma_f32_16x16x32_bf16 v[80:83], v[176:179], v[200:203], v[80:83]
	v_mfma_f32_16x16x32_bf16 v[68:71], v[168:171], v[208:211], v[68:71]
	v_mfma_f32_16x16x32_bf16 v[64:67], v[176:179], v[208:211], v[64:67]
	s_setprio 0
	s_barrier
	s_add_i32 s33, s59, s38
	v_lshl_add_u64 v[212:213], s[68:69], 0, v[132:133]
	s_mov_b32 m0, s33
	ds_read_b128 v[180:183], v151 offset:16384
	ds_read_b128 v[184:187], v151 offset:17408
	ds_read_b128 v[188:191], v151 offset:18432
	ds_read_b128 v[192:195], v151 offset:19456
	ds_read_b128 v[196:199], v151 offset:20480
	ds_read_b128 v[200:203], v151 offset:21504
	ds_read_b128 v[204:207], v151 offset:22528
	ds_read_b128 v[208:211], v151 offset:23552
	global_load_lds_dwordx4 v[212:213], off
	s_add_i32 m0, s33, 0x2000
	v_lshl_add_u64 v[214:215], s[68:69], 0, v[128:129]
	s_add_u32 s68, s68, s8
	s_addc_u32 s69, s69, s9
	s_add_i32 s33, s60, s38
	global_load_lds_dwordx4 v[214:215], off
	v_lshl_add_u64 v[216:217], s[68:69], 0, v[132:133]
	s_mov_b32 m0, s33
	v_lshl_add_u64 v[218:219], s[68:69], 0, v[128:129]
	global_load_lds_dwordx4 v[216:217], off
	s_add_i32 m0, s33, 0x2000
	v_lshl_add_u64 v[220:221], s[30:31], 0, v[134:135]
	global_load_lds_dwordx4 v[218:219], off
	s_mov_b32 m0, s46
	v_lshl_add_u64 v[222:223], s[30:31], 0, v[130:131]
	global_load_lds_dwordx4 v[220:221], off
	s_mov_b32 m0, s47
	s_nop 0
	global_load_lds_dwordx4 v[222:223], off
	s_waitcnt vmcnt(8)
	s_waitcnt lgkmcnt(0)
	s_barrier
; #define PG8_STAGE(bufoff, gbase, voff) do { _Pragma("unroll") for (int _i = 0; _i < 2; ++_i) \
;         __builtin_amdgcn_global_load_lds((const unsigned*)((const char*)(gbase) + (voff)[_i]), (PG8_LAS unsigned*)(lds + (bufoff) + ldsw + _i * 8192), 16, 0, 0); } while (0)
; #define PG8_LDA(dst, b, h) do { _Pragma("unroll") for (int m = 0; m < 4; ++m) _Pragma("unroll") for (int k = 0; k < 2; ++k) dst[m][k] = *(const PG8_LAS bf16x8*)(lds + PG8_SA(b, h) + aoff + m * 2048 + k * 1024); } while (0)
; #define PG8_LDB(dst, b, h) do { _Pragma("unroll") for (int n = 0; n < 2; ++n) _Pragma("unroll") for (int k = 0; k < 2; ++k) dst[n][k] = *(const PG8_LAS bf16x8*)(lds + PG8_SB(b, h) + boff + n * 2048 + k * 1024); } while (0)
; #define PG8_MMA(ai, bj, At, Bt) do { __builtin_amdgcn_s_setprio(1); _Pragma("unroll") for (int m = 0; m < 4; ++m) _Pragma("unroll") for (int n = 0; n < 2; ++n) _Pragma("unroll") for (int k = 0; k < 2; ++k) \
;         acc[ai][bj][m][n] = __builtin_amdgcn_mfma_f32_16x16x32_bf16(Bt[n][k], At[m][k], acc[ai][bj][m][n], 0, 0, 0); __builtin_amdgcn_s_setprio(0); } while (0)
; #define PG8_WAIT_V(n) asm volatile("s_waitcnt vmcnt(" #n ")" ::: "memory")
; #define PG8_WAIT_L(n) asm volatile("s_waitcnt lgkmcnt(" #n ")" ::: "memory")
; #define PG8_BAR __builtin_amdgcn_s_barrier()
; #define PG8_SCHED __builtin_amdgcn_sched_barrier(0)
; template <class Epi, class Sched, bool ALIGN_EPI = false, bool SP2 = false>
; __device__ __forceinline__ void gemm_phase(PG8_LAS unsigned char* lds, const Gemm g, const Sched& S, const Epi& E, const int wid) {
;     ...
;             PG8_WAIT_V(8); PG8_WAIT_L(0); PG8_BAR; PG8_MMA(1, 0, At, B0); PG8_MMA(1, 1, At, B1); PG8_BAR; PG8_SCHED;
;             PG8_LDB(B0, 1, 0); PG8_LDB(B1, 1, 1); PG8_SCHED; PG8_LDA(At, 1, 0); PG8_STAGE(PG8_SA(0, 1), a2 + hstep, voffA);
;             PG8_WAIT_V(8); PG8_WAIT_L(0); PG8_BAR; PG8_MMA(0, 0, At, B0); PG8_MMA(0, 1, At, B1); PG8_BAR; PG8_SCHED;
	s_setprio 1
	s_waitcnt lgkmcnt(0)
	v_mfma_f32_16x16x32_bf16 v[60:63], v[142:145], v[180:183], 0
	v_mfma_f32_16x16x32_bf16 v[56:59], v[156:159], v[180:183], 0
	v_mfma_f32_16x16x32_bf16 v[44:47], v[142:145], v[188:191], 0
	v_mfma_f32_16x16x32_bf16 v[40:43], v[156:159], v[188:191], 0
	v_mfma_f32_16x16x32_bf16 v[28:31], v[142:145], v[196:199], 0
	v_mfma_f32_16x16x32_bf16 v[24:27], v[156:159], v[196:199], 0
	v_mfma_f32_16x16x32_bf16 v[12:15], v[142:145], v[204:207], 0
	v_mfma_f32_16x16x32_bf16 v[8:11], v[156:159], v[204:207], 0
	v_mfma_f32_16x16x32_bf16 v[60:63], v[152:155], v[184:187], v[60:63]
	v_mfma_f32_16x16x32_bf16 v[56:59], v[160:163], v[184:187], v[56:59]
	v_mfma_f32_16x16x32_bf16 v[44:47], v[152:155], v[192:195], v[44:47]
	v_mfma_f32_16x16x32_bf16 v[40:43], v[160:163], v[192:195], v[40:43]
	v_mfma_f32_16x16x32_bf16 v[28:31], v[152:155], v[200:203], v[28:31]
	v_mfma_f32_16x16x32_bf16 v[24:27], v[160:163], v[200:203], v[24:27]
	v_mfma_f32_16x16x32_bf16 v[12:15], v[152:155], v[208:211], v[12:15]
	v_mfma_f32_16x16x32_bf16 v[8:11], v[160:163], v[208:211], v[8:11]
	s_setprio 0
	s_setprio 1
	v_mfma_f32_16x16x32_bf16 v[52:55], v[164:167], v[180:183], 0
	v_mfma_f32_16x16x32_bf16 v[48:51], v[172:175], v[180:183], 0
	v_mfma_f32_16x16x32_bf16 v[36:39], v[164:167], v[188:191], 0
	v_mfma_f32_16x16x32_bf16 v[32:35], v[172:175], v[188:191], 0
	v_mfma_f32_16x16x32_bf16 v[20:23], v[164:167], v[196:199], 0
	v_mfma_f32_16x16x32_bf16 v[16:19], v[172:175], v[196:199], 0
	v_mfma_f32_16x16x32_bf16 v[4:7], v[164:167], v[204:207], 0
	v_mfma_f32_16x16x32_bf16 v[0:3], v[172:175], v[204:207], 0
	v_mfma_f32_16x16x32_bf16 v[52:55], v[168:171], v[184:187], v[52:55]
	v_mfma_f32_16x16x32_bf16 v[48:51], v[176:179], v[184:187], v[48:51]
	v_mfma_f32_16x16x32_bf16 v[36:39], v[168:171], v[192:195], v[36:39]
	v_mfma_f32_16x16x32_bf16 v[32:35], v[176:179], v[192:195], v[32:35]
	v_mfma_f32_16x16x32_bf16 v[20:23], v[168:171], v[200:203], v[20:23]
	v_mfma_f32_16x16x32_bf16 v[16:19], v[176:179], v[200:203], v[16:19]
	v_mfma_f32_16x16x32_bf16 v[4:7], v[168:171], v[208:211], v[4:7]
	v_mfma_f32_16x16x32_bf16 v[0:3], v[176:179], v[208:211], v[0:3]
	s_setprio 0
	s_barrier
	s_add_i32 s33, 0, 0x18000
	s_add_i32 s67, 0, 0x1c000
	v_add_u32_e32 v160, s33, v148
	v_add_u32_e32 v176, s67, v148
	ds_read_b128 v[142:145], v160
	ds_read_b128 v[152:155], v160 offset:1024
	ds_read_b128 v[156:159], v160 offset:2048
	ds_read_b128 v[160:163], v160 offset:3072
	ds_read_b128 v[164:167], v176
	ds_read_b128 v[168:171], v176 offset:1024
	ds_read_b128 v[172:175], v176 offset:2048
	ds_read_b128 v[176:179], v176 offset:3072
	s_add_u32 s30, s30, s8
	s_addc_u32 s31, s31, s9
	s_mov_b32 m0, s49
	v_lshl_add_u64 v[224:225], s[30:31], 0, v[134:135]
	ds_read_b128 v[180:183], v151 offset:32768
	ds_read_b128 v[184:187], v151 offset:33792
	ds_read_b128 v[188:191], v151 offset:34816
	ds_read_b128 v[192:195], v151 offset:35840
	ds_read_b128 v[196:199], v151 offset:36864
	ds_read_b128 v[200:203], v151 offset:37888
	ds_read_b128 v[204:207], v151 offset:38912
	ds_read_b128 v[208:211], v151 offset:39936
	global_load_lds_dwordx4 v[224:225], off
	v_lshl_add_u64 v[224:225], s[30:31], 0, v[130:131]
	s_mov_b32 m0, s50
	s_nop 0
	global_load_lds_dwordx4 v[224:225], off
	s_waitcnt vmcnt(8)
	s_waitcnt lgkmcnt(0)
	s_barrier
	s_setprio 1
	s_waitcnt lgkmcnt(0)
	v_mfma_f32_16x16x32_bf16 v[124:127], v[142:145], v[180:183], v[124:127]
	v_mfma_f32_16x16x32_bf16 v[120:123], v[156:159], v[180:183], v[120:123]
	v_mfma_f32_16x16x32_bf16 v[108:111], v[142:145], v[188:191], v[108:111]
	v_mfma_f32_16x16x32_bf16 v[104:107], v[156:159], v[188:191], v[104:107]
	v_mfma_f32_16x16x32_bf16 v[92:95], v[142:145], v[196:199], v[92:95]
	v_mfma_f32_16x16x32_bf16 v[88:91], v[156:159], v[196:199], v[88:91]
	v_mfma_f32_16x16x32_bf16 v[76:79], v[142:145], v[204:207], v[76:79]
	v_mfma_f32_16x16x32_bf16 v[72:75], v[156:159], v[204:207], v[72:75]
	v_mfma_f32_16x16x32_bf16 v[124:127], v[152:155], v[184:187], v[124:127]
	v_mfma_f32_16x16x32_bf16 v[120:123], v[160:163], v[184:187], v[120:123]
	v_mfma_f32_16x16x32_bf16 v[108:111], v[152:155], v[192:195], v[108:111]
	v_mfma_f32_16x16x32_bf16 v[104:107], v[160:163], v[192:195], v[104:107]
	v_mfma_f32_16x16x32_bf16 v[92:95], v[152:155], v[200:203], v[92:95]
	v_mfma_f32_16x16x32_bf16 v[88:91], v[160:163], v[200:203], v[88:91]
	v_mfma_f32_16x16x32_bf16 v[76:79], v[152:155], v[208:211], v[76:79]
	v_mfma_f32_16x16x32_bf16 v[72:75], v[160:163], v[208:211], v[72:75]
	s_setprio 0
	s_setprio 1
	v_mfma_f32_16x16x32_bf16 v[116:119], v[164:167], v[180:183], v[116:119]
	v_mfma_f32_16x16x32_bf16 v[112:115], v[172:175], v[180:183], v[112:115]
	v_mfma_f32_16x16x32_bf16 v[100:103], v[164:167], v[188:191], v[100:103]
	v_mfma_f32_16x16x32_bf16 v[96:99], v[172:175], v[188:191], v[96:99]
	v_mfma_f32_16x16x32_bf16 v[84:87], v[164:167], v[196:199], v[84:87]
	v_mfma_f32_16x16x32_bf16 v[80:83], v[172:175], v[196:199], v[80:83]
	v_mfma_f32_16x16x32_bf16 v[68:71], v[164:167], v[204:207], v[68:71]
	v_mfma_f32_16x16x32_bf16 v[64:67], v[172:175], v[204:207], v[64:67]
	v_mfma_f32_16x16x32_bf16 v[116:119], v[168:171], v[184:187], v[116:119]
	v_mfma_f32_16x16x32_bf16 v[112:115], v[176:179], v[184:187], v[112:115]
	v_mfma_f32_16x16x32_bf16 v[100:103], v[168:171], v[192:195], v[100:103]
	v_mfma_f32_16x16x32_bf16 v[96:99], v[176:179], v[192:195], v[96:99]
	v_mfma_f32_16x16x32_bf16 v[84:87], v[168:171], v[200:203], v[84:87]
	v_mfma_f32_16x16x32_bf16 v[80:83], v[176:179], v[200:203], v[80:83]
	v_mfma_f32_16x16x32_bf16 v[68:71], v[168:171], v[208:211], v[68:71]
	v_mfma_f32_16x16x32_bf16 v[64:67], v[176:179], v[208:211], v[64:67]
	s_setprio 0
	s_barrier
; #define PG8_STAGE(bufoff, gbase, voff) do { _Pragma("unroll") for (int _i = 0; _i < 2; ++_i) \
;         __builtin_amdgcn_global_load_lds((const unsigned*)((const char*)(gbase) + (voff)[_i]), (PG8_LAS unsigned*)(lds + (bufoff) + ldsw + _i * 8192), 16, 0, 0); } while (0)
; #define PG8_LDA(dst, b, h) do { _Pragma("unroll") for (int m = 0; m < 4; ++m) _Pragma("unroll") for (int k = 0; k < 2; ++k) dst[m][k] = *(const PG8_LAS bf16x8*)(lds + PG8_SA(b, h) + aoff + m * 2048 + k * 1024); } while (0)
; #define PG8_MMA(ai, bj, At, Bt) do { __builtin_amdgcn_s_setprio(1); _Pragma("unroll") for (int m = 0; m < 4; ++m) _Pragma("unroll") for (int n = 0; n < 2; ++n) _Pragma("unroll") for (int k = 0; k < 2; ++k) \
;         acc[ai][bj][m][n] = __builtin_amdgcn_mfma_f32_16x16x32_bf16(Bt[n][k], At[m][k], acc[ai][bj][m][n], 0, 0, 0); __builtin_amdgcn_s_setprio(0); } while (0)
; #define PG8_WAIT_V(n) asm volatile("s_waitcnt vmcnt(" #n ")" ::: "memory")
; #define PG8_WAIT_L(n) asm volatile("s_waitcnt lgkmcnt(" #n ")" ::: "memory")
; #define PG8_BAR __builtin_amdgcn_s_barrier()
; #define PG8_SCHED __builtin_amdgcn_sched_barrier(0)
; template <class Epi, class Sched, bool ALIGN_EPI = false, bool SP2 = false>
; __device__ __forceinline__ void gemm_phase(PG8_LAS unsigned char* lds, const Gemm g, const Sched& S, const Epi& E, const int wid) {
;     ...
;         for (int t = 0; t < nt; t += 2) {
;             const bool last = (t == nt - 2);
;             const char* a1 = cA + (size_t)(t + 1) * kstep;
;             const char* a2 = last ? nA : cA + (size_t)(t + 2) * kstep; const char* b2 = last ? nB : cB + (size_t)(t + 2) * kstep;
;             const char* a3 = a2 + kstep; const char* b3 = b2 + kstep;
;     ...
;             PG8_LDA(At, 1, 1); PG8_STAGE(PG8_SB(1, 0), b3, voffB); PG8_STAGE(PG8_SB(1, 1), b3 + hstep, voffB); PG8_STAGE(PG8_SA(1, 0), a3, voffA);
;             PG8_WAIT_V(8); PG8_WAIT_L(0); PG8_BAR; PG8_MMA(1, 0, At, B0); PG8_MMA(1, 1, At, B1); PG8_BAR; PG8_SCHED;
	s_add_i32 s30, s33, s38
	v_lshl_add_u64 v[212:213], v[212:213], 0, s[18:19]
	s_mov_b32 m0, s30
	ds_read_b128 v[180:183], v151 offset:49152
	ds_read_b128 v[184:187], v151 offset:50176
	ds_read_b128 v[188:191], v151 offset:51200
	ds_read_b128 v[192:195], v151 offset:52224
	ds_read_b128 v[196:199], v151 offset:53248
	ds_read_b128 v[200:203], v151 offset:54272
	ds_read_b128 v[204:207], v151 offset:55296
	ds_read_b128 v[208:211], v151 offset:56320
	global_load_lds_dwordx4 v[212:213], off
	v_lshl_add_u64 v[212:213], v[214:215], 0, s[18:19]
	s_add_i32 m0, s30, 0x2000
	s_add_i32 s30, s67, s38
	global_load_lds_dwordx4 v[212:213], off
	v_lshl_add_u64 v[212:213], v[216:217], 0, s[18:19]
	s_mov_b32 m0, s30
	s_nop 0
	global_load_lds_dwordx4 v[212:213], off
	v_lshl_add_u64 v[212:213], v[218:219], 0, s[18:19]
	s_add_i32 m0, s30, 0x2000
	s_nop 0
	global_load_lds_dwordx4 v[212:213], off
	v_lshl_add_u64 v[212:213], v[220:221], 0, s[18:19]
	s_mov_b32 m0, s52
	s_nop 0
	global_load_lds_dwordx4 v[212:213], off
	v_lshl_add_u64 v[212:213], v[222:223], 0, s[18:19]
	s_mov_b32 m0, s53
	s_nop 0
	global_load_lds_dwordx4 v[212:213], off
	s_waitcnt vmcnt(8)
	s_waitcnt lgkmcnt(0)
	s_barrier
	s_setprio 1
	s_waitcnt lgkmcnt(0)
	v_mfma_f32_16x16x32_bf16 v[60:63], v[142:145], v[180:183], v[60:63]
	v_mfma_f32_16x16x32_bf16 v[56:59], v[156:159], v[180:183], v[56:59]
	v_mfma_f32_16x16x32_bf16 v[44:47], v[142:145], v[188:191], v[44:47]
	v_mfma_f32_16x16x32_bf16 v[40:43], v[156:159], v[188:191], v[40:43]
	v_mfma_f32_16x16x32_bf16 v[28:31], v[142:145], v[196:199], v[28:31]
	v_mfma_f32_16x16x32_bf16 v[24:27], v[156:159], v[196:199], v[24:27]
	v_mfma_f32_16x16x32_bf16 v[12:15], v[142:145], v[204:207], v[12:15]
	v_mfma_f32_16x16x32_bf16 v[8:11], v[156:159], v[204:207], v[8:11]
	v_mfma_f32_16x16x32_bf16 v[60:63], v[152:155], v[184:187], v[60:63]
	v_mfma_f32_16x16x32_bf16 v[56:59], v[160:163], v[184:187], v[56:59]
	v_mfma_f32_16x16x32_bf16 v[44:47], v[152:155], v[192:195], v[44:47]
	v_mfma_f32_16x16x32_bf16 v[40:43], v[160:163], v[192:195], v[40:43]
	v_mfma_f32_16x16x32_bf16 v[28:31], v[152:155], v[200:203], v[28:31]
	v_mfma_f32_16x16x32_bf16 v[24:27], v[160:163], v[200:203], v[24:27]
	v_mfma_f32_16x16x32_bf16 v[12:15], v[152:155], v[208:211], v[12:15]
	v_mfma_f32_16x16x32_bf16 v[8:11], v[160:163], v[208:211], v[8:11]
	s_setprio 0
	s_setprio 1
	v_mfma_f32_16x16x32_bf16 v[52:55], v[164:167], v[180:183], v[52:55]
	v_mfma_f32_16x16x32_bf16 v[48:51], v[172:175], v[180:183], v[48:51]
	v_mfma_f32_16x16x32_bf16 v[36:39], v[164:167], v[188:191], v[36:39]
	v_mfma_f32_16x16x32_bf16 v[32:35], v[172:175], v[188:191], v[32:35]
	v_mfma_f32_16x16x32_bf16 v[20:23], v[164:167], v[196:199], v[20:23]
	v_mfma_f32_16x16x32_bf16 v[16:19], v[172:175], v[196:199], v[16:19]
	v_mfma_f32_16x16x32_bf16 v[4:7], v[164:167], v[204:207], v[4:7]
	v_mfma_f32_16x16x32_bf16 v[0:3], v[172:175], v[204:207], v[0:3]
	v_mfma_f32_16x16x32_bf16 v[52:55], v[168:171], v[184:187], v[52:55]
	v_mfma_f32_16x16x32_bf16 v[48:51], v[176:179], v[184:187], v[48:51]
	v_mfma_f32_16x16x32_bf16 v[36:39], v[168:171], v[192:195], v[36:39]
	v_mfma_f32_16x16x32_bf16 v[32:35], v[176:179], v[192:195], v[32:35]
	v_mfma_f32_16x16x32_bf16 v[20:23], v[168:171], v[200:203], v[20:23]
	v_mfma_f32_16x16x32_bf16 v[16:19], v[176:179], v[200:203], v[16:19]
	v_mfma_f32_16x16x32_bf16 v[4:7], v[168:171], v[208:211], v[4:7]
	v_mfma_f32_16x16x32_bf16 v[0:3], v[176:179], v[208:211], v[0:3]
	s_setprio 0
	s_barrier
	s_add_u32 s28, s28, 0x100
	s_addc_u32 s29, s29, 0
	s_add_u32 s0, s0, 0x100
	s_addc_u32 s1, s1, 0
	s_cmp_ge_i32 s66, s54
	s_mov_b32 s30, s66
	s_cbranch_scc1 .LBB0_1259

; #define PG8_STAGE(bufoff, gbase, voff) do { _Pragma("unroll") for (int _i = 0; _i < 2; ++_i) \
;         __builtin_amdgcn_global_load_lds((const unsigned*)((const char*)(gbase) + (voff)[_i]), (PG8_LAS unsigned*)(lds + (bufoff) + ldsw + _i * 8192), 16, 0, 0); } while (0)
; #define PG8_LDA(dst, b, h) do { _Pragma("unroll") for (int m = 0; m < 4; ++m) _Pragma("unroll") for (int k = 0; k < 2; ++k) dst[m][k] = *(const PG8_LAS bf16x8*)(lds + PG8_SA(b, h) + aoff + m * 2048 + k * 1024); } while (0)
; #define PG8_LDB(dst, b, h) do { _Pragma("unroll") for (int n = 0; n < 2; ++n) _Pragma("unroll") for (int k = 0; k < 2; ++k) dst[n][k] = *(const PG8_LAS bf16x8*)(lds + PG8_SB(b, h) + boff + n * 2048 + k * 1024); } while (0)
; #define PG8_MMA(ai, bj, At, Bt) do { __builtin_amdgcn_s_setprio(1); _Pragma("unroll") for (int m = 0; m < 4; ++m) _Pragma("unroll") for (int n = 0; n < 2; ++n) _Pragma("unroll") for (int k = 0; k < 2; ++k) \
;         acc[ai][bj][m][n] = __builtin_amdgcn_mfma_f32_16x16x32_bf16(Bt[n][k], At[m][k], acc[ai][bj][m][n], 0, 0, 0); __builtin_amdgcn_s_setprio(0); } while (0)
; template <class Epi, class Sched, bool ALIGN_EPI = false, bool SP2 = false>
; __device__ __forceinline__ void gemm_phase(PG8_LAS unsigned char* lds, const Gemm g, const Sched& S, const Epi& E, const int wid) {
;     ...
;         const bool has_next = S.next(ui + 1, nxt);
;         const char* nA = has_next ? (const char*)g.A + (size_t)nxt.pm * tstep : cA; const char* nB = has_next ? (const char*)g.Bt + (size_t)nxt.pn * tstep : cB;
;         for (int t = 0; t < nt; t += 2) {
;             const bool last = (t == nt - 2);
;             const char* a1 = cA + (size_t)(t + 1) * kstep;
;             const char* a2 = last ? nA : cA + (size_t)(t + 2) * kstep; const char* b2 = last ? nB : cB + (size_t)(t + 2) * kstep;
;             const char* a3 = a2 + kstep; const char* b3 = b2 + kstep;
;             if (last && has_next) S.a_ready(nxt);
;             if constexpr (SP2) {
;             PG8_LDB(B0, 0, 0); PG8_LDB(B1, 0, 1); PG8_SCHED; PG8_LDA(At, 0, 0); PG8_STAGE(PG8_SA(1, 1), a1 + hstep, voffA);
;             PG8_WAIT_V(8); PG8_WAIT_L(0); PG8_BAR; PG8_MMA(0, 0, At, B0); PG8_MMA(0, 1, At, B1); PG8_BAR; PG8_SCHED;
;             PG8_LDA(At, 0, 1); PG8_STAGE(PG8_SB(0, 0), b2, voffB); PG8_STAGE(PG8_SB(0, 1), b2 + hstep, voffB); PG8_STAGE(PG8_SA(0, 0), a2, voffA);
.LBB0_1337:
	s_andn2_b64 vcc, exec, s[24:25]
	s_waitcnt lgkmcnt(0)
	s_cbranch_vccnz .Lz_GOUT
	s_add_u32 s4, s36, 0x80
	s_addc_u32 s5, s37, 0
	s_add_u32 s0, s34, 0x100
	s_addc_u32 s1, s35, 0
	s_mov_b32 s34, 0
	ds_read_b128 v[142:145], v149
	ds_read_b128 v[154:157], v149 offset:1024
	ds_read_b128 v[158:161], v149 offset:2048
	ds_read_b128 v[162:165], v149 offset:3072
	ds_read_b128 v[166:169], v150
	ds_read_b128 v[170:173], v150 offset:1024
	ds_read_b128 v[174:177], v150 offset:2048
	ds_read_b128 v[178:181], v150 offset:3072
	s_add_i32 s36, s34, 2
	s_add_u32 s33, s4, 0x80
	s_addc_u32 s35, s5, 0
	s_cmp_eq_u32 s54, s34
	s_cselect_b32 s34, s28, s33
	s_cselect_b32 s35, s29, s35
	s_cselect_b32 s69, s31, s1
	s_cselect_b32 s68, s30, s0
	v_lshl_add_u64 v[214:215], s[4:5], 0, v[136:137]
	s_add_i32 m0, s43, 0xc000
	ds_read_b128 v[182:185], v151
	ds_read_b128 v[186:189], v151 offset:1024
	ds_read_b128 v[190:193], v151 offset:2048
	ds_read_b128 v[194:197], v151 offset:3072
	ds_read_b128 v[198:201], v151 offset:4096
	ds_read_b128 v[202:205], v151 offset:5120
	ds_read_b128 v[206:209], v151 offset:6144
	ds_read_b128 v[210:213], v151 offset:7168
	global_load_lds_dwordx4 v[214:215], off
	v_lshl_add_u64 v[214:215], s[4:5], 0, v[138:139]
	s_add_i32 m0, s43, 0xe000
	s_nop 0
	global_load_lds_dwordx4 v[214:215], off
	s_waitcnt vmcnt(8)
	s_waitcnt lgkmcnt(0)
	s_barrier
	s_setprio 1
	s_waitcnt lgkmcnt(0)
	v_mfma_f32_16x16x32_bf16 v[120:123], v[142:145], v[182:185], 0
	v_mfma_f32_16x16x32_bf16 v[124:127], v[158:161], v[182:185], 0
	v_mfma_f32_16x16x32_bf16 v[108:111], v[142:145], v[190:193], 0
	v_mfma_f32_16x16x32_bf16 v[104:107], v[158:161], v[190:193], 0
	v_mfma_f32_16x16x32_bf16 v[92:95], v[142:145], v[198:201], 0
	v_mfma_f32_16x16x32_bf16 v[88:91], v[158:161], v[198:201], 0
	v_mfma_f32_16x16x32_bf16 v[76:79], v[142:145], v[206:209], 0
	v_mfma_f32_16x16x32_bf16 v[72:75], v[158:161], v[206:209], 0
	v_mfma_f32_16x16x32_bf16 v[120:123], v[154:157], v[186:189], v[120:123]
	v_mfma_f32_16x16x32_bf16 v[124:127], v[162:165], v[186:189], v[124:127]
	v_mfma_f32_16x16x32_bf16 v[108:111], v[154:157], v[194:197], v[108:111]
	v_mfma_f32_16x16x32_bf16 v[104:107], v[162:165], v[194:197], v[104:107]
	v_mfma_f32_16x16x32_bf16 v[92:95], v[154:157], v[202:205], v[92:95]
	v_mfma_f32_16x16x32_bf16 v[88:91], v[162:165], v[202:205], v[88:91]
	v_mfma_f32_16x16x32_bf16 v[76:79], v[154:157], v[210:213], v[76:79]
	v_mfma_f32_16x16x32_bf16 v[72:75], v[162:165], v[210:213], v[72:75]
	s_setprio 0
	s_setprio 1
	v_mfma_f32_16x16x32_bf16 v[116:119], v[166:169], v[182:185], 0
	v_mfma_f32_16x16x32_bf16 v[112:115], v[174:177], v[182:185], 0
	v_mfma_f32_16x16x32_bf16 v[100:103], v[166:169], v[190:193], 0
	v_mfma_f32_16x16x32_bf16 v[96:99], v[174:177], v[190:193], 0
	v_mfma_f32_16x16x32_bf16 v[84:87], v[166:169], v[198:201], 0
	v_mfma_f32_16x16x32_bf16 v[80:83], v[174:177], v[198:201], 0
	v_mfma_f32_16x16x32_bf16 v[68:71], v[166:169], v[206:209], 0
	v_mfma_f32_16x16x32_bf16 v[64:67], v[174:177], v[206:209], 0
	v_mfma_f32_16x16x32_bf16 v[116:119], v[170:173], v[186:189], v[116:119]
	v_mfma_f32_16x16x32_bf16 v[112:115], v[178:181], v[186:189], v[112:115]
	v_mfma_f32_16x16x32_bf16 v[100:103], v[170:173], v[194:197], v[100:103]
	v_mfma_f32_16x16x32_bf16 v[96:99], v[178:181], v[194:197], v[96:99]
	v_mfma_f32_16x16x32_bf16 v[84:87], v[170:173], v[202:205], v[84:87]
	v_mfma_f32_16x16x32_bf16 v[80:83], v[178:181], v[202:205], v[80:83]
	v_mfma_f32_16x16x32_bf16 v[68:71], v[170:173], v[210:213], v[68:71]
	v_mfma_f32_16x16x32_bf16 v[64:67], v[178:181], v[210:213], v[64:67]
	s_setprio 0
	s_barrier
	s_add_i32 s33, s62, s42
	v_lshl_add_u64 v[214:215], s[68:69], 0, v[130:131]
	s_mov_b32 m0, s33
	ds_read_b128 v[182:185], v151 offset:16384
	ds_read_b128 v[186:189], v151 offset:17408
	ds_read_b128 v[190:193], v151 offset:18432
	ds_read_b128 v[194:197], v151 offset:19456
	ds_read_b128 v[198:201], v151 offset:20480
	ds_read_b128 v[202:205], v151 offset:21504
	ds_read_b128 v[206:209], v151 offset:22528
	ds_read_b128 v[210:213], v151 offset:23552
	global_load_lds_dwordx4 v[214:215], off
	s_add_i32 m0, s33, 0x2000
	v_lshl_add_u64 v[216:217], s[68:69], 0, v[134:135]
	s_add_u32 s68, s68, s8
	s_addc_u32 s69, s69, s9
	s_add_i32 s33, s63, s42
	global_load_lds_dwordx4 v[216:217], off
	v_lshl_add_u64 v[218:219], s[68:69], 0, v[130:131]
	s_mov_b32 m0, s33
	v_lshl_add_u64 v[220:221], s[68:69], 0, v[134:135]
	global_load_lds_dwordx4 v[218:219], off
	s_add_i32 m0, s33, 0x2000
	v_lshl_add_u64 v[222:223], s[34:35], 0, v[128:129]
	global_load_lds_dwordx4 v[220:221], off
	s_mov_b32 m0, s43
	v_lshl_add_u64 v[224:225], s[34:35], 0, v[132:133]
	global_load_lds_dwordx4 v[222:223], off
	s_mov_b32 m0, s44
	s_nop 0
	global_load_lds_dwordx4 v[224:225], off
	s_waitcnt vmcnt(8)
	s_waitcnt lgkmcnt(0)
	s_barrier
; #define PG8_STAGE(bufoff, gbase, voff) do { _Pragma("unroll") for (int _i = 0; _i < 2; ++_i) \
;         __builtin_amdgcn_global_load_lds((const unsigned*)((const char*)(gbase) + (voff)[_i]), (PG8_LAS unsigned*)(lds + (bufoff) + ldsw + _i * 8192), 16, 0, 0); } while (0)
; #define PG8_LDA(dst, b, h) do { _Pragma("unroll") for (int m = 0; m < 4; ++m) _Pragma("unroll") for (int k = 0; k < 2; ++k) dst[m][k] = *(const PG8_LAS bf16x8*)(lds + PG8_SA(b, h) + aoff + m * 2048 + k * 1024); } while (0)
; #define PG8_LDB(dst, b, h) do { _Pragma("unroll") for (int n = 0; n < 2; ++n) _Pragma("unroll") for (int k = 0; k < 2; ++k) dst[n][k] = *(const PG8_LAS bf16x8*)(lds + PG8_SB(b, h) + boff + n * 2048 + k * 1024); } while (0)
; #define PG8_MMA(ai, bj, At, Bt) do { __builtin_amdgcn_s_setprio(1); _Pragma("unroll") for (int m = 0; m < 4; ++m) _Pragma("unroll") for (int n = 0; n < 2; ++n) _Pragma("unroll") for (int k = 0; k < 2; ++k) \
;         acc[ai][bj][m][n] = __builtin_amdgcn_mfma_f32_16x16x32_bf16(Bt[n][k], At[m][k], acc[ai][bj][m][n], 0, 0, 0); __builtin_amdgcn_s_setprio(0); } while (0)
; #define PG8_WAIT_V(n) asm volatile("s_waitcnt vmcnt(" #n ")" ::: "memory")
; #define PG8_WAIT_L(n) asm volatile("s_waitcnt lgkmcnt(" #n ")" ::: "memory")
; #define PG8_BAR __builtin_amdgcn_s_barrier()
; #define PG8_SCHED __builtin_amdgcn_sched_barrier(0)
; template <class Epi, class Sched, bool ALIGN_EPI = false, bool SP2 = false>
; __device__ __forceinline__ void gemm_phase(PG8_LAS unsigned char* lds, const Gemm g, const Sched& S, const Epi& E, const int wid) {
;     ...
;             PG8_WAIT_V(8); PG8_WAIT_L(0); PG8_BAR; PG8_MMA(1, 0, At, B0); PG8_MMA(1, 1, At, B1); PG8_BAR; PG8_SCHED;
;             PG8_LDB(B0, 1, 0); PG8_LDB(B1, 1, 1); PG8_SCHED; PG8_LDA(At, 1, 0); PG8_STAGE(PG8_SA(0, 1), a2 + hstep, voffA);
;             PG8_WAIT_V(8); PG8_WAIT_L(0); PG8_BAR; PG8_MMA(0, 0, At, B0); PG8_MMA(0, 1, At, B1); PG8_BAR; PG8_SCHED;
	s_setprio 1
	s_waitcnt lgkmcnt(0)
	v_mfma_f32_16x16x32_bf16 v[60:63], v[142:145], v[182:185], 0
	v_mfma_f32_16x16x32_bf16 v[56:59], v[158:161], v[182:185], 0
	v_mfma_f32_16x16x32_bf16 v[44:47], v[142:145], v[190:193], 0
	v_mfma_f32_16x16x32_bf16 v[40:43], v[158:161], v[190:193], 0
	v_mfma_f32_16x16x32_bf16 v[28:31], v[142:145], v[198:201], 0
	v_mfma_f32_16x16x32_bf16 v[24:27], v[158:161], v[198:201], 0
	v_mfma_f32_16x16x32_bf16 v[12:15], v[142:145], v[206:209], 0
	v_mfma_f32_16x16x32_bf16 v[8:11], v[158:161], v[206:209], 0
	v_mfma_f32_16x16x32_bf16 v[60:63], v[154:157], v[186:189], v[60:63]
	v_mfma_f32_16x16x32_bf16 v[56:59], v[162:165], v[186:189], v[56:59]
	v_mfma_f32_16x16x32_bf16 v[44:47], v[154:157], v[194:197], v[44:47]
	v_mfma_f32_16x16x32_bf16 v[40:43], v[162:165], v[194:197], v[40:43]
	v_mfma_f32_16x16x32_bf16 v[28:31], v[154:157], v[202:205], v[28:31]
	v_mfma_f32_16x16x32_bf16 v[24:27], v[162:165], v[202:205], v[24:27]
	v_mfma_f32_16x16x32_bf16 v[12:15], v[154:157], v[210:213], v[12:15]
	v_mfma_f32_16x16x32_bf16 v[8:11], v[162:165], v[210:213], v[8:11]
	s_setprio 0
	s_setprio 1
	v_mfma_f32_16x16x32_bf16 v[52:55], v[166:169], v[182:185], 0
	v_mfma_f32_16x16x32_bf16 v[48:51], v[174:177], v[182:185], 0
	v_mfma_f32_16x16x32_bf16 v[36:39], v[166:169], v[190:193], 0
	v_mfma_f32_16x16x32_bf16 v[32:35], v[174:177], v[190:193], 0
	v_mfma_f32_16x16x32_bf16 v[20:23], v[166:169], v[198:201], 0
	v_mfma_f32_16x16x32_bf16 v[16:19], v[174:177], v[198:201], 0
	v_mfma_f32_16x16x32_bf16 v[4:7], v[166:169], v[206:209], 0
	v_mfma_f32_16x16x32_bf16 v[0:3], v[174:177], v[206:209], 0
	v_mfma_f32_16x16x32_bf16 v[52:55], v[170:173], v[186:189], v[52:55]
	v_mfma_f32_16x16x32_bf16 v[48:51], v[178:181], v[186:189], v[48:51]
	v_mfma_f32_16x16x32_bf16 v[36:39], v[170:173], v[194:197], v[36:39]
	v_mfma_f32_16x16x32_bf16 v[32:35], v[178:181], v[194:197], v[32:35]
	v_mfma_f32_16x16x32_bf16 v[20:23], v[170:173], v[202:205], v[20:23]
	v_mfma_f32_16x16x32_bf16 v[16:19], v[178:181], v[202:205], v[16:19]
	v_mfma_f32_16x16x32_bf16 v[4:7], v[170:173], v[210:213], v[4:7]
	v_mfma_f32_16x16x32_bf16 v[0:3], v[178:181], v[210:213], v[0:3]
	s_setprio 0
	s_barrier
	s_add_i32 s33, 0, 0x18000
	v_add_u32_e32 v153, s33, v148
	s_add_i32 s37, 0, 0x1c000
	ds_read_b128 v[142:145], v153
	ds_read_b128 v[154:157], v153 offset:1024
	ds_read_b128 v[158:161], v153 offset:2048
	ds_read_b128 v[162:165], v153 offset:3072
	v_add_u32_e32 v153, s37, v148
	ds_read_b128 v[166:169], v153
	ds_read_b128 v[170:173], v153 offset:1024
	ds_read_b128 v[174:177], v153 offset:2048
	ds_read_b128 v[178:181], v153 offset:3072
	s_add_u32 s34, s34, s8
	s_addc_u32 s35, s35, s9
	s_mov_b32 m0, s45
	v_lshl_add_u64 v[226:227], s[34:35], 0, v[128:129]
	ds_read_b128 v[182:185], v151 offset:32768
	ds_read_b128 v[186:189], v151 offset:33792
	ds_read_b128 v[190:193], v151 offset:34816
	ds_read_b128 v[194:197], v151 offset:35840
	ds_read_b128 v[198:201], v151 offset:36864
	ds_read_b128 v[202:205], v151 offset:37888
	ds_read_b128 v[206:209], v151 offset:38912
	ds_read_b128 v[210:213], v151 offset:39936
	global_load_lds_dwordx4 v[226:227], off
	v_lshl_add_u64 v[226:227], s[34:35], 0, v[132:133]
	s_mov_b32 m0, s46
	s_nop 0
	global_load_lds_dwordx4 v[226:227], off
	s_waitcnt vmcnt(8)
	s_waitcnt lgkmcnt(0)
	s_barrier
	s_setprio 1
	s_waitcnt lgkmcnt(0)
	v_mfma_f32_16x16x32_bf16 v[120:123], v[142:145], v[182:185], v[120:123]
	v_mfma_f32_16x16x32_bf16 v[124:127], v[158:161], v[182:185], v[124:127]
	v_mfma_f32_16x16x32_bf16 v[108:111], v[142:145], v[190:193], v[108:111]
	v_mfma_f32_16x16x32_bf16 v[104:107], v[158:161], v[190:193], v[104:107]
	v_mfma_f32_16x16x32_bf16 v[92:95], v[142:145], v[198:201], v[92:95]
	v_mfma_f32_16x16x32_bf16 v[88:91], v[158:161], v[198:201], v[88:91]
	v_mfma_f32_16x16x32_bf16 v[76:79], v[142:145], v[206:209], v[76:79]
	v_mfma_f32_16x16x32_bf16 v[72:75], v[158:161], v[206:209], v[72:75]
	v_mfma_f32_16x16x32_bf16 v[120:123], v[154:157], v[186:189], v[120:123]
	v_mfma_f32_16x16x32_bf16 v[124:127], v[162:165], v[186:189], v[124:127]
	v_mfma_f32_16x16x32_bf16 v[108:111], v[154:157], v[194:197], v[108:111]
	v_mfma_f32_16x16x32_bf16 v[104:107], v[162:165], v[194:197], v[104:107]
	v_mfma_f32_16x16x32_bf16 v[92:95], v[154:157], v[202:205], v[92:95]
	v_mfma_f32_16x16x32_bf16 v[88:91], v[162:165], v[202:205], v[88:91]
	v_mfma_f32_16x16x32_bf16 v[76:79], v[154:157], v[210:213], v[76:79]
	v_mfma_f32_16x16x32_bf16 v[72:75], v[162:165], v[210:213], v[72:75]
	s_setprio 0
	s_setprio 1
	v_mfma_f32_16x16x32_bf16 v[116:119], v[166:169], v[182:185], v[116:119]
	v_mfma_f32_16x16x32_bf16 v[112:115], v[174:177], v[182:185], v[112:115]
	v_mfma_f32_16x16x32_bf16 v[100:103], v[166:169], v[190:193], v[100:103]
	v_mfma_f32_16x16x32_bf16 v[96:99], v[174:177], v[190:193], v[96:99]
	v_mfma_f32_16x16x32_bf16 v[84:87], v[166:169], v[198:201], v[84:87]
	v_mfma_f32_16x16x32_bf16 v[80:83], v[174:177], v[198:201], v[80:83]
	v_mfma_f32_16x16x32_bf16 v[68:71], v[166:169], v[206:209], v[68:71]
	v_mfma_f32_16x16x32_bf16 v[64:67], v[174:177], v[206:209], v[64:67]
	v_mfma_f32_16x16x32_bf16 v[116:119], v[170:173], v[186:189], v[116:119]
	v_mfma_f32_16x16x32_bf16 v[112:115], v[178:181], v[186:189], v[112:115]
	v_mfma_f32_16x16x32_bf16 v[100:103], v[170:173], v[194:197], v[100:103]
	v_mfma_f32_16x16x32_bf16 v[96:99], v[178:181], v[194:197], v[96:99]
	v_mfma_f32_16x16x32_bf16 v[84:87], v[170:173], v[202:205], v[84:87]
	v_mfma_f32_16x16x32_bf16 v[80:83], v[178:181], v[202:205], v[80:83]
	v_mfma_f32_16x16x32_bf16 v[68:71], v[170:173], v[210:213], v[68:71]
	v_mfma_f32_16x16x32_bf16 v[64:67], v[178:181], v[210:213], v[64:67]
	s_setprio 0
	s_barrier
; #define PG8_STAGE(bufoff, gbase, voff) do { _Pragma("unroll") for (int _i = 0; _i < 2; ++_i) \
;         __builtin_amdgcn_global_load_lds((const unsigned*)((const char*)(gbase) + (voff)[_i]), (PG8_LAS unsigned*)(lds + (bufoff) + ldsw + _i * 8192), 16, 0, 0); } while (0)
; #define PG8_LDA(dst, b, h) do { _Pragma("unroll") for (int m = 0; m < 4; ++m) _Pragma("unroll") for (int k = 0; k < 2; ++k) dst[m][k] = *(const PG8_LAS bf16x8*)(lds + PG8_SA(b, h) + aoff + m * 2048 + k * 1024); } while (0)
; #define PG8_MMA(ai, bj, At, Bt) do { __builtin_amdgcn_s_setprio(1); _Pragma("unroll") for (int m = 0; m < 4; ++m) _Pragma("unroll") for (int n = 0; n < 2; ++n) _Pragma("unroll") for (int k = 0; k < 2; ++k) \
;         acc[ai][bj][m][n] = __builtin_amdgcn_mfma_f32_16x16x32_bf16(Bt[n][k], At[m][k], acc[ai][bj][m][n], 0, 0, 0); __builtin_amdgcn_s_setprio(0); } while (0)
; #define PG8_WAIT_V(n) asm volatile("s_waitcnt vmcnt(" #n ")" ::: "memory")
; #define PG8_WAIT_L(n) asm volatile("s_waitcnt lgkmcnt(" #n ")" ::: "memory")
; #define PG8_BAR __builtin_amdgcn_s_barrier()
; #define PG8_SCHED __builtin_amdgcn_sched_barrier(0)
; template <class Epi, class Sched, bool ALIGN_EPI = false, bool SP2 = false>
; __device__ __forceinline__ void gemm_phase(PG8_LAS unsigned char* lds, const Gemm g, const Sched& S, const Epi& E, const int wid) {
;     ...
;         for (int t = 0; t < nt; t += 2) {
;             const bool last = (t == nt - 2);
;             const char* a1 = cA + (size_t)(t + 1) * kstep;
;             const char* a2 = last ? nA : cA + (size_t)(t + 2) * kstep; const char* b2 = last ? nB : cB + (size_t)(t + 2) * kstep;
;             const char* a3 = a2 + kstep; const char* b3 = b2 + kstep;
;     ...
;             PG8_LDA(At, 1, 1); PG8_STAGE(PG8_SB(1, 0), b3, voffB); PG8_STAGE(PG8_SB(1, 1), b3 + hstep, voffB); PG8_STAGE(PG8_SA(1, 0), a3, voffA);
;             PG8_WAIT_V(8); PG8_WAIT_L(0); PG8_BAR; PG8_MMA(1, 0, At, B0); PG8_MMA(1, 1, At, B1); PG8_BAR; PG8_SCHED;
	s_add_i32 s33, s33, s42
	v_lshl_add_u64 v[214:215], v[214:215], 0, s[22:23]
	s_mov_b32 m0, s33
	ds_read_b128 v[182:185], v151 offset:49152
	ds_read_b128 v[186:189], v151 offset:50176
	ds_read_b128 v[190:193], v151 offset:51200
	ds_read_b128 v[194:197], v151 offset:52224
	ds_read_b128 v[198:201], v151 offset:53248
	ds_read_b128 v[202:205], v151 offset:54272
	ds_read_b128 v[206:209], v151 offset:55296
	ds_read_b128 v[210:213], v151 offset:56320
	global_load_lds_dwordx4 v[214:215], off
	v_lshl_add_u64 v[214:215], v[216:217], 0, s[22:23]
	s_add_i32 m0, s33, 0x2000
	s_add_i32 s33, s37, s42
	global_load_lds_dwordx4 v[214:215], off
	v_lshl_add_u64 v[214:215], v[218:219], 0, s[22:23]
	s_mov_b32 m0, s33
	s_nop 0
	global_load_lds_dwordx4 v[214:215], off
	v_lshl_add_u64 v[214:215], v[220:221], 0, s[22:23]
	s_add_i32 m0, s33, 0x2000
	s_nop 0
	global_load_lds_dwordx4 v[214:215], off
	v_lshl_add_u64 v[214:215], v[222:223], 0, s[22:23]
	s_mov_b32 m0, s47
	s_nop 0
	global_load_lds_dwordx4 v[214:215], off
	v_lshl_add_u64 v[214:215], v[224:225], 0, s[22:23]
	s_mov_b32 m0, s49
	s_nop 0
	global_load_lds_dwordx4 v[214:215], off
	s_waitcnt vmcnt(8)
	s_waitcnt lgkmcnt(0)
	s_barrier
	s_setprio 1
	s_waitcnt lgkmcnt(0)
	v_mfma_f32_16x16x32_bf16 v[60:63], v[142:145], v[182:185], v[60:63]
	v_mfma_f32_16x16x32_bf16 v[56:59], v[158:161], v[182:185], v[56:59]
	v_mfma_f32_16x16x32_bf16 v[44:47], v[142:145], v[190:193], v[44:47]
	v_mfma_f32_16x16x32_bf16 v[40:43], v[158:161], v[190:193], v[40:43]
	v_mfma_f32_16x16x32_bf16 v[28:31], v[142:145], v[198:201], v[28:31]
	v_mfma_f32_16x16x32_bf16 v[24:27], v[158:161], v[198:201], v[24:27]
	v_mfma_f32_16x16x32_bf16 v[12:15], v[142:145], v[206:209], v[12:15]
	v_mfma_f32_16x16x32_bf16 v[8:11], v[158:161], v[206:209], v[8:11]
	v_mfma_f32_16x16x32_bf16 v[60:63], v[154:157], v[186:189], v[60:63]
	v_mfma_f32_16x16x32_bf16 v[56:59], v[162:165], v[186:189], v[56:59]
	v_mfma_f32_16x16x32_bf16 v[44:47], v[154:157], v[194:197], v[44:47]
	v_mfma_f32_16x16x32_bf16 v[40:43], v[162:165], v[194:197], v[40:43]
	v_mfma_f32_16x16x32_bf16 v[28:31], v[154:157], v[202:205], v[28:31]
	v_mfma_f32_16x16x32_bf16 v[24:27], v[162:165], v[202:205], v[24:27]
	v_mfma_f32_16x16x32_bf16 v[12:15], v[154:157], v[210:213], v[12:15]
	v_mfma_f32_16x16x32_bf16 v[8:11], v[162:165], v[210:213], v[8:11]
	s_setprio 0
	s_setprio 1
	v_mfma_f32_16x16x32_bf16 v[52:55], v[166:169], v[182:185], v[52:55]
	v_mfma_f32_16x16x32_bf16 v[48:51], v[174:177], v[182:185], v[48:51]
	v_mfma_f32_16x16x32_bf16 v[36:39], v[166:169], v[190:193], v[36:39]
	v_mfma_f32_16x16x32_bf16 v[32:35], v[174:177], v[190:193], v[32:35]
	v_mfma_f32_16x16x32_bf16 v[20:23], v[166:169], v[198:201], v[20:23]
	v_mfma_f32_16x16x32_bf16 v[16:19], v[174:177], v[198:201], v[16:19]
	v_mfma_f32_16x16x32_bf16 v[4:7], v[166:169], v[206:209], v[4:7]
	v_mfma_f32_16x16x32_bf16 v[0:3], v[174:177], v[206:209], v[0:3]
	v_mfma_f32_16x16x32_bf16 v[52:55], v[170:173], v[186:189], v[52:55]
	v_mfma_f32_16x16x32_bf16 v[48:51], v[178:181], v[186:189], v[48:51]
	v_mfma_f32_16x16x32_bf16 v[36:39], v[170:173], v[194:197], v[36:39]
	v_mfma_f32_16x16x32_bf16 v[32:35], v[178:181], v[194:197], v[32:35]
	v_mfma_f32_16x16x32_bf16 v[20:23], v[170:173], v[202:205], v[20:23]
	v_mfma_f32_16x16x32_bf16 v[16:19], v[178:181], v[202:205], v[16:19]
	v_mfma_f32_16x16x32_bf16 v[4:7], v[170:173], v[210:213], v[4:7]
	v_mfma_f32_16x16x32_bf16 v[0:3], v[178:181], v[210:213], v[0:3]
	s_setprio 0
	s_barrier
	s_add_u32 s4, s4, 0x100
	s_addc_u32 s5, s5, 0
	s_add_u32 s0, s0, 0x100
	s_addc_u32 s1, s1, 0
	s_cmp_ge_i32 s36, s51
	s_mov_b32 s34, s36
	s_cbranch_scc1 .LBB0_1340

; template <class Epi, class Sched, bool ALIGN_EPI = false, bool SP2 = false>
; __device__ __forceinline__ void gemm_phase(PG8_LAS unsigned char* lds, const Gemm g, const Sched& S, const Epi& E, const int wid) {
;     ...
;     f32x4 acc[2][2][4][2];
; #pragma unroll
;     for (int a = 0; a < 2; ++a)
; #pragma unroll
;         for (int b = 0; b < 2; ++b)
; #pragma unroll
;             for (int m = 0; m < 4; ++m)
; #pragma unroll
;                 for (int n = 0; n < 2; ++n) acc[a][b][m][n] = (f32x4){0.f, 0.f, 0.f, 0.f};
.Lz_GOUT:
	v_mov_b32_e32 v123, 0
	v_mov_b32_e32 v122, v123
	v_mov_b32_e32 v121, v123
	v_mov_b32_e32 v120, v123
	v_mov_b32_e32 v127, v123
	v_mov_b32_e32 v126, v123
	v_mov_b32_e32 v125, v123
	v_mov_b32_e32 v124, v123
	v_mov_b32_e32 v111, v123
	v_mov_b32_e32 v110, v123
	v_mov_b32_e32 v109, v123
	v_mov_b32_e32 v108, v123
	v_mov_b32_e32 v107, v123
	v_mov_b32_e32 v106, v123
	v_mov_b32_e32 v105, v123
	v_mov_b32_e32 v104, v123
	v_mov_b32_e32 v95, v123
	v_mov_b32_e32 v94, v123
	v_mov_b32_e32 v93, v123
	v_mov_b32_e32 v92, v123
	v_mov_b32_e32 v91, v123
	v_mov_b32_e32 v90, v123
	v_mov_b32_e32 v89, v123
	v_mov_b32_e32 v88, v123
	v_mov_b32_e32 v79, v123
	v_mov_b32_e32 v78, v123
	v_mov_b32_e32 v77, v123
	v_mov_b32_e32 v76, v123
	v_mov_b32_e32 v75, v123
	v_mov_b32_e32 v74, v123
	v_mov_b32_e32 v73, v123
	v_mov_b32_e32 v72, v123
	v_mov_b32_e32 v119, v123
	v_mov_b32_e32 v118, v123
	v_mov_b32_e32 v117, v123
	v_mov_b32_e32 v116, v123
	v_mov_b32_e32 v115, v123
	v_mov_b32_e32 v114, v123
	v_mov_b32_e32 v113, v123
	v_mov_b32_e32 v112, v123
	v_mov_b32_e32 v103, v123
	v_mov_b32_e32 v102, v123
	v_mov_b32_e32 v101, v123
	v_mov_b32_e32 v100, v123
	v_mov_b32_e32 v99, v123
	v_mov_b32_e32 v98, v123
	v_mov_b32_e32 v97, v123
	v_mov_b32_e32 v96, v123
	v_mov_b32_e32 v87, v123
	v_mov_b32_e32 v86, v123
	v_mov_b32_e32 v85, v123
	v_mov_b32_e32 v84, v123
	v_mov_b32_e32 v83, v123
	v_mov_b32_e32 v82, v123
	v_mov_b32_e32 v81, v123
	v_mov_b32_e32 v80, v123
	v_mov_b32_e32 v71, v123
	v_mov_b32_e32 v70, v123
	v_mov_b32_e32 v69, v123
	v_mov_b32_e32 v68, v123
	v_mov_b32_e32 v67, v123
	v_mov_b32_e32 v66, v123
	v_mov_b32_e32 v65, v123
	v_mov_b32_e32 v64, v123
	v_mov_b32_e32 v63, v123
	v_mov_b32_e32 v62, v123
	v_mov_b32_e32 v61, v123
	v_mov_b32_e32 v60, v123
	v_mov_b32_e32 v59, v123
	v_mov_b32_e32 v58, v123
	v_mov_b32_e32 v57, v123
	v_mov_b32_e32 v56, v123
	v_mov_b32_e32 v47, v123
	v_mov_b32_e32 v46, v123
	v_mov_b32_e32 v45, v123
	v_mov_b32_e32 v44, v123
	v_mov_b32_e32 v43, v123
	v_mov_b32_e32 v42, v123
	v_mov_b32_e32 v41, v123
	v_mov_b32_e32 v40, v123
	v_mov_b32_e32 v31, v123
	v_mov_b32_e32 v30, v123
	v_mov_b32_e32 v29, v123
	v_mov_b32_e32 v28, v123
	v_mov_b32_e32 v27, v123
	v_mov_b32_e32 v26, v123
	v_mov_b32_e32 v25, v123
	v_mov_b32_e32 v24, v123
	v_mov_b32_e32 v15, v123
	v_mov_b32_e32 v14, v123
	v_mov_b32_e32 v13, v123
	v_mov_b32_e32 v12, v123
	v_mov_b32_e32 v11, v123
	v_mov_b32_e32 v10, v123
	v_mov_b32_e32 v9, v123
	v_mov_b32_e32 v8, v123
	v_mov_b32_e32 v55, v123
	v_mov_b32_e32 v54, v123
	v_mov_b32_e32 v53, v123
	v_mov_b32_e32 v52, v123
	v_mov_b32_e32 v51, v123
	v_mov_b32_e32 v50, v123
	v_mov_b32_e32 v49, v123
	v_mov_b32_e32 v48, v123
	v_mov_b32_e32 v39, v123
	v_mov_b32_e32 v38, v123
	v_mov_b32_e32 v37, v123
	v_mov_b32_e32 v36, v123
	v_mov_b32_e32 v35, v123
	v_mov_b32_e32 v34, v123
	v_mov_b32_e32 v33, v123
	v_mov_b32_e32 v32, v123
	v_mov_b32_e32 v23, v123
	v_mov_b32_e32 v22, v123
	v_mov_b32_e32 v21, v123
	v_mov_b32_e32 v20, v123
	v_mov_b32_e32 v19, v123
	v_mov_b32_e32 v18, v123
	v_mov_b32_e32 v17, v123
	v_mov_b32_e32 v16, v123
	v_mov_b32_e32 v7, v123
	v_mov_b32_e32 v6, v123
	v_mov_b32_e32 v5, v123
	v_mov_b32_e32 v4, v123
	v_mov_b32_e32 v3, v123
	v_mov_b32_e32 v2, v123
	v_mov_b32_e32 v1, v123
	v_mov_b32_e32 v0, v123
	s_branch .LBB0_1340

; #define PG8_STAGE(bufoff, gbase, voff) do { _Pragma("unroll") for (int _i = 0; _i < 2; ++_i) \
;         __builtin_amdgcn_global_load_lds((const unsigned*)((const char*)(gbase) + (voff)[_i]), (PG8_LAS unsigned*)(lds + (bufoff) + ldsw + _i * 8192), 16, 0, 0); } while (0)
; #define PG8_LDA(dst, b, h) do { _Pragma("unroll") for (int m = 0; m < 4; ++m) _Pragma("unroll") for (int k = 0; k < 2; ++k) dst[m][k] = *(const PG8_LAS bf16x8*)(lds + PG8_SA(b, h) + aoff + m * 2048 + k * 1024); } while (0)
; #define PG8_LDB(dst, b, h) do { _Pragma("unroll") for (int n = 0; n < 2; ++n) _Pragma("unroll") for (int k = 0; k < 2; ++k) dst[n][k] = *(const PG8_LAS bf16x8*)(lds + PG8_SB(b, h) + boff + n * 2048 + k * 1024); } while (0)
; #define PG8_MMA(ai, bj, At, Bt) do { __builtin_amdgcn_s_setprio(1); _Pragma("unroll") for (int m = 0; m < 4; ++m) _Pragma("unroll") for (int n = 0; n < 2; ++n) _Pragma("unroll") for (int k = 0; k < 2; ++k) \
;         acc[ai][bj][m][n] = __builtin_amdgcn_mfma_f32_16x16x32_bf16(Bt[n][k], At[m][k], acc[ai][bj][m][n], 0, 0, 0); __builtin_amdgcn_s_setprio(0); } while (0)
; template <class Epi, class Sched, bool ALIGN_EPI = false, bool SP2 = false>
; __device__ __forceinline__ void gemm_phase(PG8_LAS unsigned char* lds, const Gemm g, const Sched& S, const Epi& E, const int wid) {
;     ...
;         const bool has_next = S.next(ui + 1, nxt);
;         const char* nA = has_next ? (const char*)g.A + (size_t)nxt.pm * tstep : cA; const char* nB = has_next ? (const char*)g.Bt + (size_t)nxt.pn * tstep : cB;
;         for (int t = 0; t < nt; t += 2) {
;             const bool last = (t == nt - 2);
;             const char* a1 = cA + (size_t)(t + 1) * kstep;
;             const char* a2 = last ? nA : cA + (size_t)(t + 2) * kstep; const char* b2 = last ? nB : cB + (size_t)(t + 2) * kstep;
;             const char* a3 = a2 + kstep; const char* b3 = b2 + kstep;
;             if (last && has_next) S.a_ready(nxt);
;             if constexpr (SP2) {
;             PG8_LDB(B0, 0, 0); PG8_LDB(B1, 0, 1); PG8_SCHED; PG8_LDA(At, 0, 0); PG8_STAGE(PG8_SA(1, 1), a1 + hstep, voffA);
;             PG8_WAIT_V(8); PG8_WAIT_L(0); PG8_BAR; PG8_MMA(0, 0, At, B0); PG8_MMA(0, 1, At, B1); PG8_BAR; PG8_SCHED;
;             PG8_LDA(At, 0, 1); PG8_STAGE(PG8_SB(0, 0), b2, voffB); PG8_STAGE(PG8_SB(0, 1), b2 + hstep, voffB); PG8_STAGE(PG8_SA(0, 0), a2, voffA);
.LBB0_1493:
	s_andn2_b64 vcc, exec, s[22:23]
	s_cbranch_vccnz .Lz_FFN1
	s_add_u32 s4, s8, 0x80
	s_addc_u32 s5, s9, 0
	s_add_u32 s0, s6, 0x100
	s_addc_u32 s1, s7, 0
	s_mov_b32 s6, 0
	ds_read_b128 v[142:145], v149
	ds_read_b128 v[152:155], v149 offset:1024
	ds_read_b128 v[156:159], v149 offset:2048
	ds_read_b128 v[160:163], v149 offset:3072
	ds_read_b128 v[164:167], v150
	ds_read_b128 v[168:171], v150 offset:1024
	ds_read_b128 v[172:175], v150 offset:2048
	ds_read_b128 v[176:179], v150 offset:3072
	s_add_i32 s8, s6, 2
	s_add_u32 s9, s4, 0x80
	s_addc_u32 s7, s5, 0
	s_cmp_eq_u32 s55, s6
	s_cselect_b32 s6, s26, s9
	s_cselect_b32 s7, s27, s7
	s_cselect_b32 s65, s29, s1
	s_cselect_b32 s64, s28, s0
	v_lshl_add_u64 v[212:213], s[4:5], 0, v[136:137]
	s_add_i32 m0, s44, 0xc000
	ds_read_b128 v[180:183], v151
	ds_read_b128 v[184:187], v151 offset:1024
	ds_read_b128 v[188:191], v151 offset:2048
	ds_read_b128 v[192:195], v151 offset:3072
	ds_read_b128 v[196:199], v151 offset:4096
	ds_read_b128 v[200:203], v151 offset:5120
	ds_read_b128 v[204:207], v151 offset:6144
	ds_read_b128 v[208:211], v151 offset:7168
	global_load_lds_dwordx4 v[212:213], off
	v_lshl_add_u64 v[212:213], s[4:5], 0, v[138:139]
	s_add_i32 m0, s44, 0xe000
	s_nop 0
	global_load_lds_dwordx4 v[212:213], off
	s_waitcnt vmcnt(8)
	s_waitcnt lgkmcnt(0)
	s_barrier
	s_setprio 1
	s_waitcnt lgkmcnt(0)
	v_mfma_f32_16x16x32_bf16 v[120:123], v[142:145], v[180:183], 0
	v_mfma_f32_16x16x32_bf16 v[112:115], v[156:159], v[180:183], 0
	v_mfma_f32_16x16x32_bf16 v[104:107], v[142:145], v[188:191], 0
	v_mfma_f32_16x16x32_bf16 v[96:99], v[156:159], v[188:191], 0
	v_mfma_f32_16x16x32_bf16 v[88:91], v[142:145], v[196:199], 0
	v_mfma_f32_16x16x32_bf16 v[80:83], v[156:159], v[196:199], 0
	v_mfma_f32_16x16x32_bf16 v[72:75], v[142:145], v[204:207], 0
	v_mfma_f32_16x16x32_bf16 v[64:67], v[156:159], v[204:207], 0
	v_mfma_f32_16x16x32_bf16 v[120:123], v[152:155], v[184:187], v[120:123]
	v_mfma_f32_16x16x32_bf16 v[112:115], v[160:163], v[184:187], v[112:115]
	v_mfma_f32_16x16x32_bf16 v[104:107], v[152:155], v[192:195], v[104:107]
	v_mfma_f32_16x16x32_bf16 v[96:99], v[160:163], v[192:195], v[96:99]
	v_mfma_f32_16x16x32_bf16 v[88:91], v[152:155], v[200:203], v[88:91]
	v_mfma_f32_16x16x32_bf16 v[80:83], v[160:163], v[200:203], v[80:83]
	v_mfma_f32_16x16x32_bf16 v[72:75], v[152:155], v[208:211], v[72:75]
	v_mfma_f32_16x16x32_bf16 v[64:67], v[160:163], v[208:211], v[64:67]
	s_setprio 0
	s_setprio 1
	v_mfma_f32_16x16x32_bf16 v[124:127], v[164:167], v[180:183], 0
	v_mfma_f32_16x16x32_bf16 v[116:119], v[172:175], v[180:183], 0
	v_mfma_f32_16x16x32_bf16 v[108:111], v[164:167], v[188:191], 0
	v_mfma_f32_16x16x32_bf16 v[100:103], v[172:175], v[188:191], 0
	v_mfma_f32_16x16x32_bf16 v[92:95], v[164:167], v[196:199], 0
	v_mfma_f32_16x16x32_bf16 v[84:87], v[172:175], v[196:199], 0
	v_mfma_f32_16x16x32_bf16 v[76:79], v[164:167], v[204:207], 0
	v_mfma_f32_16x16x32_bf16 v[68:71], v[172:175], v[204:207], 0
	v_mfma_f32_16x16x32_bf16 v[124:127], v[168:171], v[184:187], v[124:127]
	v_mfma_f32_16x16x32_bf16 v[116:119], v[176:179], v[184:187], v[116:119]
	v_mfma_f32_16x16x32_bf16 v[108:111], v[168:171], v[192:195], v[108:111]
	v_mfma_f32_16x16x32_bf16 v[100:103], v[176:179], v[192:195], v[100:103]
	v_mfma_f32_16x16x32_bf16 v[92:95], v[168:171], v[200:203], v[92:95]
	v_mfma_f32_16x16x32_bf16 v[84:87], v[176:179], v[200:203], v[84:87]
	v_mfma_f32_16x16x32_bf16 v[76:79], v[168:171], v[208:211], v[76:79]
	v_mfma_f32_16x16x32_bf16 v[68:71], v[176:179], v[208:211], v[68:71]
	s_setprio 0
	s_barrier
	s_add_i32 s9, s57, s36
	v_lshl_add_u64 v[212:213], s[64:65], 0, v[132:133]
	s_mov_b32 m0, s9
	ds_read_b128 v[180:183], v151 offset:16384
	ds_read_b128 v[184:187], v151 offset:17408
	ds_read_b128 v[188:191], v151 offset:18432
	ds_read_b128 v[192:195], v151 offset:19456
	ds_read_b128 v[196:199], v151 offset:20480
	ds_read_b128 v[200:203], v151 offset:21504
	ds_read_b128 v[204:207], v151 offset:22528
	ds_read_b128 v[208:211], v151 offset:23552
	global_load_lds_dwordx4 v[212:213], off
	s_add_i32 m0, s9, 0x2000
	v_lshl_add_u64 v[214:215], s[64:65], 0, v[128:129]
	s_add_u32 s64, s64, s12
	s_addc_u32 s65, s65, s13
	s_add_i32 s9, s58, s36
	global_load_lds_dwordx4 v[214:215], off
	v_lshl_add_u64 v[216:217], s[64:65], 0, v[132:133]
	s_mov_b32 m0, s9
	v_lshl_add_u64 v[218:219], s[64:65], 0, v[128:129]
	global_load_lds_dwordx4 v[216:217], off
	s_add_i32 m0, s9, 0x2000
	v_lshl_add_u64 v[220:221], s[6:7], 0, v[134:135]
	global_load_lds_dwordx4 v[218:219], off
	s_mov_b32 m0, s44
	v_lshl_add_u64 v[222:223], s[6:7], 0, v[130:131]
	global_load_lds_dwordx4 v[220:221], off
	s_mov_b32 m0, s45
	s_nop 0
	global_load_lds_dwordx4 v[222:223], off
	s_waitcnt vmcnt(8)
	s_waitcnt lgkmcnt(0)
	s_barrier
; #define PG8_STAGE(bufoff, gbase, voff) do { _Pragma("unroll") for (int _i = 0; _i < 2; ++_i) \
;         __builtin_amdgcn_global_load_lds((const unsigned*)((const char*)(gbase) + (voff)[_i]), (PG8_LAS unsigned*)(lds + (bufoff) + ldsw + _i * 8192), 16, 0, 0); } while (0)
; #define PG8_LDA(dst, b, h) do { _Pragma("unroll") for (int m = 0; m < 4; ++m) _Pragma("unroll") for (int k = 0; k < 2; ++k) dst[m][k] = *(const PG8_LAS bf16x8*)(lds + PG8_SA(b, h) + aoff + m * 2048 + k * 1024); } while (0)
; #define PG8_LDB(dst, b, h) do { _Pragma("unroll") for (int n = 0; n < 2; ++n) _Pragma("unroll") for (int k = 0; k < 2; ++k) dst[n][k] = *(const PG8_LAS bf16x8*)(lds + PG8_SB(b, h) + boff + n * 2048 + k * 1024); } while (0)
; #define PG8_MMA(ai, bj, At, Bt) do { __builtin_amdgcn_s_setprio(1); _Pragma("unroll") for (int m = 0; m < 4; ++m) _Pragma("unroll") for (int n = 0; n < 2; ++n) _Pragma("unroll") for (int k = 0; k < 2; ++k) \
;         acc[ai][bj][m][n] = __builtin_amdgcn_mfma_f32_16x16x32_bf16(Bt[n][k], At[m][k], acc[ai][bj][m][n], 0, 0, 0); __builtin_amdgcn_s_setprio(0); } while (0)
; #define PG8_WAIT_V(n) asm volatile("s_waitcnt vmcnt(" #n ")" ::: "memory")
; #define PG8_WAIT_L(n) asm volatile("s_waitcnt lgkmcnt(" #n ")" ::: "memory")
; #define PG8_BAR __builtin_amdgcn_s_barrier()
; #define PG8_SCHED __builtin_amdgcn_sched_barrier(0)
; template <class Epi, class Sched, bool ALIGN_EPI = false, bool SP2 = false>
; __device__ __forceinline__ void gemm_phase(PG8_LAS unsigned char* lds, const Gemm g, const Sched& S, const Epi& E, const int wid) {
;     ...
;             PG8_WAIT_V(8); PG8_WAIT_L(0); PG8_BAR; PG8_MMA(1, 0, At, B0); PG8_MMA(1, 1, At, B1); PG8_BAR; PG8_SCHED;
;             PG8_LDB(B0, 1, 0); PG8_LDB(B1, 1, 1); PG8_SCHED; PG8_LDA(At, 1, 0); PG8_STAGE(PG8_SA(0, 1), a2 + hstep, voffA);
;             PG8_WAIT_V(8); PG8_WAIT_L(0); PG8_BAR; PG8_MMA(0, 0, At, B0); PG8_MMA(0, 1, At, B1); PG8_BAR; PG8_SCHED;
	s_setprio 1
	s_waitcnt lgkmcnt(0)
	v_mfma_f32_16x16x32_bf16 v[56:59], v[142:145], v[180:183], 0
	v_mfma_f32_16x16x32_bf16 v[48:51], v[156:159], v[180:183], 0
	v_mfma_f32_16x16x32_bf16 v[40:43], v[142:145], v[188:191], 0
	v_mfma_f32_16x16x32_bf16 v[32:35], v[156:159], v[188:191], 0
	v_mfma_f32_16x16x32_bf16 v[24:27], v[142:145], v[196:199], 0
	v_mfma_f32_16x16x32_bf16 v[16:19], v[156:159], v[196:199], 0
	v_mfma_f32_16x16x32_bf16 v[8:11], v[142:145], v[204:207], 0
	v_mfma_f32_16x16x32_bf16 v[4:7], v[156:159], v[204:207], 0
	v_mfma_f32_16x16x32_bf16 v[56:59], v[152:155], v[184:187], v[56:59]
	v_mfma_f32_16x16x32_bf16 v[48:51], v[160:163], v[184:187], v[48:51]
	v_mfma_f32_16x16x32_bf16 v[40:43], v[152:155], v[192:195], v[40:43]
	v_mfma_f32_16x16x32_bf16 v[32:35], v[160:163], v[192:195], v[32:35]
	v_mfma_f32_16x16x32_bf16 v[24:27], v[152:155], v[200:203], v[24:27]
	v_mfma_f32_16x16x32_bf16 v[16:19], v[160:163], v[200:203], v[16:19]
	v_mfma_f32_16x16x32_bf16 v[8:11], v[152:155], v[208:211], v[8:11]
	v_mfma_f32_16x16x32_bf16 v[4:7], v[160:163], v[208:211], v[4:7]
	s_setprio 0
	s_setprio 1
	v_mfma_f32_16x16x32_bf16 v[60:63], v[164:167], v[180:183], 0
	v_mfma_f32_16x16x32_bf16 v[52:55], v[172:175], v[180:183], 0
	v_mfma_f32_16x16x32_bf16 v[44:47], v[164:167], v[188:191], 0
	v_mfma_f32_16x16x32_bf16 v[36:39], v[172:175], v[188:191], 0
	v_mfma_f32_16x16x32_bf16 v[28:31], v[164:167], v[196:199], 0
	v_mfma_f32_16x16x32_bf16 v[20:23], v[172:175], v[196:199], 0
	v_mfma_f32_16x16x32_bf16 v[12:15], v[164:167], v[204:207], 0
	v_mfma_f32_16x16x32_bf16 v[0:3], v[172:175], v[204:207], 0
	v_mfma_f32_16x16x32_bf16 v[60:63], v[168:171], v[184:187], v[60:63]
	v_mfma_f32_16x16x32_bf16 v[52:55], v[176:179], v[184:187], v[52:55]
	v_mfma_f32_16x16x32_bf16 v[44:47], v[168:171], v[192:195], v[44:47]
	v_mfma_f32_16x16x32_bf16 v[36:39], v[176:179], v[192:195], v[36:39]
	v_mfma_f32_16x16x32_bf16 v[28:31], v[168:171], v[200:203], v[28:31]
	v_mfma_f32_16x16x32_bf16 v[20:23], v[176:179], v[200:203], v[20:23]
	v_mfma_f32_16x16x32_bf16 v[12:15], v[168:171], v[208:211], v[12:15]
	v_mfma_f32_16x16x32_bf16 v[0:3], v[176:179], v[208:211], v[0:3]
	s_setprio 0
	s_barrier
	s_add_i32 s9, 0, 0x18000
	s_add_i32 s33, 0, 0x1c000
	v_add_u32_e32 v160, s9, v148
	v_add_u32_e32 v176, s33, v148
	ds_read_b128 v[142:145], v160
	ds_read_b128 v[152:155], v160 offset:1024
	ds_read_b128 v[156:159], v160 offset:2048
	ds_read_b128 v[160:163], v160 offset:3072
	ds_read_b128 v[164:167], v176
	ds_read_b128 v[168:171], v176 offset:1024
	ds_read_b128 v[172:175], v176 offset:2048
	ds_read_b128 v[176:179], v176 offset:3072
	s_add_u32 s6, s6, s12
	s_addc_u32 s7, s7, s13
	s_mov_b32 m0, s46
	v_lshl_add_u64 v[224:225], s[6:7], 0, v[134:135]
	ds_read_b128 v[180:183], v151 offset:32768
	ds_read_b128 v[184:187], v151 offset:33792
	ds_read_b128 v[188:191], v151 offset:34816
	ds_read_b128 v[192:195], v151 offset:35840
	ds_read_b128 v[196:199], v151 offset:36864
	ds_read_b128 v[200:203], v151 offset:37888
	ds_read_b128 v[204:207], v151 offset:38912
	ds_read_b128 v[208:211], v151 offset:39936
	global_load_lds_dwordx4 v[224:225], off
	v_lshl_add_u64 v[224:225], s[6:7], 0, v[130:131]
	s_mov_b32 m0, s47
	s_nop 0
	global_load_lds_dwordx4 v[224:225], off
	s_waitcnt vmcnt(8)
	s_waitcnt lgkmcnt(0)
	s_barrier
	s_setprio 1
	s_waitcnt lgkmcnt(0)
	v_mfma_f32_16x16x32_bf16 v[120:123], v[142:145], v[180:183], v[120:123]
	v_mfma_f32_16x16x32_bf16 v[112:115], v[156:159], v[180:183], v[112:115]
	v_mfma_f32_16x16x32_bf16 v[104:107], v[142:145], v[188:191], v[104:107]
	v_mfma_f32_16x16x32_bf16 v[96:99], v[156:159], v[188:191], v[96:99]
	v_mfma_f32_16x16x32_bf16 v[88:91], v[142:145], v[196:199], v[88:91]
	v_mfma_f32_16x16x32_bf16 v[80:83], v[156:159], v[196:199], v[80:83]
	v_mfma_f32_16x16x32_bf16 v[72:75], v[142:145], v[204:207], v[72:75]
	v_mfma_f32_16x16x32_bf16 v[64:67], v[156:159], v[204:207], v[64:67]
	v_mfma_f32_16x16x32_bf16 v[120:123], v[152:155], v[184:187], v[120:123]
	v_mfma_f32_16x16x32_bf16 v[112:115], v[160:163], v[184:187], v[112:115]
	v_mfma_f32_16x16x32_bf16 v[104:107], v[152:155], v[192:195], v[104:107]
	v_mfma_f32_16x16x32_bf16 v[96:99], v[160:163], v[192:195], v[96:99]
	v_mfma_f32_16x16x32_bf16 v[88:91], v[152:155], v[200:203], v[88:91]
	v_mfma_f32_16x16x32_bf16 v[80:83], v[160:163], v[200:203], v[80:83]
	v_mfma_f32_16x16x32_bf16 v[72:75], v[152:155], v[208:211], v[72:75]
	v_mfma_f32_16x16x32_bf16 v[64:67], v[160:163], v[208:211], v[64:67]
	s_setprio 0
	s_setprio 1
	v_mfma_f32_16x16x32_bf16 v[124:127], v[164:167], v[180:183], v[124:127]
	v_mfma_f32_16x16x32_bf16 v[116:119], v[172:175], v[180:183], v[116:119]
	v_mfma_f32_16x16x32_bf16 v[108:111], v[164:167], v[188:191], v[108:111]
	v_mfma_f32_16x16x32_bf16 v[100:103], v[172:175], v[188:191], v[100:103]
	v_mfma_f32_16x16x32_bf16 v[92:95], v[164:167], v[196:199], v[92:95]
	v_mfma_f32_16x16x32_bf16 v[84:87], v[172:175], v[196:199], v[84:87]
	v_mfma_f32_16x16x32_bf16 v[76:79], v[164:167], v[204:207], v[76:79]
	v_mfma_f32_16x16x32_bf16 v[68:71], v[172:175], v[204:207], v[68:71]
	v_mfma_f32_16x16x32_bf16 v[124:127], v[168:171], v[184:187], v[124:127]
	v_mfma_f32_16x16x32_bf16 v[116:119], v[176:179], v[184:187], v[116:119]
	v_mfma_f32_16x16x32_bf16 v[108:111], v[168:171], v[192:195], v[108:111]
	v_mfma_f32_16x16x32_bf16 v[100:103], v[176:179], v[192:195], v[100:103]
	v_mfma_f32_16x16x32_bf16 v[92:95], v[168:171], v[200:203], v[92:95]
	v_mfma_f32_16x16x32_bf16 v[84:87], v[176:179], v[200:203], v[84:87]
	v_mfma_f32_16x16x32_bf16 v[76:79], v[168:171], v[208:211], v[76:79]
	v_mfma_f32_16x16x32_bf16 v[68:71], v[176:179], v[208:211], v[68:71]
	s_setprio 0
	s_barrier
; #define PG8_STAGE(bufoff, gbase, voff) do { _Pragma("unroll") for (int _i = 0; _i < 2; ++_i) \
;         __builtin_amdgcn_global_load_lds((const unsigned*)((const char*)(gbase) + (voff)[_i]), (PG8_LAS unsigned*)(lds + (bufoff) + ldsw + _i * 8192), 16, 0, 0); } while (0)
; #define PG8_LDA(dst, b, h) do { _Pragma("unroll") for (int m = 0; m < 4; ++m) _Pragma("unroll") for (int k = 0; k < 2; ++k) dst[m][k] = *(const PG8_LAS bf16x8*)(lds + PG8_SA(b, h) + aoff + m * 2048 + k * 1024); } while (0)
; #define PG8_MMA(ai, bj, At, Bt) do { __builtin_amdgcn_s_setprio(1); _Pragma("unroll") for (int m = 0; m < 4; ++m) _Pragma("unroll") for (int n = 0; n < 2; ++n) _Pragma("unroll") for (int k = 0; k < 2; ++k) \
;         acc[ai][bj][m][n] = __builtin_amdgcn_mfma_f32_16x16x32_bf16(Bt[n][k], At[m][k], acc[ai][bj][m][n], 0, 0, 0); __builtin_amdgcn_s_setprio(0); } while (0)
; #define PG8_WAIT_V(n) asm volatile("s_waitcnt vmcnt(" #n ")" ::: "memory")
; #define PG8_WAIT_L(n) asm volatile("s_waitcnt lgkmcnt(" #n ")" ::: "memory")
; #define PG8_BAR __builtin_amdgcn_s_barrier()
; #define PG8_SCHED __builtin_amdgcn_sched_barrier(0)
; template <class Epi, class Sched, bool ALIGN_EPI = false, bool SP2 = false>
; __device__ __forceinline__ void gemm_phase(PG8_LAS unsigned char* lds, const Gemm g, const Sched& S, const Epi& E, const int wid) {
;     ...
;         for (int t = 0; t < nt; t += 2) {
;             const bool last = (t == nt - 2);
;             const char* a1 = cA + (size_t)(t + 1) * kstep;
;             const char* a2 = last ? nA : cA + (size_t)(t + 2) * kstep; const char* b2 = last ? nB : cB + (size_t)(t + 2) * kstep;
;             const char* a3 = a2 + kstep; const char* b3 = b2 + kstep;
;     ...
;             PG8_LDA(At, 1, 1); PG8_STAGE(PG8_SB(1, 0), b3, voffB); PG8_STAGE(PG8_SB(1, 1), b3 + hstep, voffB); PG8_STAGE(PG8_SA(1, 0), a3, voffA);
;             PG8_WAIT_V(8); PG8_WAIT_L(0); PG8_BAR; PG8_MMA(1, 0, At, B0); PG8_MMA(1, 1, At, B1); PG8_BAR; PG8_SCHED;
	s_add_i32 s6, s9, s36
	v_lshl_add_u64 v[212:213], v[212:213], 0, s[20:21]
	s_mov_b32 m0, s6
	ds_read_b128 v[180:183], v151 offset:49152
	ds_read_b128 v[184:187], v151 offset:50176
	ds_read_b128 v[188:191], v151 offset:51200
	ds_read_b128 v[192:195], v151 offset:52224
	ds_read_b128 v[196:199], v151 offset:53248
	ds_read_b128 v[200:203], v151 offset:54272
	ds_read_b128 v[204:207], v151 offset:55296
	ds_read_b128 v[208:211], v151 offset:56320
	global_load_lds_dwordx4 v[212:213], off
	v_lshl_add_u64 v[212:213], v[214:215], 0, s[20:21]
	s_add_i32 m0, s6, 0x2000
	s_add_i32 s6, s33, s36
	global_load_lds_dwordx4 v[212:213], off
	v_lshl_add_u64 v[212:213], v[216:217], 0, s[20:21]
	s_mov_b32 m0, s6
	s_nop 0
	global_load_lds_dwordx4 v[212:213], off
	v_lshl_add_u64 v[212:213], v[218:219], 0, s[20:21]
	s_add_i32 m0, s6, 0x2000
	s_nop 0
	global_load_lds_dwordx4 v[212:213], off
	v_lshl_add_u64 v[212:213], v[220:221], 0, s[20:21]
	s_mov_b32 m0, s50
	s_nop 0
	global_load_lds_dwordx4 v[212:213], off
	v_lshl_add_u64 v[212:213], v[222:223], 0, s[20:21]
	s_mov_b32 m0, s51
	s_nop 0
	global_load_lds_dwordx4 v[212:213], off
	s_waitcnt vmcnt(8)
	s_waitcnt lgkmcnt(0)
	s_barrier
	s_setprio 1
	s_waitcnt lgkmcnt(0)
	v_mfma_f32_16x16x32_bf16 v[56:59], v[142:145], v[180:183], v[56:59]
	v_mfma_f32_16x16x32_bf16 v[48:51], v[156:159], v[180:183], v[48:51]
	v_mfma_f32_16x16x32_bf16 v[40:43], v[142:145], v[188:191], v[40:43]
	v_mfma_f32_16x16x32_bf16 v[32:35], v[156:159], v[188:191], v[32:35]
	v_mfma_f32_16x16x32_bf16 v[24:27], v[142:145], v[196:199], v[24:27]
	v_mfma_f32_16x16x32_bf16 v[16:19], v[156:159], v[196:199], v[16:19]
	v_mfma_f32_16x16x32_bf16 v[8:11], v[142:145], v[204:207], v[8:11]
	v_mfma_f32_16x16x32_bf16 v[4:7], v[156:159], v[204:207], v[4:7]
	v_mfma_f32_16x16x32_bf16 v[56:59], v[152:155], v[184:187], v[56:59]
	v_mfma_f32_16x16x32_bf16 v[48:51], v[160:163], v[184:187], v[48:51]
	v_mfma_f32_16x16x32_bf16 v[40:43], v[152:155], v[192:195], v[40:43]
	v_mfma_f32_16x16x32_bf16 v[32:35], v[160:163], v[192:195], v[32:35]
	v_mfma_f32_16x16x32_bf16 v[24:27], v[152:155], v[200:203], v[24:27]
	v_mfma_f32_16x16x32_bf16 v[16:19], v[160:163], v[200:203], v[16:19]
	v_mfma_f32_16x16x32_bf16 v[8:11], v[152:155], v[208:211], v[8:11]
	v_mfma_f32_16x16x32_bf16 v[4:7], v[160:163], v[208:211], v[4:7]
	s_setprio 0
	s_setprio 1
	v_mfma_f32_16x16x32_bf16 v[60:63], v[164:167], v[180:183], v[60:63]
	v_mfma_f32_16x16x32_bf16 v[52:55], v[172:175], v[180:183], v[52:55]
	v_mfma_f32_16x16x32_bf16 v[44:47], v[164:167], v[188:191], v[44:47]
	v_mfma_f32_16x16x32_bf16 v[36:39], v[172:175], v[188:191], v[36:39]
	v_mfma_f32_16x16x32_bf16 v[28:31], v[164:167], v[196:199], v[28:31]
	v_mfma_f32_16x16x32_bf16 v[20:23], v[172:175], v[196:199], v[20:23]
	v_mfma_f32_16x16x32_bf16 v[12:15], v[164:167], v[204:207], v[12:15]
	v_mfma_f32_16x16x32_bf16 v[0:3], v[172:175], v[204:207], v[0:3]
	v_mfma_f32_16x16x32_bf16 v[60:63], v[168:171], v[184:187], v[60:63]
	v_mfma_f32_16x16x32_bf16 v[52:55], v[176:179], v[184:187], v[52:55]
	v_mfma_f32_16x16x32_bf16 v[44:47], v[168:171], v[192:195], v[44:47]
	v_mfma_f32_16x16x32_bf16 v[36:39], v[176:179], v[192:195], v[36:39]
	v_mfma_f32_16x16x32_bf16 v[28:31], v[168:171], v[200:203], v[28:31]
	v_mfma_f32_16x16x32_bf16 v[20:23], v[176:179], v[200:203], v[20:23]
	v_mfma_f32_16x16x32_bf16 v[12:15], v[168:171], v[208:211], v[12:15]
	v_mfma_f32_16x16x32_bf16 v[0:3], v[176:179], v[208:211], v[0:3]
	s_setprio 0
	s_barrier
	s_add_u32 s4, s4, 0x100
	s_addc_u32 s5, s5, 0
	s_add_u32 s0, s0, 0x100
	s_addc_u32 s1, s1, 0
	s_cmp_ge_i32 s8, s52
	s_mov_b32 s6, s8
	s_cbranch_scc1 .LBB0_1496

; template <class Epi, class Sched, bool ALIGN_EPI = false, bool SP2 = false>
; __device__ __forceinline__ void gemm_phase(PG8_LAS unsigned char* lds, const Gemm g, const Sched& S, const Epi& E, const int wid) {
;     ...
;     f32x4 acc[2][2][4][2];
; #pragma unroll
;     for (int a = 0; a < 2; ++a)
; #pragma unroll
;         for (int b = 0; b < 2; ++b)
; #pragma unroll
;             for (int m = 0; m < 4; ++m)
; #pragma unroll
;                 for (int n = 0; n < 2; ++n) acc[a][b][m][n] = (f32x4){0.f, 0.f, 0.f, 0.f};
.Lz_FFN1:
	v_mov_b32_e32 v123, 0
	v_mov_b32_e32 v122, v123
	v_mov_b32_e32 v121, v123
	v_mov_b32_e32 v120, v123
	v_mov_b32_e32 v115, v123
	v_mov_b32_e32 v114, v123
	v_mov_b32_e32 v113, v123
	v_mov_b32_e32 v112, v123
	v_mov_b32_e32 v107, v123
	v_mov_b32_e32 v106, v123
	v_mov_b32_e32 v105, v123
	v_mov_b32_e32 v104, v123
	v_mov_b32_e32 v99, v123
	v_mov_b32_e32 v98, v123
	v_mov_b32_e32 v97, v123
	v_mov_b32_e32 v96, v123
	v_mov_b32_e32 v91, v123
	v_mov_b32_e32 v90, v123
	v_mov_b32_e32 v89, v123
	v_mov_b32_e32 v88, v123
	v_mov_b32_e32 v83, v123
	v_mov_b32_e32 v82, v123
	v_mov_b32_e32 v81, v123
	v_mov_b32_e32 v80, v123
	v_mov_b32_e32 v75, v123
	v_mov_b32_e32 v74, v123
	v_mov_b32_e32 v73, v123
	v_mov_b32_e32 v72, v123
	v_mov_b32_e32 v67, v123
	v_mov_b32_e32 v66, v123
	v_mov_b32_e32 v65, v123
	v_mov_b32_e32 v64, v123
	v_mov_b32_e32 v127, v123
	v_mov_b32_e32 v126, v123
	v_mov_b32_e32 v125, v123
	v_mov_b32_e32 v124, v123
	v_mov_b32_e32 v119, v123
	v_mov_b32_e32 v118, v123
	v_mov_b32_e32 v117, v123
	v_mov_b32_e32 v116, v123
	v_mov_b32_e32 v111, v123
	v_mov_b32_e32 v110, v123
	v_mov_b32_e32 v109, v123
	v_mov_b32_e32 v108, v123
	v_mov_b32_e32 v103, v123
	v_mov_b32_e32 v102, v123
	v_mov_b32_e32 v101, v123
	v_mov_b32_e32 v100, v123
	v_mov_b32_e32 v95, v123
	v_mov_b32_e32 v94, v123
	v_mov_b32_e32 v93, v123
	v_mov_b32_e32 v92, v123
	v_mov_b32_e32 v87, v123
	v_mov_b32_e32 v86, v123
	v_mov_b32_e32 v85, v123
	v_mov_b32_e32 v84, v123
	v_mov_b32_e32 v79, v123
	v_mov_b32_e32 v78, v123
	v_mov_b32_e32 v77, v123
	v_mov_b32_e32 v76, v123
	v_mov_b32_e32 v71, v123
	v_mov_b32_e32 v70, v123
	v_mov_b32_e32 v69, v123
	v_mov_b32_e32 v68, v123
	v_mov_b32_e32 v59, v123
	v_mov_b32_e32 v58, v123
	v_mov_b32_e32 v57, v123
	v_mov_b32_e32 v56, v123
	v_mov_b32_e32 v51, v123
	v_mov_b32_e32 v50, v123
	v_mov_b32_e32 v49, v123
	v_mov_b32_e32 v48, v123
	v_mov_b32_e32 v43, v123
	v_mov_b32_e32 v42, v123
	v_mov_b32_e32 v41, v123
	v_mov_b32_e32 v40, v123
	v_mov_b32_e32 v35, v123
	v_mov_b32_e32 v34, v123
	v_mov_b32_e32 v33, v123
	v_mov_b32_e32 v32, v123
	v_mov_b32_e32 v27, v123
	v_mov_b32_e32 v26, v123
	v_mov_b32_e32 v25, v123
	v_mov_b32_e32 v24, v123
	v_mov_b32_e32 v19, v123
	v_mov_b32_e32 v18, v123
	v_mov_b32_e32 v17, v123
	v_mov_b32_e32 v16, v123
	v_mov_b32_e32 v11, v123
	v_mov_b32_e32 v10, v123
	v_mov_b32_e32 v9, v123
	v_mov_b32_e32 v8, v123
	v_mov_b32_e32 v7, v123
	v_mov_b32_e32 v6, v123
	v_mov_b32_e32 v5, v123
	v_mov_b32_e32 v4, v123
	v_mov_b32_e32 v63, v123
	v_mov_b32_e32 v62, v123
	v_mov_b32_e32 v61, v123
	v_mov_b32_e32 v60, v123
	v_mov_b32_e32 v55, v123
	v_mov_b32_e32 v54, v123
	v_mov_b32_e32 v53, v123
	v_mov_b32_e32 v52, v123
	v_mov_b32_e32 v47, v123
	v_mov_b32_e32 v46, v123
	v_mov_b32_e32 v45, v123
	v_mov_b32_e32 v44, v123
	v_mov_b32_e32 v39, v123
	v_mov_b32_e32 v38, v123
	v_mov_b32_e32 v37, v123
	v_mov_b32_e32 v36, v123
	v_mov_b32_e32 v31, v123
	v_mov_b32_e32 v30, v123
	v_mov_b32_e32 v29, v123
	v_mov_b32_e32 v28, v123
	v_mov_b32_e32 v23, v123
	v_mov_b32_e32 v22, v123
	v_mov_b32_e32 v21, v123
	v_mov_b32_e32 v20, v123
	v_mov_b32_e32 v15, v123
	v_mov_b32_e32 v14, v123
	v_mov_b32_e32 v13, v123
	v_mov_b32_e32 v12, v123
	v_mov_b32_e32 v3, v123
	v_mov_b32_e32 v2, v123
	v_mov_b32_e32 v1, v123
	v_mov_b32_e32 v0, v123
	s_branch .LBB0_1496

; #define PG8_STAGE(bufoff, gbase, voff) do { _Pragma("unroll") for (int _i = 0; _i < 2; ++_i) \
;         __builtin_amdgcn_global_load_lds((const unsigned*)((const char*)(gbase) + (voff)[_i]), (PG8_LAS unsigned*)(lds + (bufoff) + ldsw + _i * 8192), 16, 0, 0); } while (0)
; #define PG8_LDA(dst, b, h) do { _Pragma("unroll") for (int m = 0; m < 4; ++m) _Pragma("unroll") for (int k = 0; k < 2; ++k) dst[m][k] = *(const PG8_LAS bf16x8*)(lds + PG8_SA(b, h) + aoff + m * 2048 + k * 1024); } while (0)
; #define PG8_LDB(dst, b, h) do { _Pragma("unroll") for (int n = 0; n < 2; ++n) _Pragma("unroll") for (int k = 0; k < 2; ++k) dst[n][k] = *(const PG8_LAS bf16x8*)(lds + PG8_SB(b, h) + boff + n * 2048 + k * 1024); } while (0)
; #define PG8_MMA(ai, bj, At, Bt) do { __builtin_amdgcn_s_setprio(1); _Pragma("unroll") for (int m = 0; m < 4; ++m) _Pragma("unroll") for (int n = 0; n < 2; ++n) _Pragma("unroll") for (int k = 0; k < 2; ++k) \
;         acc[ai][bj][m][n] = __builtin_amdgcn_mfma_f32_16x16x32_bf16(Bt[n][k], At[m][k], acc[ai][bj][m][n], 0, 0, 0); __builtin_amdgcn_s_setprio(0); } while (0)
; template <class Epi, class Sched, bool ALIGN_EPI = false, bool SP2 = false>
; __device__ __forceinline__ void gemm_phase(PG8_LAS unsigned char* lds, const Gemm g, const Sched& S, const Epi& E, const int wid) {
;     ...
;         const bool has_next = S.next(ui + 1, nxt);
;         const char* nA = has_next ? (const char*)g.A + (size_t)nxt.pm * tstep : cA; const char* nB = has_next ? (const char*)g.Bt + (size_t)nxt.pn * tstep : cB;
;         for (int t = 0; t < nt; t += 2) {
;             const bool last = (t == nt - 2);
;             const char* a1 = cA + (size_t)(t + 1) * kstep;
;             const char* a2 = last ? nA : cA + (size_t)(t + 2) * kstep; const char* b2 = last ? nB : cB + (size_t)(t + 2) * kstep;
;             const char* a3 = a2 + kstep; const char* b3 = b2 + kstep;
;             if (last && has_next) S.a_ready(nxt);
;             if constexpr (SP2) {
;             PG8_LDB(B0, 0, 0); PG8_LDB(B1, 0, 1); PG8_SCHED; PG8_LDA(At, 0, 0); PG8_STAGE(PG8_SA(1, 1), a1 + hstep, voffA);
;             PG8_WAIT_V(8); PG8_WAIT_L(0); PG8_BAR; PG8_MMA(0, 0, At, B0); PG8_MMA(0, 1, At, B1); PG8_BAR; PG8_SCHED;
;             PG8_LDA(At, 0, 1); PG8_STAGE(PG8_SB(0, 0), b2, voffB); PG8_STAGE(PG8_SB(0, 1), b2 + hstep, voffB); PG8_STAGE(PG8_SA(0, 0), a2, voffA);
.LBB0_1572:
	s_andn2_b64 vcc, exec, s[18:19]
	s_cbranch_vccnz .Lz_FFN2
	s_add_u32 s40, s40, 0x80
	s_addc_u32 s41, s41, 0
	s_add_u32 s73, s42, 0x100
	s_addc_u32 s74, s43, 0
	s_mov_b32 s42, 0
	ds_read_b128 v[146:149], v143
	ds_read_b128 v[150:153], v143 offset:1024
	ds_read_b128 v[154:157], v143 offset:2048
	ds_read_b128 v[158:161], v143 offset:3072
	ds_read_b128 v[162:165], v144
	ds_read_b128 v[166:169], v144 offset:1024
	ds_read_b128 v[170:173], v144 offset:2048
	ds_read_b128 v[174:177], v144 offset:3072
	s_add_i32 s75, s42, 2
	s_add_u32 s33, s40, 0x80
	s_addc_u32 s43, s41, 0
	s_cmp_eq_u32 s65, s42
	s_cselect_b32 s42, s2, s33
	s_cselect_b32 s43, s3, s43
	s_cselect_b32 s77, s39, s74
	s_cselect_b32 s76, s38, s73
	v_lshl_add_u64 v[138:139], s[40:41], 0, v[132:133]
	s_add_i32 m0, s55, 0xc000
	ds_read_b128 v[178:181], v145
	ds_read_b128 v[182:185], v145 offset:1024
	ds_read_b128 v[186:189], v145 offset:2048
	ds_read_b128 v[190:193], v145 offset:3072
	ds_read_b128 v[194:197], v145 offset:4096
	ds_read_b128 v[198:201], v145 offset:5120
	ds_read_b128 v[202:205], v145 offset:6144
	ds_read_b128 v[206:209], v145 offset:7168
	global_load_lds_dwordx4 v[138:139], off
	v_lshl_add_u64 v[138:139], s[40:41], 0, v[134:135]
	s_add_i32 m0, s55, 0xe000
	s_nop 0
	global_load_lds_dwordx4 v[138:139], off
	s_waitcnt vmcnt(8)
	s_waitcnt lgkmcnt(0)
	s_barrier
	s_setprio 1
	s_waitcnt lgkmcnt(0)
	v_mfma_f32_16x16x32_bf16 v[124:127], v[146:149], v[178:181], 0
	v_mfma_f32_16x16x32_bf16 v[120:123], v[154:157], v[178:181], 0
	v_mfma_f32_16x16x32_bf16 v[108:111], v[146:149], v[186:189], 0
	v_mfma_f32_16x16x32_bf16 v[104:107], v[154:157], v[186:189], 0
	v_mfma_f32_16x16x32_bf16 v[92:95], v[146:149], v[194:197], 0
	v_mfma_f32_16x16x32_bf16 v[88:91], v[154:157], v[194:197], 0
	v_mfma_f32_16x16x32_bf16 v[76:79], v[146:149], v[202:205], 0
	v_mfma_f32_16x16x32_bf16 v[72:75], v[154:157], v[202:205], 0
	v_mfma_f32_16x16x32_bf16 v[124:127], v[150:153], v[182:185], v[124:127]
	v_mfma_f32_16x16x32_bf16 v[120:123], v[158:161], v[182:185], v[120:123]
	v_mfma_f32_16x16x32_bf16 v[108:111], v[150:153], v[190:193], v[108:111]
	v_mfma_f32_16x16x32_bf16 v[104:107], v[158:161], v[190:193], v[104:107]
	v_mfma_f32_16x16x32_bf16 v[92:95], v[150:153], v[198:201], v[92:95]
	v_mfma_f32_16x16x32_bf16 v[88:91], v[158:161], v[198:201], v[88:91]
	v_mfma_f32_16x16x32_bf16 v[76:79], v[150:153], v[206:209], v[76:79]
	v_mfma_f32_16x16x32_bf16 v[72:75], v[158:161], v[206:209], v[72:75]
	s_setprio 0
	s_setprio 1
	v_mfma_f32_16x16x32_bf16 v[116:119], v[162:165], v[178:181], 0
	v_mfma_f32_16x16x32_bf16 v[112:115], v[170:173], v[178:181], 0
	v_mfma_f32_16x16x32_bf16 v[100:103], v[162:165], v[186:189], 0
	v_mfma_f32_16x16x32_bf16 v[96:99], v[170:173], v[186:189], 0
	v_mfma_f32_16x16x32_bf16 v[84:87], v[162:165], v[194:197], 0
	v_mfma_f32_16x16x32_bf16 v[80:83], v[170:173], v[194:197], 0
	v_mfma_f32_16x16x32_bf16 v[68:71], v[162:165], v[202:205], 0
	v_mfma_f32_16x16x32_bf16 v[64:67], v[170:173], v[202:205], 0
	v_mfma_f32_16x16x32_bf16 v[116:119], v[166:169], v[182:185], v[116:119]
	v_mfma_f32_16x16x32_bf16 v[112:115], v[174:177], v[182:185], v[112:115]
	v_mfma_f32_16x16x32_bf16 v[100:103], v[166:169], v[190:193], v[100:103]
	v_mfma_f32_16x16x32_bf16 v[96:99], v[174:177], v[190:193], v[96:99]
	v_mfma_f32_16x16x32_bf16 v[84:87], v[166:169], v[198:201], v[84:87]
	v_mfma_f32_16x16x32_bf16 v[80:83], v[174:177], v[198:201], v[80:83]
	v_mfma_f32_16x16x32_bf16 v[68:71], v[166:169], v[206:209], v[68:71]
	v_mfma_f32_16x16x32_bf16 v[64:67], v[174:177], v[206:209], v[64:67]
	s_setprio 0
	s_barrier
	s_add_i32 s33, s67, s47
	v_lshl_add_u64 v[138:139], s[76:77], 0, v[130:131]
	s_mov_b32 m0, s33
	ds_read_b128 v[178:181], v145 offset:16384
	ds_read_b128 v[182:185], v145 offset:17408
	ds_read_b128 v[186:189], v145 offset:18432
	ds_read_b128 v[190:193], v145 offset:19456
	ds_read_b128 v[194:197], v145 offset:20480
	ds_read_b128 v[198:201], v145 offset:21504
	ds_read_b128 v[202:205], v145 offset:22528
	ds_read_b128 v[206:209], v145 offset:23552
	global_load_lds_dwordx4 v[138:139], off
	s_add_i32 m0, s33, 0x2000
	v_lshl_add_u64 v[210:211], s[76:77], 0, v[128:129]
	s_add_u32 s76, s76, s8
	s_addc_u32 s77, s77, s9
	s_add_i32 s33, s68, s47
	global_load_lds_dwordx4 v[210:211], off
	v_lshl_add_u64 v[212:213], s[76:77], 0, v[130:131]
	s_mov_b32 m0, s33
	v_lshl_add_u64 v[214:215], s[76:77], 0, v[128:129]
	global_load_lds_dwordx4 v[212:213], off
	s_add_i32 m0, s33, 0x2000
	v_lshl_add_u64 v[216:217], s[42:43], 0, v[130:131]
	global_load_lds_dwordx4 v[214:215], off
	s_mov_b32 m0, s55
	v_lshl_add_u64 v[218:219], s[42:43], 0, v[128:129]
	global_load_lds_dwordx4 v[216:217], off
	s_mov_b32 m0, s56
	s_nop 0
	global_load_lds_dwordx4 v[218:219], off
	s_waitcnt vmcnt(8)
	s_waitcnt lgkmcnt(0)
	s_barrier
; #define PG8_STAGE(bufoff, gbase, voff) do { _Pragma("unroll") for (int _i = 0; _i < 2; ++_i) \
;         __builtin_amdgcn_global_load_lds((const unsigned*)((const char*)(gbase) + (voff)[_i]), (PG8_LAS unsigned*)(lds + (bufoff) + ldsw + _i * 8192), 16, 0, 0); } while (0)
; #define PG8_LDA(dst, b, h) do { _Pragma("unroll") for (int m = 0; m < 4; ++m) _Pragma("unroll") for (int k = 0; k < 2; ++k) dst[m][k] = *(const PG8_LAS bf16x8*)(lds + PG8_SA(b, h) + aoff + m * 2048 + k * 1024); } while (0)
; #define PG8_LDB(dst, b, h) do { _Pragma("unroll") for (int n = 0; n < 2; ++n) _Pragma("unroll") for (int k = 0; k < 2; ++k) dst[n][k] = *(const PG8_LAS bf16x8*)(lds + PG8_SB(b, h) + boff + n * 2048 + k * 1024); } while (0)
; #define PG8_MMA(ai, bj, At, Bt) do { __builtin_amdgcn_s_setprio(1); _Pragma("unroll") for (int m = 0; m < 4; ++m) _Pragma("unroll") for (int n = 0; n < 2; ++n) _Pragma("unroll") for (int k = 0; k < 2; ++k) \
;         acc[ai][bj][m][n] = __builtin_amdgcn_mfma_f32_16x16x32_bf16(Bt[n][k], At[m][k], acc[ai][bj][m][n], 0, 0, 0); __builtin_amdgcn_s_setprio(0); } while (0)
; #define PG8_WAIT_V(n) asm volatile("s_waitcnt vmcnt(" #n ")" ::: "memory")
; #define PG8_WAIT_L(n) asm volatile("s_waitcnt lgkmcnt(" #n ")" ::: "memory")
; #define PG8_BAR __builtin_amdgcn_s_barrier()
; #define PG8_SCHED __builtin_amdgcn_sched_barrier(0)
; template <class Epi, class Sched, bool ALIGN_EPI = false, bool SP2 = false>
; __device__ __forceinline__ void gemm_phase(PG8_LAS unsigned char* lds, const Gemm g, const Sched& S, const Epi& E, const int wid) {
;     ...
;             PG8_WAIT_V(8); PG8_WAIT_L(0); PG8_BAR; PG8_MMA(0, 0, At, B0); PG8_MMA(0, 1, At, B1); PG8_BAR; PG8_SCHED;
;             PG8_LDA(At, 0, 1); PG8_STAGE(PG8_SB(0, 0), b2, voffB); PG8_STAGE(PG8_SB(0, 1), b2 + hstep, voffB); PG8_STAGE(PG8_SA(0, 0), a2, voffA);
;             PG8_WAIT_V(8); PG8_WAIT_L(0); PG8_BAR; PG8_MMA(1, 0, At, B0); PG8_MMA(1, 1, At, B1); PG8_BAR; PG8_SCHED;
;             PG8_LDB(B0, 1, 0); PG8_LDB(B1, 1, 1); PG8_SCHED; PG8_LDA(At, 1, 0); PG8_STAGE(PG8_SA(0, 1), a2 + hstep, voffA);
;             PG8_WAIT_V(8); PG8_WAIT_L(0); PG8_BAR; PG8_MMA(0, 0, At, B0); PG8_MMA(0, 1, At, B1); PG8_BAR; PG8_SCHED;
	s_setprio 1
	s_waitcnt lgkmcnt(0)
	v_mfma_f32_16x16x32_bf16 v[60:63], v[146:149], v[178:181], 0
	v_mfma_f32_16x16x32_bf16 v[56:59], v[154:157], v[178:181], 0
	v_mfma_f32_16x16x32_bf16 v[44:47], v[146:149], v[186:189], 0
	v_mfma_f32_16x16x32_bf16 v[40:43], v[154:157], v[186:189], 0
	v_mfma_f32_16x16x32_bf16 v[28:31], v[146:149], v[194:197], 0
	v_mfma_f32_16x16x32_bf16 v[24:27], v[154:157], v[194:197], 0
	v_mfma_f32_16x16x32_bf16 v[12:15], v[146:149], v[202:205], 0
	v_mfma_f32_16x16x32_bf16 v[8:11], v[154:157], v[202:205], 0
	v_mfma_f32_16x16x32_bf16 v[60:63], v[150:153], v[182:185], v[60:63]
	v_mfma_f32_16x16x32_bf16 v[56:59], v[158:161], v[182:185], v[56:59]
	v_mfma_f32_16x16x32_bf16 v[44:47], v[150:153], v[190:193], v[44:47]
	v_mfma_f32_16x16x32_bf16 v[40:43], v[158:161], v[190:193], v[40:43]
	v_mfma_f32_16x16x32_bf16 v[28:31], v[150:153], v[198:201], v[28:31]
	v_mfma_f32_16x16x32_bf16 v[24:27], v[158:161], v[198:201], v[24:27]
	v_mfma_f32_16x16x32_bf16 v[12:15], v[150:153], v[206:209], v[12:15]
	v_mfma_f32_16x16x32_bf16 v[8:11], v[158:161], v[206:209], v[8:11]
	s_setprio 0
	s_setprio 1
	v_mfma_f32_16x16x32_bf16 v[52:55], v[162:165], v[178:181], 0
	v_mfma_f32_16x16x32_bf16 v[48:51], v[170:173], v[178:181], 0
	v_mfma_f32_16x16x32_bf16 v[36:39], v[162:165], v[186:189], 0
	v_mfma_f32_16x16x32_bf16 v[32:35], v[170:173], v[186:189], 0
	v_mfma_f32_16x16x32_bf16 v[20:23], v[162:165], v[194:197], 0
	v_mfma_f32_16x16x32_bf16 v[16:19], v[170:173], v[194:197], 0
	v_mfma_f32_16x16x32_bf16 v[4:7], v[162:165], v[202:205], 0
	v_mfma_f32_16x16x32_bf16 v[0:3], v[170:173], v[202:205], 0
	v_mfma_f32_16x16x32_bf16 v[52:55], v[166:169], v[182:185], v[52:55]
	v_mfma_f32_16x16x32_bf16 v[48:51], v[174:177], v[182:185], v[48:51]
	v_mfma_f32_16x16x32_bf16 v[36:39], v[166:169], v[190:193], v[36:39]
	v_mfma_f32_16x16x32_bf16 v[32:35], v[174:177], v[190:193], v[32:35]
	v_mfma_f32_16x16x32_bf16 v[20:23], v[166:169], v[198:201], v[20:23]
	v_mfma_f32_16x16x32_bf16 v[16:19], v[174:177], v[198:201], v[16:19]
	v_mfma_f32_16x16x32_bf16 v[4:7], v[166:169], v[206:209], v[4:7]
	v_mfma_f32_16x16x32_bf16 v[0:3], v[174:177], v[206:209], v[0:3]
	s_setprio 0
	s_barrier
	s_add_i32 s33, 0, 0x18000
	s_add_i32 s76, 0, 0x1c000
	v_add_u32_e32 v158, s33, v142
	v_add_u32_e32 v174, s76, v142
	ds_read_b128 v[146:149], v158
	ds_read_b128 v[150:153], v158 offset:1024
	ds_read_b128 v[154:157], v158 offset:2048
	ds_read_b128 v[158:161], v158 offset:3072
	ds_read_b128 v[162:165], v174
	ds_read_b128 v[166:169], v174 offset:1024
	ds_read_b128 v[170:173], v174 offset:2048
	ds_read_b128 v[174:177], v174 offset:3072
	s_add_u32 s42, s42, s8
	s_addc_u32 s43, s43, s9
	s_mov_b32 m0, s57
	v_lshl_add_u64 v[220:221], s[42:43], 0, v[130:131]
	ds_read_b128 v[178:181], v145 offset:32768
	ds_read_b128 v[182:185], v145 offset:33792
	ds_read_b128 v[186:189], v145 offset:34816
	ds_read_b128 v[190:193], v145 offset:35840
	ds_read_b128 v[194:197], v145 offset:36864
	ds_read_b128 v[198:201], v145 offset:37888
	ds_read_b128 v[202:205], v145 offset:38912
	ds_read_b128 v[206:209], v145 offset:39936
	global_load_lds_dwordx4 v[220:221], off
	v_lshl_add_u64 v[220:221], s[42:43], 0, v[128:129]
	s_mov_b32 m0, s58
	s_nop 0
	global_load_lds_dwordx4 v[220:221], off
	s_waitcnt vmcnt(8)
	s_waitcnt lgkmcnt(0)
	s_barrier
	s_setprio 1
	s_waitcnt lgkmcnt(0)
	v_mfma_f32_16x16x32_bf16 v[124:127], v[146:149], v[178:181], v[124:127]
	v_mfma_f32_16x16x32_bf16 v[120:123], v[154:157], v[178:181], v[120:123]
	v_mfma_f32_16x16x32_bf16 v[108:111], v[146:149], v[186:189], v[108:111]
	v_mfma_f32_16x16x32_bf16 v[104:107], v[154:157], v[186:189], v[104:107]
	v_mfma_f32_16x16x32_bf16 v[92:95], v[146:149], v[194:197], v[92:95]
	v_mfma_f32_16x16x32_bf16 v[88:91], v[154:157], v[194:197], v[88:91]
	v_mfma_f32_16x16x32_bf16 v[76:79], v[146:149], v[202:205], v[76:79]
	v_mfma_f32_16x16x32_bf16 v[72:75], v[154:157], v[202:205], v[72:75]
	v_mfma_f32_16x16x32_bf16 v[124:127], v[150:153], v[182:185], v[124:127]
	v_mfma_f32_16x16x32_bf16 v[120:123], v[158:161], v[182:185], v[120:123]
	v_mfma_f32_16x16x32_bf16 v[108:111], v[150:153], v[190:193], v[108:111]
	v_mfma_f32_16x16x32_bf16 v[104:107], v[158:161], v[190:193], v[104:107]
	v_mfma_f32_16x16x32_bf16 v[92:95], v[150:153], v[198:201], v[92:95]
	v_mfma_f32_16x16x32_bf16 v[88:91], v[158:161], v[198:201], v[88:91]
	v_mfma_f32_16x16x32_bf16 v[76:79], v[150:153], v[206:209], v[76:79]
	v_mfma_f32_16x16x32_bf16 v[72:75], v[158:161], v[206:209], v[72:75]
	s_setprio 0
	s_setprio 1
	v_mfma_f32_16x16x32_bf16 v[116:119], v[162:165], v[178:181], v[116:119]
	v_mfma_f32_16x16x32_bf16 v[112:115], v[170:173], v[178:181], v[112:115]
	v_mfma_f32_16x16x32_bf16 v[100:103], v[162:165], v[186:189], v[100:103]
	v_mfma_f32_16x16x32_bf16 v[96:99], v[170:173], v[186:189], v[96:99]
	v_mfma_f32_16x16x32_bf16 v[84:87], v[162:165], v[194:197], v[84:87]
	v_mfma_f32_16x16x32_bf16 v[80:83], v[170:173], v[194:197], v[80:83]
	v_mfma_f32_16x16x32_bf16 v[68:71], v[162:165], v[202:205], v[68:71]
	v_mfma_f32_16x16x32_bf16 v[64:67], v[170:173], v[202:205], v[64:67]
	v_mfma_f32_16x16x32_bf16 v[116:119], v[166:169], v[182:185], v[116:119]
	v_mfma_f32_16x16x32_bf16 v[112:115], v[174:177], v[182:185], v[112:115]
	v_mfma_f32_16x16x32_bf16 v[100:103], v[166:169], v[190:193], v[100:103]
	v_mfma_f32_16x16x32_bf16 v[96:99], v[174:177], v[190:193], v[96:99]
	v_mfma_f32_16x16x32_bf16 v[84:87], v[166:169], v[198:201], v[84:87]
	v_mfma_f32_16x16x32_bf16 v[80:83], v[174:177], v[198:201], v[80:83]
	v_mfma_f32_16x16x32_bf16 v[68:71], v[166:169], v[206:209], v[68:71]
	v_mfma_f32_16x16x32_bf16 v[64:67], v[174:177], v[206:209], v[64:67]
	s_setprio 0
	s_barrier
; #define PG8_STAGE(bufoff, gbase, voff) do { _Pragma("unroll") for (int _i = 0; _i < 2; ++_i) \
;         __builtin_amdgcn_global_load_lds((const unsigned*)((const char*)(gbase) + (voff)[_i]), (PG8_LAS unsigned*)(lds + (bufoff) + ldsw + _i * 8192), 16, 0, 0); } while (0)
; #define PG8_LDA(dst, b, h) do { _Pragma("unroll") for (int m = 0; m < 4; ++m) _Pragma("unroll") for (int k = 0; k < 2; ++k) dst[m][k] = *(const PG8_LAS bf16x8*)(lds + PG8_SA(b, h) + aoff + m * 2048 + k * 1024); } while (0)
; #define PG8_MMA(ai, bj, At, Bt) do { __builtin_amdgcn_s_setprio(1); _Pragma("unroll") for (int m = 0; m < 4; ++m) _Pragma("unroll") for (int n = 0; n < 2; ++n) _Pragma("unroll") for (int k = 0; k < 2; ++k) \
;         acc[ai][bj][m][n] = __builtin_amdgcn_mfma_f32_16x16x32_bf16(Bt[n][k], At[m][k], acc[ai][bj][m][n], 0, 0, 0); __builtin_amdgcn_s_setprio(0); } while (0)
; #define PG8_WAIT_V(n) asm volatile("s_waitcnt vmcnt(" #n ")" ::: "memory")
; #define PG8_WAIT_L(n) asm volatile("s_waitcnt lgkmcnt(" #n ")" ::: "memory")
; #define PG8_BAR __builtin_amdgcn_s_barrier()
; #define PG8_SCHED __builtin_amdgcn_sched_barrier(0)
; template <class Epi, class Sched, bool ALIGN_EPI = false, bool SP2 = false>
; __device__ __forceinline__ void gemm_phase(PG8_LAS unsigned char* lds, const Gemm g, const Sched& S, const Epi& E, const int wid) {
;     ...
;         for (int t = 0; t < nt; t += 2) {
;             const bool last = (t == nt - 2);
;             const char* a1 = cA + (size_t)(t + 1) * kstep;
;             const char* a2 = last ? nA : cA + (size_t)(t + 2) * kstep; const char* b2 = last ? nB : cB + (size_t)(t + 2) * kstep;
;     ...
;             PG8_LDA(At, 1, 1); PG8_STAGE(PG8_SB(1, 0), b3, voffB); PG8_STAGE(PG8_SB(1, 1), b3 + hstep, voffB); PG8_STAGE(PG8_SA(1, 0), a3, voffA);
;             PG8_WAIT_V(8); PG8_WAIT_L(0); PG8_BAR; PG8_MMA(1, 0, At, B0); PG8_MMA(1, 1, At, B1); PG8_BAR; PG8_SCHED;
	s_add_i32 s33, s33, s47
	v_lshl_add_u64 v[138:139], v[138:139], 0, s[16:17]
	s_mov_b32 m0, s33
	ds_read_b128 v[178:181], v145 offset:49152
	ds_read_b128 v[182:185], v145 offset:50176
	ds_read_b128 v[186:189], v145 offset:51200
	ds_read_b128 v[190:193], v145 offset:52224
	ds_read_b128 v[194:197], v145 offset:53248
	ds_read_b128 v[198:201], v145 offset:54272
	ds_read_b128 v[202:205], v145 offset:55296
	ds_read_b128 v[206:209], v145 offset:56320
	global_load_lds_dwordx4 v[138:139], off
	v_lshl_add_u64 v[138:139], v[210:211], 0, s[16:17]
	s_add_i32 m0, s33, 0x2000
	s_add_i32 s33, s76, s47
	global_load_lds_dwordx4 v[138:139], off
	v_lshl_add_u64 v[138:139], v[212:213], 0, s[16:17]
	s_mov_b32 m0, s33
	s_nop 0
	global_load_lds_dwordx4 v[138:139], off
	v_lshl_add_u64 v[138:139], v[214:215], 0, s[16:17]
	s_add_i32 m0, s33, 0x2000
	s_nop 0
	global_load_lds_dwordx4 v[138:139], off
	v_lshl_add_u64 v[138:139], v[216:217], 0, s[16:17]
	s_mov_b32 m0, s60
	s_nop 0
	global_load_lds_dwordx4 v[138:139], off
	v_lshl_add_u64 v[138:139], v[218:219], 0, s[16:17]
	s_mov_b32 m0, s61
	s_nop 0
	global_load_lds_dwordx4 v[138:139], off
	s_waitcnt vmcnt(8)
	s_waitcnt lgkmcnt(0)
	s_barrier
	s_setprio 1
	s_waitcnt lgkmcnt(0)
	v_mfma_f32_16x16x32_bf16 v[60:63], v[146:149], v[178:181], v[60:63]
	v_mfma_f32_16x16x32_bf16 v[56:59], v[154:157], v[178:181], v[56:59]
	v_mfma_f32_16x16x32_bf16 v[44:47], v[146:149], v[186:189], v[44:47]
	v_mfma_f32_16x16x32_bf16 v[40:43], v[154:157], v[186:189], v[40:43]
	v_mfma_f32_16x16x32_bf16 v[28:31], v[146:149], v[194:197], v[28:31]
	v_mfma_f32_16x16x32_bf16 v[24:27], v[154:157], v[194:197], v[24:27]
	v_mfma_f32_16x16x32_bf16 v[12:15], v[146:149], v[202:205], v[12:15]
	v_mfma_f32_16x16x32_bf16 v[8:11], v[154:157], v[202:205], v[8:11]
	v_mfma_f32_16x16x32_bf16 v[60:63], v[150:153], v[182:185], v[60:63]
	v_mfma_f32_16x16x32_bf16 v[56:59], v[158:161], v[182:185], v[56:59]
	v_mfma_f32_16x16x32_bf16 v[44:47], v[150:153], v[190:193], v[44:47]
	v_mfma_f32_16x16x32_bf16 v[40:43], v[158:161], v[190:193], v[40:43]
	v_mfma_f32_16x16x32_bf16 v[28:31], v[150:153], v[198:201], v[28:31]
	v_mfma_f32_16x16x32_bf16 v[24:27], v[158:161], v[198:201], v[24:27]
	v_mfma_f32_16x16x32_bf16 v[12:15], v[150:153], v[206:209], v[12:15]
	v_mfma_f32_16x16x32_bf16 v[8:11], v[158:161], v[206:209], v[8:11]
	s_setprio 0
	s_setprio 1
	v_mfma_f32_16x16x32_bf16 v[52:55], v[162:165], v[178:181], v[52:55]
	v_mfma_f32_16x16x32_bf16 v[48:51], v[170:173], v[178:181], v[48:51]
	v_mfma_f32_16x16x32_bf16 v[36:39], v[162:165], v[186:189], v[36:39]
	v_mfma_f32_16x16x32_bf16 v[32:35], v[170:173], v[186:189], v[32:35]
	v_mfma_f32_16x16x32_bf16 v[20:23], v[162:165], v[194:197], v[20:23]
	v_mfma_f32_16x16x32_bf16 v[16:19], v[170:173], v[194:197], v[16:19]
	v_mfma_f32_16x16x32_bf16 v[4:7], v[162:165], v[202:205], v[4:7]
	v_mfma_f32_16x16x32_bf16 v[0:3], v[170:173], v[202:205], v[0:3]
	v_mfma_f32_16x16x32_bf16 v[52:55], v[166:169], v[182:185], v[52:55]
	v_mfma_f32_16x16x32_bf16 v[48:51], v[174:177], v[182:185], v[48:51]
	v_mfma_f32_16x16x32_bf16 v[36:39], v[166:169], v[190:193], v[36:39]
	v_mfma_f32_16x16x32_bf16 v[32:35], v[174:177], v[190:193], v[32:35]
	v_mfma_f32_16x16x32_bf16 v[20:23], v[166:169], v[198:201], v[20:23]
	v_mfma_f32_16x16x32_bf16 v[16:19], v[174:177], v[198:201], v[16:19]
	v_mfma_f32_16x16x32_bf16 v[4:7], v[166:169], v[206:209], v[4:7]
	v_mfma_f32_16x16x32_bf16 v[0:3], v[174:177], v[206:209], v[0:3]
	s_setprio 0
	s_barrier
	s_add_u32 s40, s40, 0x100
	s_addc_u32 s41, s41, 0
	s_add_u32 s73, s73, 0x100
	s_addc_u32 s74, s74, 0
	s_cmp_ge_i32 s75, s62
	s_mov_b32 s42, s75
	s_cbranch_scc1 .LBB0_1575
